# all six GEMM K-loops moved to LDS-DMA staging (global_load_lds, source-swizzled, no ds_write or prefetch VGPRs) + peer_v/u-pass instruction trims
# speedup vs baseline: 1.0336x; 1.0314x over previous
; __device__ __forceinline__ int otid() { int t = threadIdx.x; asm volatile("" : "+v"(t)); return t; }
; template <int MI, bool SWAP, bool F8 = false>
; __device__ __forceinline__ void gemm_core(const bf16_t* __restrict__ A, int lda, const bf16_t* __restrict__ B, int ldb,
;                                           int K, char* smem, f32x4 (&acc)[MI][4]) {
;   const int tid = otid(), lane = tid & 63, w = tid >> 6, wm = w >> 1, wn = w & 1;
;   const int lr = tid >> 3, lc = tid & 7;
;   const int li = lane & 15, g = lane >> 4;
;   u32x4 ra[MI], rb[4];
;   const bf16_t* ap = A + (size_t)lr * lda + lc * 8;
;   const bf16_t* bp = B + (size_t)lr * ldb + lc * 8;
; #pragma unroll
;   for (int i = 0; i < MI; ++i)
; #pragma unroll
;     for (int j = 0; j < 4; ++j) acc[i][j] = (f32x4){0.f, 0.f, 0.f, 0.f};
;   const int nk = K >> 6;
; #pragma unroll
;   for (int i = 0; i < MI; ++i) ra[i] = *(const u32x4*)(ap + (size_t)(32 * i) * lda);
; #pragma unroll
;   for (int i = 0; i < 4; ++i) rb[i] = *(const u32x4*)(bp + (size_t)(32 * i) * ldb);
;   const int woff = lr * 128 + ((lc ^ (lr & 7)) << 4);
;   const int xrow = (wm * 16 * MI + li) * 128;
;   const int wrow = 32768 + (wn * 32 + li) * 128;
; __global__ void __launch_bounds__(256, 2) fwd_kernel(P p) {
;     ...
;       for (int it = blockIdx.x; it < 64 * 24; it += G) {
;         const int tm = (it & 7) * 8 + (it >> 3) / 24, tn = (it >> 3) % 24;
;         gemm_tile_bf16<8>(XN + (size_t)tm * 256 * 1024, 1024,
;                        (const bf16_t*)(ws + OFF_WOIN) + ((size_t)li2 * 3072 + tn * 128) * 1024, 1024, 1024,
;                        PR + (size_t)tm * 256 * 3072 + tn * 128, 3072, smem);
.LBB0_116:
	s_lshr_b32 s18, s6, 1
	s_lshr_b64 s[0:1], s[6:7], 1
	s_mov_b64 s[14:15], 0
	s_add_u32 s12, s68, s14
	s_addc_u32 s13, s69, s15
	s_add_u32 s16, s12, 0x13a84000
	s_addc_u32 s17, s13, 0
	v_writelane_b32 v255, s6, 60
	s_bitcmp1_b32 s6, 0
	v_mov_b32_e32 v248, v208
	v_writelane_b32 v255, s7, 61
	s_cselect_b64 s[6:7], -1, 0
	s_and_b64 vcc, exec, s[6:7]
	s_mov_b64 s[6:7], -1
	s_cbranch_vccz .LBB0_291
	v_readlane_b32 s6, v255, 16
	s_add_u32 s8, s12, 0x19a84000
	v_readlane_b32 s7, v255, 17
	s_addc_u32 s9, s13, 0
	s_andn2_b64 vcc, exec, s[6:7]
	s_cbranch_vccnz .LBB0_122
	s_mul_i32 s6, s1, 0x600000
	s_mul_hi_u32 s7, s0, 0x600000
	s_add_i32 s7, s7, s6
	s_add_u32 s19, s12, 0x17a84000
	s_addc_u32 s24, s13, 0
	s_add_u32 s25, s12, 0x1884000
	s_mul_i32 s6, s0, 0x600000
	s_addc_u32 s26, s13, 0
	s_add_u32 s6, s14, s6
	s_addc_u32 s7, s15, s7
	s_add_u32 s6, s68, s6
	v_readlane_b32 s10, v255, 53
	s_addc_u32 s7, s69, s7
	v_readlane_b32 s27, v255, 48
	s_mov_b32 s28, s10
	v_readlane_b32 s11, v255, 54
.LBB0_119:
	s_ashr_i32 s11, s28, 3
	s_mul_hi_i32 s20, s11, 0x2aaaaaab
	s_lshl_b32 s10, s28, 3
	s_lshr_b32 s21, s20, 31
	s_ashr_i32 s20, s20, 2
	s_and_b32 s10, s10, 56
	s_add_i32 s34, s20, s21
	s_add_i32 s10, s10, s34
	s_mul_i32 s20, s34, 24
	s_sub_i32 s30, s11, s20
	s_ashr_i32 s11, s10, 31
	s_waitcnt vmcnt(17)
	v_mov_b32_e32 v30, v208
	s_and_b32 s29, s27, 56
	s_lshl_b64 s[20:21], s[10:11], 19
	s_add_u32 s22, s19, s20
	v_ashrrev_i32_e32 v2, 3, v30
	v_ashrrev_i32_e32 v3, 31, v2
	s_addc_u32 s23, s24, s21
	v_lshlrev_b64 v[20:21], 11, v[2:3]
	v_lshlrev_b32_e32 v0, 4, v30
	v_lshl_add_u64 v[24:25], s[22:23], 0, v[20:21]
	v_and_b32_e32 v0, 0x70, v0
	v_lshl_add_u64 v[24:25], v[24:25], 0, v[0:1]
	v_add_co_u32_e32 v26, vcc, s93, v24
	s_lshl_b32 s20, s30, 7
	s_nop 0
	v_addc_co_u32_e32 v27, vcc, 0, v25, vcc
	v_lshrrev_b32_e32 v254, 3, v208
	v_and_b32_e32 v254, 7, v254
	v_xor_b32_e32 v252, v254, v208
	v_and_b32_e32 v252, 7, v252
	v_lshlrev_b32_e32 v252, 4, v252
	v_lshl_or_b32 v252, v254, 11, v252
	v_add_u32_e32 v253, 0x10000, v252
	v_lshrrev_b32_e32 v254, 6, v208
	s_nop 0
	v_readfirstlane_b32 s62, v254
	s_lshl_b32 s62, s62, 10
	v_readfirstlane_b32 s56, v24
	v_readfirstlane_b32 s57, v25
	v_add_co_u32_e32 v26, vcc, s46, v24
	s_ashr_i32 s21, s20, 31
	s_nop 0
	v_addc_co_u32_e32 v27, vcc, 0, v25, vcc
	v_add_co_u32_e32 v28, vcc, s47, v24
	s_mul_i32 s11, s18, 0xc00
	s_nop 0
	v_addc_co_u32_e32 v29, vcc, 0, v25, vcc
	v_add_co_u32_e32 v26, vcc, s50, v24
	s_add_u32 s30, s20, s11
	s_nop 0
	v_addc_co_u32_e32 v27, vcc, 0, v25, vcc
	s_addc_u32 s31, s21, 0
	v_add_co_u32_e32 v28, vcc, s51, v24
	s_lshl_b64 s[30:31], s[30:31], 11
	s_nop 0
	v_addc_co_u32_e32 v29, vcc, 0, v25, vcc
	s_mov_b32 s11, 0x60000
	s_add_u32 s30, s25, s30
	v_add_co_u32_e32 v26, vcc, s11, v24
	s_addc_u32 s31, s26, s31
	s_nop 0
	v_addc_co_u32_e32 v27, vcc, 0, v25, vcc
	s_mov_b32 s11, 0x70000
	v_lshl_add_u64 v[22:23], s[30:31], 0, v[20:21]
	v_add_co_u32_e32 v24, vcc, s11, v24
	v_lshl_add_u64 v[22:23], v[22:23], 0, v[0:1]
	s_nop 0
	v_addc_co_u32_e32 v25, vcc, 0, v25, vcc
	v_add_co_u32_e32 v24, vcc, s93, v22
	v_and_b32_e32 v3, 15, v30
	s_nop 0
	v_addc_co_u32_e32 v25, vcc, 0, v23, vcc
	s_nop 0
	v_readfirstlane_b32 s58, v22
	v_readfirstlane_b32 s59, v23
	v_add_co_u32_e32 v24, vcc, s46, v22
	s_add_i32 s22, s34, s29
	s_nop 0
	v_addc_co_u32_e32 v25, vcc, 0, v23, vcc
	v_add_co_u32_e32 v22, vcc, s47, v22
	v_lshrrev_b32_e32 v31, 4, v30
	s_nop 0
	v_addc_co_u32_e32 v23, vcc, 0, v23, vcc
	v_lshlrev_b32_e32 v22, 7, v2
	v_xor_b32_e32 v2, v2, v30
	v_lshlrev_b32_e32 v2, 4, v2
	v_and_or_b32 v207, v2, s33, v22
	v_lshlrev_b32_e32 v2, 7, v30
	v_and_b32_e32 v22, 0xffffc780, v2
	v_lshrrev_b32_e32 v2, 1, v30
	v_and_or_b32 v2, v2, 32, v3
	v_and_b32_e32 v24, 7, v30
	s_ashr_i32 s23, s22, 31
	v_lshlrev_b32_e32 v23, 7, v2
	v_bitop3_b32 v2, v31, v24, 3 bitop3:0x6c
	s_lshl_b64 s[22:23], s[22:23], 19
	v_bfe_u32 v0, v30, 4, 2
	v_lshlrev_b32_e32 v25, 4, v2
	v_lshl_add_u64 v[2:3], s[22:23], 0, v[20:21]
	s_lshl_b64 s[22:23], s[20:21], 11
	v_bitop3_b32 v0, v0, v24, 4 bitop3:0x36
	v_lshlrev_b32_e32 v24, 4, v24
	v_lshl_add_u64 v[20:21], v[20:21], 0, s[22:23]
	v_lshlrev_b32_e32 v0, 4, v0
	v_or_b32_e32 v2, v2, v24
	v_or_b32_e32 v20, v20, v24
	v_mov_b32_e32 v144, 0
	v_lshl_add_u64 v[2:3], s[12:13], 0, v[2:3]
	v_lshl_add_u64 v[204:205], s[6:7], 0, v[20:21]
	s_mov_b64 s[22:23], 0
	v_add_u32_e32 v215, v23, v25
	v_add_u32_e32 v213, v22, v25
	v_add_u32_e32 v206, v23, v0
	v_add_u32_e32 v0, v22, v0
	v_mov_b32_e32 v145, v144
	v_mov_b32_e32 v146, v144
	v_mov_b32_e32 v147, v144
	s_waitcnt vmcnt(26)
	v_mov_b32_e32 v92, v144
	v_mov_b32_e32 v93, v144
	v_mov_b32_e32 v94, v144
	v_mov_b32_e32 v95, v144
	s_waitcnt vmcnt(25)
	v_mov_b32_e32 v96, v144
	v_mov_b32_e32 v97, v144
	v_mov_b32_e32 v98, v144
	v_mov_b32_e32 v99, v144
	s_waitcnt vmcnt(24)
	v_mov_b32_e32 v100, v144
	v_mov_b32_e32 v101, v144
	v_mov_b32_e32 v102, v144
	v_mov_b32_e32 v103, v144
	v_mov_b32_e32 v108, v144
	v_mov_b32_e32 v109, v144
	v_mov_b32_e32 v110, v144
	v_mov_b32_e32 v111, v144
	v_mov_b32_e32 v112, v144
	v_mov_b32_e32 v113, v144
	v_mov_b32_e32 v114, v144
	v_mov_b32_e32 v115, v144
	s_waitcnt vmcnt(23)
; template <int MI, bool SWAP, bool F8 = false>
; __device__ __forceinline__ void gemm_core(const bf16_t* __restrict__ A, int lda, const bf16_t* __restrict__ B, int ldb,
;                                           int K, char* smem, f32x4 (&acc)[MI][4]) {
;     ...
;   for (int kt = 0; kt < nk; ++kt) {
;     __syncthreads();
; #pragma unroll
;     for (int i = 0; i < MI; ++i) *(u32x4*)(smem + woff + i * 4096) = ra[i];
; #pragma unroll
;     for (int i = 0; i < 4; ++i) *(u32x4*)(smem + 32768 + woff + i * 4096) = rb[i];
;     __syncthreads();
;     if (kt + 1 < nk) {
; #pragma unroll
;       for (int i = 0; i < MI; ++i) ra[i] = *(const u32x4*)(ap + (size_t)(32 * i) * lda + (kt + 1) * 64);
; #pragma unroll
;       for (int i = 0; i < 4; ++i) rb[i] = *(const u32x4*)(bp + (size_t)(32 * i) * ldb + (kt + 1) * 64);
;     }
;     if (F8) {
;       const int c0 = (g ^ (li & 7)) << 4, c1 = ((4 + g) ^ (li & 7)) << 4;
;       i32x8 wf8[4];
; #pragma unroll
;       for (int j = 0; j < 4; ++j) {
;         const char* rp = smem + wrow + ((j & 1) * 16 + (j >> 1) * 64) * 128;
;         const u32x4 lo = *(const u32x4*)(rp + c0), hi = *(const u32x4*)(rp + c1);
;         wf8[j] = (i32x8){(int)lo.x, (int)lo.y, (int)lo.z, (int)lo.w, (int)hi.x, (int)hi.y, (int)hi.z, (int)hi.w};
;       }
; #pragma unroll
;       for (int i = 0; i < MI; ++i) {
;         const char* rp = smem + xrow + i * 2048;
;         const u32x4 lo = *(const u32x4*)(rp + c0), hi = *(const u32x4*)(rp + c1);
;         const i32x8 xf8 = {(int)lo.x, (int)lo.y, (int)lo.z, (int)lo.w, (int)hi.x, (int)hi.y, (int)hi.z, (int)hi.w};
; #pragma unroll
;         for (int j = 0; j < 4; ++j)
;           acc[i][j] = __builtin_amdgcn_mfma_scale_f32_16x16x128_f8f6f4(wf8[j], xf8, acc[i][j], 0, 0, 0, 0x77777777, 0, 0x7f7f7f7f);
;       }
;     } else {
; #pragma unroll
;     for (int kk = 0; kk < 2; ++kk) {
;       const int ch = ((kk * 4 + g) ^ (li & 7)) << 4;
;       bf16x8 xf[MI], wf[4];
; #pragma unroll
;       for (int j = 0; j < 4; ++j) wf[j] = *(const bf16x8*)(smem + wrow + ((j & 1) * 16 + (j >> 1) * 64) * 128 + ch);
; #pragma unroll
;       for (int i = 0; i < MI; ++i) xf[i] = *(const bf16x8*)(smem + xrow + i * 2048 + ch);
; #pragma unroll
;       for (int i = 0; i < MI; ++i)
; #pragma unroll
;         for (int j = 0; j < 4; ++j) {
	v_mov_b32_e32 v56, v144
	v_mov_b32_e32 v57, v144
	v_mov_b32_e32 v58, v144
	v_mov_b32_e32 v59, v144
	v_mov_b32_e32 v48, v144
	v_mov_b32_e32 v49, v144
	v_mov_b32_e32 v50, v144
	v_mov_b32_e32 v51, v144
	v_mov_b32_e32 v52, v144
	v_mov_b32_e32 v53, v144
	v_mov_b32_e32 v54, v144
	v_mov_b32_e32 v55, v144
	v_mov_b32_e32 v20, v144
	v_mov_b32_e32 v21, v144
	v_mov_b32_e32 v22, v144
	v_mov_b32_e32 v23, v144
	v_mov_b32_e32 v24, v144
	v_mov_b32_e32 v25, v144
	v_mov_b32_e32 v26, v144
	v_mov_b32_e32 v27, v144
	v_mov_b32_e32 v28, v144
	v_mov_b32_e32 v29, v144
	v_mov_b32_e32 v30, v144
	v_mov_b32_e32 v31, v144
	v_mov_b32_e32 v32, v144
	v_mov_b32_e32 v33, v144
	v_mov_b32_e32 v34, v144
	v_mov_b32_e32 v35, v144
	v_mov_b32_e32 v36, v144
	v_mov_b32_e32 v37, v144
	v_mov_b32_e32 v38, v144
	v_mov_b32_e32 v39, v144
	v_mov_b32_e32 v40, v144
	v_mov_b32_e32 v41, v144
	v_mov_b32_e32 v42, v144
	v_mov_b32_e32 v43, v144
	v_mov_b32_e32 v44, v144
	v_mov_b32_e32 v45, v144
	v_mov_b32_e32 v46, v144
	v_mov_b32_e32 v47, v144
	v_mov_b32_e32 v60, v144
	v_mov_b32_e32 v61, v144
	v_mov_b32_e32 v62, v144
	v_mov_b32_e32 v63, v144
	s_waitcnt vmcnt(22)
	v_mov_b32_e32 v64, v144
	v_mov_b32_e32 v65, v144
	v_mov_b32_e32 v66, v144
	v_mov_b32_e32 v67, v144
	v_mov_b32_e32 v68, v144
	v_mov_b32_e32 v69, v144
	v_mov_b32_e32 v70, v144
	v_mov_b32_e32 v71, v144
	v_mov_b32_e32 v72, v144
	v_mov_b32_e32 v73, v144
	v_mov_b32_e32 v74, v144
	v_mov_b32_e32 v75, v144
	v_mov_b32_e32 v76, v144
	v_mov_b32_e32 v77, v144
	v_mov_b32_e32 v78, v144
	v_mov_b32_e32 v79, v144
	v_mov_b32_e32 v80, v144
	v_mov_b32_e32 v81, v144
	v_mov_b32_e32 v82, v144
	v_mov_b32_e32 v83, v144
	s_waitcnt vmcnt(21)
	v_mov_b32_e32 v84, v144
	v_mov_b32_e32 v85, v144
	v_mov_b32_e32 v86, v144
	v_mov_b32_e32 v87, v144
	s_waitcnt vmcnt(20)
	v_mov_b32_e32 v88, v144
	v_mov_b32_e32 v89, v144
	v_mov_b32_e32 v90, v144
	v_mov_b32_e32 v91, v144
	v_mov_b32_e32 v104, v144
	v_mov_b32_e32 v105, v144
	v_mov_b32_e32 v106, v144
	v_mov_b32_e32 v107, v144
	v_mov_b32_e32 v116, v144
	v_mov_b32_e32 v117, v144
	v_mov_b32_e32 v118, v144
	v_mov_b32_e32 v119, v144
	v_mov_b32_e32 v120, v144
	v_mov_b32_e32 v121, v144
	v_mov_b32_e32 v122, v144
	v_mov_b32_e32 v123, v144
	v_mov_b32_e32 v124, v144
	v_mov_b32_e32 v125, v144
	v_mov_b32_e32 v126, v144
	v_mov_b32_e32 v127, v144
	v_mov_b32_e32 v128, v144
	v_mov_b32_e32 v129, v144
	v_mov_b32_e32 v130, v144
	v_mov_b32_e32 v131, v144
	v_mov_b32_e32 v132, v144
	v_mov_b32_e32 v133, v144
	v_mov_b32_e32 v134, v144
	v_mov_b32_e32 v135, v144
	v_mov_b32_e32 v136, v144
	v_mov_b32_e32 v137, v144
	v_mov_b32_e32 v138, v144
	v_mov_b32_e32 v139, v144
	v_mov_b32_e32 v140, v144
	v_mov_b32_e32 v141, v144
	v_mov_b32_e32 v142, v144
	v_mov_b32_e32 v143, v144
.LBB0_120:
	s_barrier
	s_mov_b32 m0, s62
	s_nop 0
	global_load_lds_dwordx4 v252, s[56:57]
	s_add_u32 m0, s62, 0x1000
	s_nop 0
	global_load_lds_dwordx4 v253, s[56:57]
	s_add_u32 s56, s56, 0x20000
	s_addc_u32 s57, s57, 0
	s_add_u32 m0, s62, 0x2000
	s_nop 0
	global_load_lds_dwordx4 v252, s[56:57]
	s_add_u32 m0, s62, 0x3000
	s_nop 0
	global_load_lds_dwordx4 v253, s[56:57]
	s_add_u32 s56, s56, 0x20000
	s_addc_u32 s57, s57, 0
	s_add_u32 m0, s62, 0x4000
	s_nop 0
	global_load_lds_dwordx4 v252, s[56:57]
	s_add_u32 m0, s62, 0x5000
	s_nop 0
	global_load_lds_dwordx4 v253, s[56:57]
	s_add_u32 s56, s56, 0x20000
	s_addc_u32 s57, s57, 0
	s_add_u32 m0, s62, 0x6000
	s_nop 0
	global_load_lds_dwordx4 v252, s[56:57]
	s_add_u32 m0, s62, 0x7000
	s_nop 0
	global_load_lds_dwordx4 v253, s[56:57]
	s_sub_u32 s56, s56, 0x60000
	s_subb_u32 s57, s57, 0
	s_add_u32 m0, s62, 0x8000
	s_nop 0
	global_load_lds_dwordx4 v252, s[58:59]
	s_add_u32 m0, s62, 0x9000
	s_nop 0
	global_load_lds_dwordx4 v253, s[58:59]
	s_add_u32 s58, s58, 0x20000
	s_addc_u32 s59, s59, 0
	s_add_u32 m0, s62, 0xa000
	s_nop 0
	global_load_lds_dwordx4 v252, s[58:59]
	s_add_u32 m0, s62, 0xb000
	s_nop 0
	global_load_lds_dwordx4 v253, s[58:59]
	s_sub_u32 s58, s58, 0x20000
	s_subb_u32 s59, s59, 0
	v_add_u32_e32 v252, 0x80, v252
	v_add_u32_e32 v253, 0x80, v253
	s_waitcnt vmcnt(0)
	s_barrier
	ds_read_b128 v[148:151], v215 offset:32768
	ds_read_b128 v[152:155], v215 offset:34816
	ds_read_b128 v[156:159], v213
	ds_read_b128 v[160:163], v213 offset:2048
	ds_read_b128 v[164:167], v215 offset:40960
	ds_read_b128 v[168:171], v215 offset:43008
	s_waitcnt lgkmcnt(3)
	v_mfma_f32_16x16x32_bf16 v[140:143], v[148:151], v[156:159], v[140:143]
	v_mfma_f32_16x16x32_bf16 v[136:139], v[152:155], v[156:159], v[136:139]
	s_waitcnt lgkmcnt(1)
	v_mfma_f32_16x16x32_bf16 v[132:135], v[164:167], v[156:159], v[132:135]
	s_waitcnt lgkmcnt(0)
	v_mfma_f32_16x16x32_bf16 v[128:131], v[168:171], v[156:159], v[128:131]
	v_mfma_f32_16x16x32_bf16 v[124:127], v[148:151], v[160:163], v[124:127]
	v_mfma_f32_16x16x32_bf16 v[120:123], v[152:155], v[160:163], v[120:123]
	v_mfma_f32_16x16x32_bf16 v[116:119], v[164:167], v[160:163], v[116:119]
	v_mfma_f32_16x16x32_bf16 v[104:107], v[168:171], v[160:163], v[104:107]
	ds_read_b128 v[156:159], v213 offset:4096
	ds_read_b128 v[160:163], v213 offset:6144
	s_waitcnt lgkmcnt(1)
	v_mfma_f32_16x16x32_bf16 v[88:91], v[148:151], v[156:159], v[88:91]
	v_mfma_f32_16x16x32_bf16 v[84:87], v[152:155], v[156:159], v[84:87]
	v_mfma_f32_16x16x32_bf16 v[80:83], v[164:167], v[156:159], v[80:83]
	v_mfma_f32_16x16x32_bf16 v[76:79], v[168:171], v[156:159], v[76:79]
	s_waitcnt lgkmcnt(0)
	v_mfma_f32_16x16x32_bf16 v[72:75], v[148:151], v[160:163], v[72:75]
	v_mfma_f32_16x16x32_bf16 v[68:71], v[152:155], v[160:163], v[68:71]
	v_mfma_f32_16x16x32_bf16 v[64:67], v[164:167], v[160:163], v[64:67]
	v_mfma_f32_16x16x32_bf16 v[60:63], v[168:171], v[160:163], v[60:63]
	ds_read_b128 v[156:159], v213 offset:8192
	ds_read_b128 v[160:163], v213 offset:10240
	s_waitcnt lgkmcnt(1)
; template <int MI, bool SWAP, bool F8 = false>
; __device__ __forceinline__ void gemm_core(const bf16_t* __restrict__ A, int lda, const bf16_t* __restrict__ B, int ldb,
;                                           int K, char* smem, f32x4 (&acc)[MI][4]) {
;     ...
;   for (int kt = 0; kt < nk; ++kt) {
;     __syncthreads();
; #pragma unroll
;     for (int i = 0; i < MI; ++i) *(u32x4*)(smem + woff + i * 4096) = ra[i];
; #pragma unroll
;     for (int i = 0; i < 4; ++i) *(u32x4*)(smem + 32768 + woff + i * 4096) = rb[i];
;     __syncthreads();
;     if (kt + 1 < nk) {
; #pragma unroll
;       for (int i = 0; i < MI; ++i) ra[i] = *(const u32x4*)(ap + (size_t)(32 * i) * lda + (kt + 1) * 64);
; #pragma unroll
;       for (int i = 0; i < 4; ++i) rb[i] = *(const u32x4*)(bp + (size_t)(32 * i) * ldb + (kt + 1) * 64);
;     }
;     if (F8) {
;       const int c0 = (g ^ (li & 7)) << 4, c1 = ((4 + g) ^ (li & 7)) << 4;
;       i32x8 wf8[4];
; #pragma unroll
;       for (int j = 0; j < 4; ++j) {
;         const char* rp = smem + wrow + ((j & 1) * 16 + (j >> 1) * 64) * 128;
;         const u32x4 lo = *(const u32x4*)(rp + c0), hi = *(const u32x4*)(rp + c1);
;         wf8[j] = (i32x8){(int)lo.x, (int)lo.y, (int)lo.z, (int)lo.w, (int)hi.x, (int)hi.y, (int)hi.z, (int)hi.w};
;       }
; #pragma unroll
;       for (int i = 0; i < MI; ++i) {
;         const char* rp = smem + xrow + i * 2048;
;         const u32x4 lo = *(const u32x4*)(rp + c0), hi = *(const u32x4*)(rp + c1);
;         const i32x8 xf8 = {(int)lo.x, (int)lo.y, (int)lo.z, (int)lo.w, (int)hi.x, (int)hi.y, (int)hi.z, (int)hi.w};
; #pragma unroll
;         for (int j = 0; j < 4; ++j)
;           acc[i][j] = __builtin_amdgcn_mfma_scale_f32_16x16x128_f8f6f4(wf8[j], xf8, acc[i][j], 0, 0, 0, 0x77777777, 0, 0x7f7f7f7f);
;       }
;     } else {
; #pragma unroll
;     for (int kk = 0; kk < 2; ++kk) {
;       const int ch = ((kk * 4 + g) ^ (li & 7)) << 4;
;       bf16x8 xf[MI], wf[4];
; #pragma unroll
;       for (int j = 0; j < 4; ++j) wf[j] = *(const bf16x8*)(smem + wrow + ((j & 1) * 16 + (j >> 1) * 64) * 128 + ch);
; #pragma unroll
;       for (int i = 0; i < MI; ++i) xf[i] = *(const bf16x8*)(smem + xrow + i * 2048 + ch);
; #pragma unroll
;       for (int i = 0; i < MI; ++i)
; #pragma unroll
;         for (int j = 0; j < 4; ++j) {
	v_mfma_f32_16x16x32_bf16 v[44:47], v[148:151], v[156:159], v[44:47]
	v_mfma_f32_16x16x32_bf16 v[40:43], v[152:155], v[156:159], v[40:43]
	v_mfma_f32_16x16x32_bf16 v[36:39], v[164:167], v[156:159], v[36:39]
	v_mfma_f32_16x16x32_bf16 v[32:35], v[168:171], v[156:159], v[32:35]
	s_waitcnt lgkmcnt(0)
	v_mfma_f32_16x16x32_bf16 v[28:31], v[148:151], v[160:163], v[28:31]
	v_mfma_f32_16x16x32_bf16 v[24:27], v[152:155], v[160:163], v[24:27]
	v_mfma_f32_16x16x32_bf16 v[20:23], v[164:167], v[160:163], v[20:23]
	v_mfma_f32_16x16x32_bf16 v[52:55], v[168:171], v[160:163], v[52:55]
	ds_read_b128 v[156:159], v213 offset:12288
	ds_read_b128 v[160:163], v213 offset:14336
	ds_read_b128 v[172:175], v206 offset:32768
	ds_read_b128 v[180:183], v206 offset:34816
	s_waitcnt lgkmcnt(3)
	v_mfma_f32_16x16x32_bf16 v[48:51], v[148:151], v[156:159], v[48:51]
	v_mfma_f32_16x16x32_bf16 v[56:59], v[152:155], v[156:159], v[56:59]
	s_waitcnt lgkmcnt(2)
	v_mfma_f32_16x16x32_bf16 v[100:103], v[148:151], v[160:163], v[100:103]
	v_mfma_f32_16x16x32_bf16 v[96:99], v[152:155], v[160:163], v[96:99]
	ds_read_b128 v[148:151], v0
	ds_read_b128 v[152:155], v0 offset:2048
	ds_read_b128 v[192:195], v206 offset:40960
	ds_read_b128 v[196:199], v206 offset:43008
	s_waitcnt lgkmcnt(3)
	v_mfma_f32_16x16x32_bf16 v[140:143], v[172:175], v[148:151], v[140:143]
	v_mfma_f32_16x16x32_bf16 v[136:139], v[180:183], v[148:151], v[136:139]
	s_waitcnt lgkmcnt(1)
	v_mfma_f32_16x16x32_bf16 v[132:135], v[192:195], v[148:151], v[132:135]
	s_waitcnt lgkmcnt(0)
	v_mfma_f32_16x16x32_bf16 v[128:131], v[196:199], v[148:151], v[128:131]
	v_mfma_f32_16x16x32_bf16 v[124:127], v[172:175], v[152:155], v[124:127]
	v_mfma_f32_16x16x32_bf16 v[120:123], v[180:183], v[152:155], v[120:123]
	v_mfma_f32_16x16x32_bf16 v[116:119], v[192:195], v[152:155], v[116:119]
	v_mfma_f32_16x16x32_bf16 v[104:107], v[196:199], v[152:155], v[104:107]
	ds_read_b128 v[148:151], v0 offset:4096
	ds_read_b128 v[152:155], v0 offset:6144
	v_mfma_f32_16x16x32_bf16 v[112:115], v[164:167], v[156:159], v[112:115]
	v_mfma_f32_16x16x32_bf16 v[92:95], v[164:167], v[160:163], v[92:95]
	v_mfma_f32_16x16x32_bf16 v[108:111], v[168:171], v[156:159], v[108:111]
	v_mfma_f32_16x16x32_bf16 v[144:147], v[168:171], v[160:163], v[144:147]
	s_waitcnt lgkmcnt(0)
	v_mfma_f32_16x16x32_bf16 v[72:75], v[172:175], v[152:155], v[72:75]
	v_mfma_f32_16x16x32_bf16 v[68:71], v[180:183], v[152:155], v[68:71]
	v_mfma_f32_16x16x32_bf16 v[64:67], v[192:195], v[152:155], v[64:67]
	v_mfma_f32_16x16x32_bf16 v[60:63], v[196:199], v[152:155], v[60:63]
	v_mfma_f32_16x16x32_bf16 v[88:91], v[172:175], v[148:151], v[88:91]
	v_mfma_f32_16x16x32_bf16 v[84:87], v[180:183], v[148:151], v[84:87]
	v_mfma_f32_16x16x32_bf16 v[80:83], v[192:195], v[148:151], v[80:83]
	v_mfma_f32_16x16x32_bf16 v[76:79], v[196:199], v[148:151], v[76:79]
	ds_read_b128 v[148:151], v0 offset:8192
	ds_read_b128 v[156:159], v0 offset:10240
	ds_read_b128 v[160:163], v0 offset:12288
	ds_read_b128 v[200:203], v0 offset:14336
	s_waitcnt lgkmcnt(3)
	v_mfma_f32_16x16x32_bf16 v[44:47], v[172:175], v[148:151], v[44:47]
	v_mfma_f32_16x16x32_bf16 v[40:43], v[180:183], v[148:151], v[40:43]
	v_mfma_f32_16x16x32_bf16 v[36:39], v[192:195], v[148:151], v[36:39]
	v_mfma_f32_16x16x32_bf16 v[32:35], v[196:199], v[148:151], v[32:35]
	s_waitcnt lgkmcnt(2)
	v_mfma_f32_16x16x32_bf16 v[28:31], v[172:175], v[156:159], v[28:31]
	v_mfma_f32_16x16x32_bf16 v[24:27], v[180:183], v[156:159], v[24:27]
	v_mfma_f32_16x16x32_bf16 v[20:23], v[192:195], v[156:159], v[20:23]
	v_mfma_f32_16x16x32_bf16 v[52:55], v[196:199], v[156:159], v[52:55]
	s_waitcnt lgkmcnt(1)
	v_mfma_f32_16x16x32_bf16 v[48:51], v[172:175], v[160:163], v[48:51]
	v_mfma_f32_16x16x32_bf16 v[56:59], v[180:183], v[160:163], v[56:59]
	v_mfma_f32_16x16x32_bf16 v[112:115], v[192:195], v[160:163], v[112:115]
	v_mfma_f32_16x16x32_bf16 v[108:111], v[196:199], v[160:163], v[108:111]
	s_waitcnt lgkmcnt(0)
	v_mfma_f32_16x16x32_bf16 v[100:103], v[172:175], v[200:203], v[100:103]
	v_mfma_f32_16x16x32_bf16 v[96:99], v[180:183], v[200:203], v[96:99]
	v_mfma_f32_16x16x32_bf16 v[92:95], v[192:195], v[200:203], v[92:95]
	v_mfma_f32_16x16x32_bf16 v[144:147], v[196:199], v[200:203], v[144:147]
	s_add_u32 s22, s22, 0x80
	s_addc_u32 s23, s23, 0
	s_cmpk_lg_i32 s22, 0x780
	s_cbranch_scc1 .LBB0_120
	s_barrier
	s_mov_b32 m0, s62
	s_nop 0
	global_load_lds_dwordx4 v252, s[56:57]
	s_add_u32 m0, s62, 0x1000
	s_nop 0
	global_load_lds_dwordx4 v253, s[56:57]
	s_add_u32 s56, s56, 0x20000
	s_addc_u32 s57, s57, 0
	s_add_u32 m0, s62, 0x2000
	s_nop 0
	global_load_lds_dwordx4 v252, s[56:57]
	s_add_u32 m0, s62, 0x3000
	s_nop 0
	global_load_lds_dwordx4 v253, s[56:57]
	s_add_u32 s56, s56, 0x20000
	s_addc_u32 s57, s57, 0
	s_add_u32 m0, s62, 0x4000
	s_nop 0
	global_load_lds_dwordx4 v252, s[56:57]
	s_add_u32 m0, s62, 0x5000
	s_nop 0
	global_load_lds_dwordx4 v253, s[56:57]
	s_add_u32 s56, s56, 0x20000
	s_addc_u32 s57, s57, 0
	s_add_u32 m0, s62, 0x6000
	s_nop 0
	global_load_lds_dwordx4 v252, s[56:57]
	s_add_u32 m0, s62, 0x7000
	s_nop 0
	global_load_lds_dwordx4 v253, s[56:57]
	s_sub_u32 s56, s56, 0x60000
	s_subb_u32 s57, s57, 0
	s_add_u32 m0, s62, 0x8000
	s_nop 0
	global_load_lds_dwordx4 v252, s[58:59]
	s_add_u32 m0, s62, 0x9000
	s_nop 0
	global_load_lds_dwordx4 v253, s[58:59]
	s_add_u32 s58, s58, 0x20000
	s_addc_u32 s59, s59, 0
	s_add_u32 m0, s62, 0xa000
	s_nop 0
	global_load_lds_dwordx4 v252, s[58:59]
	s_add_u32 m0, s62, 0xb000
	s_nop 0
	global_load_lds_dwordx4 v253, s[58:59]
	s_sub_u32 s58, s58, 0x20000
	s_subb_u32 s59, s59, 0
	s_waitcnt vmcnt(0)
	s_barrier
; template <int MI, bool SWAP, bool F8 = false>
; __device__ __forceinline__ void gemm_core(const bf16_t* __restrict__ A, int lda, const bf16_t* __restrict__ B, int ldb,
;                                           int K, char* smem, f32x4 (&acc)[MI][4]) {
;     ...
;     for (int kk = 0; kk < 2; ++kk) {
;       const int ch = ((kk * 4 + g) ^ (li & 7)) << 4;
;       bf16x8 xf[MI], wf[4];
; #pragma unroll
;       for (int j = 0; j < 4; ++j) wf[j] = *(const bf16x8*)(smem + wrow + ((j & 1) * 16 + (j >> 1) * 64) * 128 + ch);
; #pragma unroll
;       for (int i = 0; i < MI; ++i) xf[i] = *(const bf16x8*)(smem + xrow + i * 2048 + ch);
; #pragma unroll
;       for (int i = 0; i < MI; ++i)
; #pragma unroll
;         for (int j = 0; j < 4; ++j) {
;           if (SWAP) acc[i][j] = __builtin_amdgcn_mfma_f32_16x16x32_bf16(xf[i], wf[j], acc[i][j], 0, 0, 0);
;           else acc[i][j] = __builtin_amdgcn_mfma_f32_16x16x32_bf16(wf[j], xf[i], acc[i][j], 0, 0, 0);
;         }
; template <int MI, bool F8 = false>
; __device__ void gemm_tile_bf16(const bf16_t* A, int lda, const bf16_t* B, int ldb, int K, bf16_t* C, int ldc, char* smem) {
;     ...
; #pragma unroll
;   for (int i = 0; i < MI; ++i)
; #pragma unroll
;     for (int j = 0; j < 4; ++j) {
;       u32x2 v;
;       v.x = pk_bf16(acc[i][j][0], acc[i][j][1]);
;       v.y = pk_bf16(acc[i][j][2], acc[i][j][3]);
;       *(u32x2*)(C + (size_t)MROW(i) * ldc + NCOL(j)) = v;
;     }
	ds_read_b128 v[148:151], v215 offset:32768
	ds_read_b128 v[152:155], v215 offset:34816
	ds_read_b128 v[156:159], v215 offset:40960
	ds_read_b128 v[160:163], v215 offset:43008
	ds_read_b128 v[164:167], v213
	ds_read_b128 v[168:171], v213 offset:2048
	ds_read_b128 v[172:175], v213 offset:4096
	ds_read_b128 v[176:179], v213 offset:6144
	ds_read_b128 v[180:183], v213 offset:8192
	ds_read_b128 v[184:187], v213 offset:10240
	ds_read_b128 v[188:191], v213 offset:12288
	ds_read_b128 v[192:195], v213 offset:14336
	s_waitcnt lgkmcnt(7)
	v_mfma_f32_16x16x32_bf16 v[140:143], v[148:151], v[164:167], v[140:143]
	s_mul_hi_i32 s11, s10, 0x180000
	s_mul_i32 s10, s10, 0x180000
	s_add_u32 s22, s8, s10
	v_mfma_f32_16x16x32_bf16 v[136:139], v[152:155], v[164:167], v[136:139]
	s_addc_u32 s23, s9, s11
	s_lshl_b64 s[10:11], s[20:21], 1
	s_add_u32 s10, s22, s10
	v_mfma_f32_16x16x32_bf16 v[132:135], v[156:159], v[164:167], v[132:135]
	s_addc_u32 s11, s23, s11
	s_movk_i32 s20, 0x1800
	s_add_i32 s28, s28, s78
	v_mfma_f32_16x16x32_bf16 v[128:131], v[160:163], v[164:167], v[128:131]
	s_add_i32 s27, s27, s71
	s_cmpk_gt_i32 s28, 0x5ff
	s_waitcnt lgkmcnt(6)
	v_mfma_f32_16x16x32_bf16 v[124:127], v[148:151], v[168:171], v[124:127]
	v_mfma_f32_16x16x32_bf16 v[120:123], v[152:155], v[168:171], v[120:123]
	v_mfma_f32_16x16x32_bf16 v[116:119], v[156:159], v[168:171], v[116:119]
	v_mfma_f32_16x16x32_bf16 v[104:107], v[160:163], v[168:171], v[104:107]
	s_waitcnt lgkmcnt(5)
	v_mfma_f32_16x16x32_bf16 v[88:91], v[148:151], v[172:175], v[88:91]
	v_mfma_f32_16x16x32_bf16 v[84:87], v[152:155], v[172:175], v[84:87]
	v_mfma_f32_16x16x32_bf16 v[80:83], v[156:159], v[172:175], v[80:83]
	v_mfma_f32_16x16x32_bf16 v[76:79], v[160:163], v[172:175], v[76:79]
	s_waitcnt lgkmcnt(4)
	v_mfma_f32_16x16x32_bf16 v[72:75], v[148:151], v[176:179], v[72:75]
	v_mfma_f32_16x16x32_bf16 v[68:71], v[152:155], v[176:179], v[68:71]
	v_mfma_f32_16x16x32_bf16 v[64:67], v[156:159], v[176:179], v[64:67]
	v_mfma_f32_16x16x32_bf16 v[60:63], v[160:163], v[176:179], v[60:63]
	s_waitcnt lgkmcnt(3)
	v_mfma_f32_16x16x32_bf16 v[44:47], v[148:151], v[180:183], v[44:47]
	v_mfma_f32_16x16x32_bf16 v[40:43], v[152:155], v[180:183], v[40:43]
	v_mfma_f32_16x16x32_bf16 v[36:39], v[156:159], v[180:183], v[36:39]
	v_mfma_f32_16x16x32_bf16 v[32:35], v[160:163], v[180:183], v[32:35]
	s_waitcnt lgkmcnt(2)
	v_mfma_f32_16x16x32_bf16 v[28:31], v[148:151], v[184:187], v[28:31]
	v_mfma_f32_16x16x32_bf16 v[24:27], v[152:155], v[184:187], v[24:27]
	v_mfma_f32_16x16x32_bf16 v[20:23], v[156:159], v[184:187], v[20:23]
	v_mfma_f32_16x16x32_bf16 v[52:55], v[160:163], v[184:187], v[52:55]
	s_waitcnt lgkmcnt(1)
	v_mfma_f32_16x16x32_bf16 v[48:51], v[148:151], v[188:191], v[48:51]
	v_mfma_f32_16x16x32_bf16 v[164:167], v[152:155], v[188:191], v[56:59]
	v_mfma_f32_16x16x32_bf16 v[168:171], v[156:159], v[188:191], v[112:115]
	v_mfma_f32_16x16x32_bf16 v[172:175], v[160:163], v[188:191], v[108:111]
	s_waitcnt lgkmcnt(0)
	v_mfma_f32_16x16x32_bf16 v[148:151], v[148:151], v[192:195], v[100:103]
	v_mfma_f32_16x16x32_bf16 v[152:155], v[152:155], v[192:195], v[96:99]
	v_mfma_f32_16x16x32_bf16 v[156:159], v[156:159], v[192:195], v[92:95]
	v_mfma_f32_16x16x32_bf16 v[144:147], v[160:163], v[192:195], v[144:147]
	ds_read_b128 v[160:163], v206 offset:32768
	ds_read_b128 v[176:179], v206 offset:34816
	ds_read_b128 v[180:183], v206 offset:40960
	ds_read_b128 v[184:187], v206 offset:43008
	ds_read_b128 v[56:59], v0
	ds_read_b128 v[92:95], v0 offset:2048
	ds_read_b128 v[96:99], v0 offset:4096
	ds_read_b128 v[188:191], v0 offset:6144
	ds_read_b128 v[192:195], v0 offset:8192
	ds_read_b128 v[196:199], v0 offset:10240
	ds_read_b128 v[200:203], v0 offset:12288
	ds_read_b128 v[204:207], v0 offset:14336
	s_waitcnt lgkmcnt(7)
	v_mfma_f32_16x16x32_bf16 v[140:143], v[160:163], v[56:59], v[140:143]
	v_mfma_f32_16x16x32_bf16 v[136:139], v[176:179], v[56:59], v[136:139]
	v_mfma_f32_16x16x32_bf16 v[132:135], v[180:183], v[56:59], v[132:135]
	s_nop 5
	v_cvt_pk_bf16_f32 v140, v140, v141
	v_cvt_pk_bf16_f32 v141, v142, v143
	v_cvt_pk_bf16_f32 v136, v136, v137
	v_mfma_f32_16x16x32_bf16 v[128:131], v[184:187], v[56:59], v[128:131]
	v_cvt_pk_bf16_f32 v137, v138, v139
	v_cvt_pk_bf16_f32 v132, v132, v133
	v_cvt_pk_bf16_f32 v133, v134, v135
	s_waitcnt lgkmcnt(2)
	v_mfma_f32_16x16x32_bf16 v[56:59], v[180:183], v[196:199], v[20:23]
	s_waitcnt lgkmcnt(0)
; template <int MI, bool F8 = false>
; __device__ void gemm_tile_bf16(const bf16_t* A, int lda, const bf16_t* B, int ldb, int K, bf16_t* C, int ldc, char* smem) {
;     ...
; #pragma unroll
;   for (int i = 0; i < MI; ++i)
; #pragma unroll
;     for (int j = 0; j < 4; ++j) {
;       u32x2 v;
;       v.x = pk_bf16(acc[i][j][0], acc[i][j][1]);
;       v.y = pk_bf16(acc[i][j][2], acc[i][j][3]);
;       *(u32x2*)(C + (size_t)MROW(i) * ldc + NCOL(j)) = v;
;     }
	v_mfma_f32_16x16x32_bf16 v[20:23], v[184:187], v[204:207], v[144:147]
	s_nop 0
	v_cvt_pk_bf16_f32 v128, v128, v129
	v_cvt_pk_bf16_f32 v129, v130, v131
	s_nop 2
	v_cvt_pk_bf16_f32 v56, v56, v57
	v_mov_b32_e32 v146, v208
	v_mfma_f32_16x16x32_bf16 v[124:127], v[160:163], v[92:95], v[124:127]
	v_lshrrev_b32_e32 v0, 1, v146
	v_and_b32_e32 v0, 32, v0
	v_lshrrev_b32_e32 v2, 2, v146
	v_and_b32_e32 v147, 0xffffff8f, v146
	v_and_or_b32 v0, v2, 12, v0
	v_mov_b64_e32 v[2:3], s[10:11]
	v_mfma_f32_16x16x32_bf16 v[216:219], v[180:183], v[92:95], v[116:119]
	v_mad_i64_i32 v[144:145], s[10:11], v147, s20, v[2:3]
	v_lshlrev_b32_e32 v0, 1, v0
	v_mfma_f32_16x16x32_bf16 v[116:119], v[184:187], v[92:95], v[104:107]
	v_lshl_add_u64 v[142:143], v[144:145], 0, v[0:1]
	global_store_dwordx2 v[142:143], v[128:129], off offset:160
	v_or_b32_e32 v128, 16, v147
	v_mfma_f32_16x16x32_bf16 v[112:115], v[160:163], v[96:99], v[88:91]
	v_mad_i64_i32 v[128:129], s[10:11], v128, s20, v[2:3]
	v_cvt_pk_bf16_f32 v124, v124, v125
	v_mfma_f32_16x16x32_bf16 v[100:103], v[184:187], v[96:99], v[76:79]
	v_cvt_pk_bf16_f32 v125, v126, v127
	v_lshl_add_u64 v[126:127], v[128:129], 0, v[0:1]
	v_cvt_pk_bf16_f32 v116, v116, v117
	v_cvt_pk_bf16_f32 v117, v118, v119
	global_store_dwordx2 v[126:127], v[116:117], off offset:160
	v_or_b32_e32 v116, 32, v147
	v_mfma_f32_16x16x32_bf16 v[108:111], v[176:179], v[96:99], v[84:87]
	v_mad_i64_i32 v[116:117], s[10:11], v116, s20, v[2:3]
	v_cvt_pk_bf16_f32 v112, v112, v113
	v_mfma_f32_16x16x32_bf16 v[104:107], v[180:183], v[96:99], v[80:83]
	v_cvt_pk_bf16_f32 v113, v114, v115
	v_lshl_add_u64 v[114:115], v[116:117], 0, v[0:1]
	v_cvt_pk_bf16_f32 v100, v100, v101
	v_mfma_f32_16x16x32_bf16 v[96:99], v[160:163], v[188:191], v[72:75]
	v_cvt_pk_bf16_f32 v101, v102, v103
	global_store_dwordx2 v[114:115], v[100:101], off offset:160
	v_or_b32_e32 v100, 48, v147
	v_mfma_f32_16x16x32_bf16 v[84:87], v[184:187], v[188:191], v[60:63]
	v_mad_i64_i32 v[100:101], s[10:11], v100, s20, v[2:3]
	s_nop 2
	v_cvt_pk_bf16_f32 v96, v96, v97
	v_mfma_f32_16x16x32_bf16 v[120:123], v[176:179], v[92:95], v[120:123]
	v_cvt_pk_bf16_f32 v97, v98, v99
	v_lshl_add_u64 v[98:99], v[100:101], 0, v[0:1]
	v_cvt_pk_bf16_f32 v84, v84, v85
	v_mfma_f32_16x16x32_bf16 v[92:95], v[176:179], v[188:191], v[68:71]
	v_cvt_pk_bf16_f32 v85, v86, v87
	global_store_dwordx2 v[98:99], v[84:85], off offset:160
	v_or_b32_e32 v84, 64, v147
	v_mfma_f32_16x16x32_bf16 v[80:83], v[160:163], v[192:195], v[44:47]
	v_mad_i64_i32 v[84:85], s[10:11], v84, s20, v[2:3]
	v_cvt_pk_bf16_f32 v120, v120, v121
	v_mfma_f32_16x16x32_bf16 v[68:71], v[184:187], v[192:195], v[32:35]
	v_cvt_pk_bf16_f32 v121, v122, v123
	s_nop 3
	v_cvt_pk_bf16_f32 v80, v80, v81
	v_cvt_pk_bf16_f32 v81, v82, v83
	v_mfma_f32_16x16x32_bf16 v[88:91], v[180:183], v[188:191], v[64:67]
	v_lshl_add_u64 v[82:83], v[84:85], 0, v[0:1]
	v_cvt_pk_bf16_f32 v68, v68, v69
	v_cvt_pk_bf16_f32 v69, v70, v71
	v_mfma_f32_16x16x32_bf16 v[64:67], v[160:163], v[196:199], v[28:31]
	global_store_dwordx2 v[82:83], v[68:69], off offset:160
	v_or_b32_e32 v68, 0x50, v147
	v_mad_i64_i32 v[68:69], s[10:11], v68, s20, v[2:3]
	v_mfma_f32_16x16x32_bf16 v[52:55], v[184:187], v[196:199], v[52:55]
	s_nop 3
	v_cvt_pk_bf16_f32 v64, v64, v65
	v_cvt_pk_bf16_f32 v65, v66, v67
	v_lshl_add_u64 v[66:67], v[68:69], 0, v[0:1]
	v_mfma_f32_16x16x32_bf16 v[72:75], v[180:183], v[192:195], v[36:39]
	global_store_dwordx2 v[126:127], v[120:121], off offset:32
	v_cvt_pk_bf16_f32 v52, v52, v53
	v_cvt_pk_bf16_f32 v53, v54, v55
	v_mfma_f32_16x16x32_bf16 v[48:51], v[160:163], v[200:203], v[48:51]
	global_store_dwordx2 v[66:67], v[52:53], off offset:160
	v_or_b32_e32 v52, 0x60, v147
	v_mad_i64_i32 v[52:53], s[10:11], v52, s20, v[2:3]
	v_mfma_f32_16x16x32_bf16 v[36:39], v[184:187], v[200:203], v[172:175]
	s_nop 3
	v_cvt_pk_bf16_f32 v48, v48, v49
	v_cvt_pk_bf16_f32 v49, v50, v51
	v_lshl_add_u64 v[50:51], v[52:53], 0, v[0:1]
	v_mfma_f32_16x16x32_bf16 v[76:79], v[176:179], v[192:195], v[40:43]
	v_cvt_pk_bf16_f32 v120, v216, v217
	v_cvt_pk_bf16_f32 v36, v36, v37
	v_cvt_pk_bf16_f32 v37, v38, v39
	v_mfma_f32_16x16x32_bf16 v[60:63], v[176:179], v[196:199], v[24:27]
	global_store_dwordx2 v[50:51], v[36:37], off offset:160
	v_or_b32_e32 v36, 0x70, v146
	v_mad_i64_i32 v[2:3], s[10:11], v36, s20, v[2:3]
	v_mfma_f32_16x16x32_bf16 v[44:47], v[176:179], v[200:203], v[164:167]
	v_cvt_pk_bf16_f32 v121, v218, v219
	v_cvt_pk_bf16_f32 v108, v108, v109
	v_cvt_pk_bf16_f32 v109, v110, v111
	v_mfma_f32_16x16x32_bf16 v[40:43], v[180:183], v[200:203], v[168:171]
	v_cvt_pk_bf16_f32 v104, v104, v105
	v_cvt_pk_bf16_f32 v105, v106, v107
	v_cvt_pk_bf16_f32 v92, v92, v93
	v_mfma_f32_16x16x32_bf16 v[32:35], v[160:163], v[204:207], v[148:151]
	v_cvt_pk_bf16_f32 v93, v94, v95
	v_cvt_pk_bf16_f32 v88, v88, v89
	v_cvt_pk_bf16_f32 v89, v90, v91
	v_mfma_f32_16x16x32_bf16 v[28:31], v[176:179], v[204:207], v[152:155]
	v_cvt_pk_bf16_f32 v76, v76, v77
	v_cvt_pk_bf16_f32 v77, v78, v79
	v_cvt_pk_bf16_f32 v72, v72, v73
	v_mfma_f32_16x16x32_bf16 v[24:27], v[180:183], v[204:207], v[156:159]
	v_cvt_pk_bf16_f32 v73, v74, v75
	v_cvt_pk_bf16_f32 v60, v60, v61
	v_cvt_pk_bf16_f32 v61, v62, v63
	v_cvt_pk_bf16_f32 v57, v58, v59
	v_cvt_pk_bf16_f32 v44, v44, v45
	v_cvt_pk_bf16_f32 v45, v46, v47
	v_cvt_pk_bf16_f32 v40, v40, v41
	v_cvt_pk_bf16_f32 v41, v42, v43
	v_cvt_pk_bf16_f32 v32, v32, v33
	v_cvt_pk_bf16_f32 v33, v34, v35
	v_lshl_add_u64 v[2:3], v[2:3], 0, v[0:1]
	v_cvt_pk_bf16_f32 v28, v28, v29
	v_cvt_pk_bf16_f32 v29, v30, v31
	v_cvt_pk_bf16_f32 v24, v24, v25
	v_cvt_pk_bf16_f32 v25, v26, v27
	v_cvt_pk_bf16_f32 v20, v20, v21
	v_cvt_pk_bf16_f32 v21, v22, v23
	global_store_dwordx2 v[142:143], v[140:141], off
	global_store_dwordx2 v[142:143], v[136:137], off offset:32
	global_store_dwordx2 v[142:143], v[132:133], off offset:128
	global_store_dwordx2 v[126:127], v[124:125], off
	global_store_dwordx2 v[126:127], v[120:121], off offset:128
	global_store_dwordx2 v[114:115], v[112:113], off
	global_store_dwordx2 v[114:115], v[108:109], off offset:32
	global_store_dwordx2 v[114:115], v[104:105], off offset:128
	global_store_dwordx2 v[98:99], v[96:97], off
	global_store_dwordx2 v[98:99], v[92:93], off offset:32
	global_store_dwordx2 v[98:99], v[88:89], off offset:128
	global_store_dwordx2 v[82:83], v[80:81], off
	global_store_dwordx2 v[82:83], v[76:77], off offset:32
	global_store_dwordx2 v[82:83], v[72:73], off offset:128
	global_store_dwordx2 v[66:67], v[64:65], off
	global_store_dwordx2 v[66:67], v[60:61], off offset:32
	global_store_dwordx2 v[66:67], v[56:57], off offset:128
	global_store_dwordx2 v[50:51], v[48:49], off
	global_store_dwordx2 v[50:51], v[44:45], off offset:32
	global_store_dwordx2 v[50:51], v[40:41], off offset:128
	global_store_dwordx2 v[2:3], v[32:33], off
	global_store_dwordx2 v[2:3], v[28:29], off offset:32
	global_store_dwordx2 v[2:3], v[24:25], off offset:128
	global_store_dwordx2 v[2:3], v[20:21], off offset:160
	s_cbranch_scc0 .LBB0_119

; __device__ __forceinline__ int otid() { int t = threadIdx.x; asm volatile("" : "+v"(t)); return t; }
; template <int MI, bool SWAP, bool F8 = false>
; __device__ __forceinline__ void gemm_core(const bf16_t* __restrict__ A, int lda, const bf16_t* __restrict__ B, int ldb,
;                                           int K, char* smem, f32x4 (&acc)[MI][4]) {
;   const int tid = otid(), lane = tid & 63, w = tid >> 6, wm = w >> 1, wn = w & 1;
;   const int lr = tid >> 3, lc = tid & 7;
;   const int li = lane & 15, g = lane >> 4;
;   u32x4 ra[MI], rb[4];
;   const bf16_t* ap = A + (size_t)lr * lda + lc * 8;
;   const bf16_t* bp = B + (size_t)lr * ldb + lc * 8;
; #pragma unroll
;   for (int i = 0; i < MI; ++i)
; #pragma unroll
;     for (int j = 0; j < 4; ++j) acc[i][j] = (f32x4){0.f, 0.f, 0.f, 0.f};
;   const int nk = K >> 6;
; #pragma unroll
;   for (int i = 0; i < MI; ++i) ra[i] = *(const u32x4*)(ap + (size_t)(32 * i) * lda);
; #pragma unroll
;   for (int i = 0; i < 4; ++i) rb[i] = *(const u32x4*)(bp + (size_t)(32 * i) * ldb);
;   const int woff = lr * 128 + ((lc ^ (lr & 7)) << 4);
;   const int xrow = (wm * 16 * MI + li) * 128;
;   const int wrow = 32768 + (wn * 32 + li) * 128;
.LBB0_235:
	s_lshl_b32 s10, s23, 11
	s_and_b32 s66, s10, 0x1c0000
	s_lshl_b32 s10, s25, 3
	s_and_b32 s10, s10, 56
	s_ashr_i32 s30, s25, 6
	s_add_i32 s20, s10, s30
	s_ashr_i32 s21, s20, 31
	v_mov_b32_e32 v30, v208
	s_and_b32 s27, s24, 56
	s_lshl_b64 s[10:11], s[20:21], 18
	s_lshl_b64 s[20:21], s[20:21], 19
	s_add_u32 s20, s6, s20
	v_ashrrev_i32_e32 v2, 3, v30
	v_ashrrev_i32_e32 v3, 31, v2
	s_addc_u32 s21, s7, s21
	v_lshlrev_b64 v[20:21], 11, v[2:3]
	v_lshlrev_b32_e32 v0, 4, v30
	v_lshl_add_u64 v[24:25], s[20:21], 0, v[20:21]
	v_and_b32_e32 v0, 0x70, v0
	v_lshl_add_u64 v[24:25], v[24:25], 0, v[0:1]
	v_add_co_u32_e32 v26, vcc, s93, v24
	s_lshl_b32 s26, s25, 4
	s_nop 0
	v_addc_co_u32_e32 v27, vcc, 0, v25, vcc
	v_lshrrev_b32_e32 v254, 3, v208
	v_and_b32_e32 v254, 7, v254
	v_xor_b32_e32 v252, v254, v208
	v_and_b32_e32 v252, 7, v252
	v_lshlrev_b32_e32 v252, 4, v252
	v_lshl_or_b32 v252, v254, 11, v252
	v_add_u32_e32 v253, 0x10000, v252
	v_lshrrev_b32_e32 v254, 6, v208
	s_nop 0
	v_readfirstlane_b32 s62, v254
	s_lshl_b32 s62, s62, 10
	v_readfirstlane_b32 s56, v24
	v_readfirstlane_b32 s57, v25
	v_add_co_u32_e32 v26, vcc, s46, v24
	s_and_b32 s26, s26, 0x380
	s_nop 0
	v_addc_co_u32_e32 v27, vcc, 0, v25, vcc
	v_add_co_u32_e32 v28, vcc, s47, v24
	s_lshl_b32 s28, s26, 11
	s_nop 0
	v_addc_co_u32_e32 v29, vcc, 0, v25, vcc
	v_add_co_u32_e32 v26, vcc, s50, v24
	s_mov_b32 s20, 0x60000
	s_nop 0
	v_addc_co_u32_e32 v27, vcc, 0, v25, vcc
	v_add_co_u32_e32 v28, vcc, s51, v24
	s_add_u32 s28, s19, s28
	s_nop 0
	v_addc_co_u32_e32 v29, vcc, 0, v25, vcc
	v_add_co_u32_e32 v26, vcc, s20, v24
	s_addc_u32 s29, s22, 0
	s_nop 0
	v_addc_co_u32_e32 v27, vcc, 0, v25, vcc
	s_mov_b32 s20, 0x70000
	v_lshl_add_u64 v[22:23], s[28:29], 0, v[20:21]
	v_add_co_u32_e32 v24, vcc, s20, v24
	v_lshl_add_u64 v[22:23], v[22:23], 0, v[0:1]
	s_nop 0
	v_addc_co_u32_e32 v25, vcc, 0, v25, vcc
	v_add_co_u32_e32 v24, vcc, s93, v22
	v_lshlrev_b32_e32 v0, 7, v2
	s_nop 0
	v_addc_co_u32_e32 v25, vcc, 0, v23, vcc
	s_nop 0
	v_readfirstlane_b32 s58, v22
	v_readfirstlane_b32 s59, v23
	v_add_co_u32_e32 v24, vcc, s46, v22
	v_xor_b32_e32 v2, v2, v30
	s_nop 0
	v_addc_co_u32_e32 v25, vcc, 0, v23, vcc
	v_add_co_u32_e32 v22, vcc, s47, v22
	v_lshlrev_b32_e32 v2, 4, v2
	s_nop 0
	v_addc_co_u32_e32 v23, vcc, 0, v23, vcc
	v_and_or_b32 v0, v2, s33, v0
	v_lshlrev_b32_e32 v2, 7, v30
	v_and_b32_e32 v3, 15, v30
	v_and_b32_e32 v202, 0xffffc780, v2
	v_lshrrev_b32_e32 v2, 1, v30
	v_lshrrev_b32_e32 v31, 4, v30
	v_and_or_b32 v2, v2, 32, v3
	v_and_b32_e32 v23, 7, v30
	s_add_i32 s20, s30, s27
	v_bfe_u32 v22, v30, 4, 2
	v_lshlrev_b32_e32 v203, 7, v2
	v_bitop3_b32 v2, v31, v23, 3 bitop3:0x6c
	s_ashr_i32 s21, s20, 31
	v_lshlrev_b32_e32 v204, 4, v2
	v_bitop3_b32 v2, v22, v23, 4 bitop3:0x36
	s_lshl_b64 s[20:21], s[20:21], 19
	v_lshlrev_b32_e32 v205, 4, v2
	v_lshl_add_u64 v[2:3], s[20:21], 0, v[20:21]
	v_lshlrev_b32_e32 v22, 4, v23
	v_lshl_add_u64 v[20:21], s[66:67], 0, v[20:21]
	v_or_b32_e32 v2, v2, v22
	v_or_b32_e32 v20, v20, v22
	v_mov_b32_e32 v144, 0
	v_lshl_add_u64 v[2:3], s[12:13], 0, v[2:3]
	v_lshl_add_u64 v[200:201], s[8:9], 0, v[20:21]
	s_mov_b64 s[20:21], 0
	v_mov_b32_e32 v145, v144
	v_mov_b32_e32 v146, v144
	v_mov_b32_e32 v147, v144
	v_mov_b32_e32 v100, v144
	v_mov_b32_e32 v101, v144
	v_mov_b32_e32 v102, v144
	v_mov_b32_e32 v103, v144
	v_mov_b32_e32 v112, v144
	v_mov_b32_e32 v113, v144
	v_mov_b32_e32 v114, v144
	v_mov_b32_e32 v115, v144
	v_mov_b32_e32 v116, v144
	v_mov_b32_e32 v117, v144
	v_mov_b32_e32 v118, v144
	v_mov_b32_e32 v119, v144
	v_mov_b32_e32 v120, v144
	v_mov_b32_e32 v121, v144
	v_mov_b32_e32 v122, v144
	v_mov_b32_e32 v123, v144
	v_mov_b32_e32 v128, v144
	v_mov_b32_e32 v129, v144
	v_mov_b32_e32 v130, v144
	v_mov_b32_e32 v131, v144
	v_mov_b32_e32 v76, v144
	v_mov_b32_e32 v77, v144
	v_mov_b32_e32 v78, v144
	v_mov_b32_e32 v79, v144
	v_mov_b32_e32 v72, v144
	v_mov_b32_e32 v73, v144
	v_mov_b32_e32 v74, v144
	v_mov_b32_e32 v75, v144
	v_mov_b32_e32 v64, v144
	v_mov_b32_e32 v65, v144
	v_mov_b32_e32 v66, v144
	v_mov_b32_e32 v67, v144
	v_mov_b32_e32 v68, v144
	v_mov_b32_e32 v69, v144
	v_mov_b32_e32 v70, v144
	v_mov_b32_e32 v71, v144
	v_mov_b32_e32 v20, v144
	v_mov_b32_e32 v21, v144
	v_mov_b32_e32 v22, v144
	v_mov_b32_e32 v23, v144
	v_mov_b32_e32 v24, v144
	v_mov_b32_e32 v25, v144
	v_mov_b32_e32 v26, v144
	v_mov_b32_e32 v27, v144
	v_mov_b32_e32 v28, v144
	v_mov_b32_e32 v29, v144
	v_mov_b32_e32 v30, v144
	v_mov_b32_e32 v31, v144
	v_mov_b32_e32 v32, v144
	v_mov_b32_e32 v33, v144
	v_mov_b32_e32 v34, v144
	v_mov_b32_e32 v35, v144
	v_mov_b32_e32 v36, v144
	v_mov_b32_e32 v37, v144
	v_mov_b32_e32 v38, v144
	v_mov_b32_e32 v39, v144
	v_mov_b32_e32 v40, v144
	v_mov_b32_e32 v41, v144
	v_mov_b32_e32 v42, v144
	v_mov_b32_e32 v43, v144
	v_mov_b32_e32 v44, v144
	v_mov_b32_e32 v45, v144
	v_mov_b32_e32 v46, v144
	v_mov_b32_e32 v47, v144
	v_mov_b32_e32 v48, v144
	v_mov_b32_e32 v49, v144
	v_mov_b32_e32 v50, v144
	v_mov_b32_e32 v51, v144
	v_mov_b32_e32 v52, v144
	v_mov_b32_e32 v53, v144
	v_mov_b32_e32 v54, v144
	v_mov_b32_e32 v55, v144
	v_mov_b32_e32 v56, v144
	v_mov_b32_e32 v57, v144
	v_mov_b32_e32 v58, v144
	v_mov_b32_e32 v59, v144
	v_mov_b32_e32 v60, v144
	v_mov_b32_e32 v61, v144
	v_mov_b32_e32 v62, v144
	v_mov_b32_e32 v63, v144
	v_mov_b32_e32 v80, v144
	v_mov_b32_e32 v81, v144
	v_mov_b32_e32 v82, v144
	v_mov_b32_e32 v83, v144
	v_mov_b32_e32 v84, v144
	v_mov_b32_e32 v85, v144
	v_mov_b32_e32 v86, v144
	v_mov_b32_e32 v87, v144
	v_mov_b32_e32 v88, v144
	v_mov_b32_e32 v89, v144
	v_mov_b32_e32 v90, v144
	v_mov_b32_e32 v91, v144
	v_mov_b32_e32 v92, v144
	v_mov_b32_e32 v93, v144
	v_mov_b32_e32 v94, v144
	v_mov_b32_e32 v95, v144
	v_mov_b32_e32 v96, v144
	v_mov_b32_e32 v97, v144
	v_mov_b32_e32 v98, v144
	v_mov_b32_e32 v99, v144
	v_mov_b32_e32 v104, v144
	v_mov_b32_e32 v105, v144
	v_mov_b32_e32 v106, v144
	v_mov_b32_e32 v107, v144
	v_mov_b32_e32 v108, v144
	v_mov_b32_e32 v109, v144
	v_mov_b32_e32 v110, v144
	v_mov_b32_e32 v111, v144
	v_mov_b32_e32 v124, v144
	v_mov_b32_e32 v125, v144
	v_mov_b32_e32 v126, v144
	v_mov_b32_e32 v127, v144
	v_mov_b32_e32 v132, v144
	v_mov_b32_e32 v133, v144
	v_mov_b32_e32 v134, v144
	v_mov_b32_e32 v135, v144
	v_mov_b32_e32 v136, v144
	v_mov_b32_e32 v137, v144
	v_mov_b32_e32 v138, v144
	v_mov_b32_e32 v139, v144
	v_mov_b32_e32 v140, v144
	v_mov_b32_e32 v141, v144
	v_mov_b32_e32 v142, v144
	v_mov_b32_e32 v143, v144
; template <int MI, bool SWAP, bool F8 = false>
; __device__ __forceinline__ void gemm_core(const bf16_t* __restrict__ A, int lda, const bf16_t* __restrict__ B, int ldb,
;                                           int K, char* smem, f32x4 (&acc)[MI][4]) {
;     ...
;   for (int kt = 0; kt < nk; ++kt) {
;     __syncthreads();
; #pragma unroll
;     for (int i = 0; i < MI; ++i) *(u32x4*)(smem + woff + i * 4096) = ra[i];
; #pragma unroll
;     for (int i = 0; i < 4; ++i) *(u32x4*)(smem + 32768 + woff + i * 4096) = rb[i];
;     __syncthreads();
;     if (kt + 1 < nk) {
; #pragma unroll
;       for (int i = 0; i < MI; ++i) ra[i] = *(const u32x4*)(ap + (size_t)(32 * i) * lda + (kt + 1) * 64);
; #pragma unroll
;       for (int i = 0; i < 4; ++i) rb[i] = *(const u32x4*)(bp + (size_t)(32 * i) * ldb + (kt + 1) * 64);
;     }
;     if (F8) {
;       const int c0 = (g ^ (li & 7)) << 4, c1 = ((4 + g) ^ (li & 7)) << 4;
;       i32x8 wf8[4];
; #pragma unroll
;       for (int j = 0; j < 4; ++j) {
;         const char* rp = smem + wrow + ((j & 1) * 16 + (j >> 1) * 64) * 128;
;         const u32x4 lo = *(const u32x4*)(rp + c0), hi = *(const u32x4*)(rp + c1);
;         wf8[j] = (i32x8){(int)lo.x, (int)lo.y, (int)lo.z, (int)lo.w, (int)hi.x, (int)hi.y, (int)hi.z, (int)hi.w};
;       }
; #pragma unroll
;       for (int i = 0; i < MI; ++i) {
;         const char* rp = smem + xrow + i * 2048;
;         const u32x4 lo = *(const u32x4*)(rp + c0), hi = *(const u32x4*)(rp + c1);
;         const i32x8 xf8 = {(int)lo.x, (int)lo.y, (int)lo.z, (int)lo.w, (int)hi.x, (int)hi.y, (int)hi.z, (int)hi.w};
; #pragma unroll
;         for (int j = 0; j < 4; ++j)
;           acc[i][j] = __builtin_amdgcn_mfma_scale_f32_16x16x128_f8f6f4(wf8[j], xf8, acc[i][j], 0, 0, 0, 0x77777777, 0, 0x7f7f7f7f);
;       }
;     } else {
; #pragma unroll
;     for (int kk = 0; kk < 2; ++kk) {
;       const int ch = ((kk * 4 + g) ^ (li & 7)) << 4;
;       bf16x8 xf[MI], wf[4];
; #pragma unroll
;       for (int j = 0; j < 4; ++j) wf[j] = *(const bf16x8*)(smem + wrow + ((j & 1) * 16 + (j >> 1) * 64) * 128 + ch);
; #pragma unroll
;       for (int i = 0; i < MI; ++i) xf[i] = *(const bf16x8*)(smem + xrow + i * 2048 + ch);
; #pragma unroll
;       for (int i = 0; i < MI; ++i)
; #pragma unroll
;         for (int j = 0; j < 4; ++j) {
.LBB0_236:
	v_add_u32_e32 v215, v203, v204
	s_barrier
	s_mov_b32 m0, s62
	s_nop 0
	global_load_lds_dwordx4 v252, s[56:57]
	s_add_u32 m0, s62, 0x1000
	s_nop 0
	global_load_lds_dwordx4 v253, s[56:57]
	s_add_u32 s56, s56, 0x20000
	s_addc_u32 s57, s57, 0
	s_add_u32 m0, s62, 0x2000
	s_nop 0
	global_load_lds_dwordx4 v252, s[56:57]
	s_add_u32 m0, s62, 0x3000
	s_nop 0
	global_load_lds_dwordx4 v253, s[56:57]
	s_add_u32 s56, s56, 0x20000
	s_addc_u32 s57, s57, 0
	s_add_u32 m0, s62, 0x4000
	s_nop 0
	global_load_lds_dwordx4 v252, s[56:57]
	s_add_u32 m0, s62, 0x5000
	s_nop 0
	global_load_lds_dwordx4 v253, s[56:57]
	s_add_u32 s56, s56, 0x20000
	s_addc_u32 s57, s57, 0
	s_add_u32 m0, s62, 0x6000
	s_nop 0
	global_load_lds_dwordx4 v252, s[56:57]
	s_add_u32 m0, s62, 0x7000
	s_nop 0
	global_load_lds_dwordx4 v253, s[56:57]
	s_sub_u32 s56, s56, 0x60000
	s_subb_u32 s57, s57, 0
	s_add_u32 m0, s62, 0x8000
	s_nop 0
	global_load_lds_dwordx4 v252, s[58:59]
	s_add_u32 m0, s62, 0x9000
	s_nop 0
	global_load_lds_dwordx4 v253, s[58:59]
	s_add_u32 s58, s58, 0x20000
	s_addc_u32 s59, s59, 0
	s_add_u32 m0, s62, 0xa000
	s_nop 0
	global_load_lds_dwordx4 v252, s[58:59]
	s_add_u32 m0, s62, 0xb000
	s_nop 0
	global_load_lds_dwordx4 v253, s[58:59]
	s_sub_u32 s58, s58, 0x20000
	s_subb_u32 s59, s59, 0
	v_add_u32_e32 v252, 0x80, v252
	v_add_u32_e32 v253, 0x80, v253
	s_waitcnt vmcnt(0)
	s_barrier
	v_add_u32_e32 v213, v202, v204
	ds_read_b128 v[148:151], v215 offset:32768
	ds_read_b128 v[152:155], v215 offset:34816
	ds_read_b128 v[156:159], v213
	ds_read_b128 v[160:163], v213 offset:2048
	ds_read_b128 v[164:167], v215 offset:40960
	ds_read_b128 v[168:171], v215 offset:43008
	s_waitcnt lgkmcnt(3)
	v_mfma_f32_16x16x32_bf16 v[140:143], v[148:151], v[156:159], v[140:143]
	v_add_u32_e32 v207, v203, v205
	v_add_u32_e32 v206, v202, v205
	v_mfma_f32_16x16x32_bf16 v[136:139], v[152:155], v[156:159], v[136:139]
	s_waitcnt lgkmcnt(1)
	v_mfma_f32_16x16x32_bf16 v[132:135], v[164:167], v[156:159], v[132:135]
	s_waitcnt lgkmcnt(0)
	v_mfma_f32_16x16x32_bf16 v[124:127], v[168:171], v[156:159], v[124:127]
	v_mfma_f32_16x16x32_bf16 v[108:111], v[148:151], v[160:163], v[108:111]
	v_mfma_f32_16x16x32_bf16 v[104:107], v[152:155], v[160:163], v[104:107]
	v_mfma_f32_16x16x32_bf16 v[96:99], v[164:167], v[160:163], v[96:99]
	v_mfma_f32_16x16x32_bf16 v[92:95], v[168:171], v[160:163], v[92:95]
	ds_read_b128 v[156:159], v213 offset:4096
	ds_read_b128 v[160:163], v213 offset:6144
	s_waitcnt lgkmcnt(1)
	v_mfma_f32_16x16x32_bf16 v[88:91], v[148:151], v[156:159], v[88:91]
	v_mfma_f32_16x16x32_bf16 v[84:87], v[152:155], v[156:159], v[84:87]
	v_mfma_f32_16x16x32_bf16 v[80:83], v[164:167], v[156:159], v[80:83]
	v_mfma_f32_16x16x32_bf16 v[60:63], v[168:171], v[156:159], v[60:63]
	s_waitcnt lgkmcnt(0)
	v_mfma_f32_16x16x32_bf16 v[56:59], v[148:151], v[160:163], v[56:59]
	v_mfma_f32_16x16x32_bf16 v[52:55], v[152:155], v[160:163], v[52:55]
	v_mfma_f32_16x16x32_bf16 v[48:51], v[164:167], v[160:163], v[48:51]
	v_mfma_f32_16x16x32_bf16 v[44:47], v[168:171], v[160:163], v[44:47]
	ds_read_b128 v[156:159], v213 offset:8192
	ds_read_b128 v[160:163], v213 offset:10240
	s_waitcnt lgkmcnt(1)
	v_mfma_f32_16x16x32_bf16 v[40:43], v[148:151], v[156:159], v[40:43]
	v_mfma_f32_16x16x32_bf16 v[36:39], v[152:155], v[156:159], v[36:39]
	v_mfma_f32_16x16x32_bf16 v[32:35], v[164:167], v[156:159], v[32:35]
	v_mfma_f32_16x16x32_bf16 v[28:31], v[168:171], v[156:159], v[28:31]
	s_waitcnt lgkmcnt(0)
	v_mfma_f32_16x16x32_bf16 v[24:27], v[148:151], v[160:163], v[24:27]
	v_mfma_f32_16x16x32_bf16 v[20:23], v[152:155], v[160:163], v[20:23]
	v_mfma_f32_16x16x32_bf16 v[68:71], v[164:167], v[160:163], v[68:71]
	v_mfma_f32_16x16x32_bf16 v[64:67], v[168:171], v[160:163], v[64:67]
	ds_read_b128 v[156:159], v213 offset:12288
	ds_read_b128 v[160:163], v213 offset:14336
	ds_read_b128 v[172:175], v207 offset:32768
	ds_read_b128 v[180:183], v207 offset:34816
	s_waitcnt lgkmcnt(3)
	v_mfma_f32_16x16x32_bf16 v[72:75], v[148:151], v[156:159], v[72:75]
	v_mfma_f32_16x16x32_bf16 v[76:79], v[152:155], v[156:159], v[76:79]
	v_mfma_f32_16x16x32_bf16 v[128:131], v[164:167], v[156:159], v[128:131]
	v_mfma_f32_16x16x32_bf16 v[120:123], v[168:171], v[156:159], v[120:123]
	s_waitcnt lgkmcnt(2)
	v_mfma_f32_16x16x32_bf16 v[116:119], v[148:151], v[160:163], v[116:119]
	v_mfma_f32_16x16x32_bf16 v[112:115], v[152:155], v[160:163], v[112:115]
	ds_read_b128 v[148:151], v206
	ds_read_b128 v[152:155], v206 offset:2048
	ds_read_b128 v[192:195], v207 offset:40960
	ds_read_b128 v[196:199], v207 offset:43008
	v_mfma_f32_16x16x32_bf16 v[100:103], v[164:167], v[160:163], v[100:103]
	v_mfma_f32_16x16x32_bf16 v[144:147], v[168:171], v[160:163], v[144:147]
	s_waitcnt lgkmcnt(3)
	v_mfma_f32_16x16x32_bf16 v[140:143], v[172:175], v[148:151], v[140:143]
	v_mfma_f32_16x16x32_bf16 v[136:139], v[180:183], v[148:151], v[136:139]
	s_waitcnt lgkmcnt(1)
	v_mfma_f32_16x16x32_bf16 v[132:135], v[192:195], v[148:151], v[132:135]
	s_waitcnt lgkmcnt(0)
	v_mfma_f32_16x16x32_bf16 v[124:127], v[196:199], v[148:151], v[124:127]
	v_mfma_f32_16x16x32_bf16 v[108:111], v[172:175], v[152:155], v[108:111]
	v_mfma_f32_16x16x32_bf16 v[104:107], v[180:183], v[152:155], v[104:107]
	v_mfma_f32_16x16x32_bf16 v[96:99], v[192:195], v[152:155], v[96:99]
	v_mfma_f32_16x16x32_bf16 v[92:95], v[196:199], v[152:155], v[92:95]
	ds_read_b128 v[148:151], v206 offset:4096
	ds_read_b128 v[152:155], v206 offset:6144
	s_waitcnt lgkmcnt(1)
; template <int MI, bool SWAP, bool F8 = false>
; __device__ __forceinline__ void gemm_core(const bf16_t* __restrict__ A, int lda, const bf16_t* __restrict__ B, int ldb,
;                                           int K, char* smem, f32x4 (&acc)[MI][4]) {
;     ...
;   for (int kt = 0; kt < nk; ++kt) {
;     __syncthreads();
; #pragma unroll
;     for (int i = 0; i < MI; ++i) *(u32x4*)(smem + woff + i * 4096) = ra[i];
; #pragma unroll
;     for (int i = 0; i < 4; ++i) *(u32x4*)(smem + 32768 + woff + i * 4096) = rb[i];
;     __syncthreads();
;     if (kt + 1 < nk) {
; #pragma unroll
;       for (int i = 0; i < MI; ++i) ra[i] = *(const u32x4*)(ap + (size_t)(32 * i) * lda + (kt + 1) * 64);
; #pragma unroll
;       for (int i = 0; i < 4; ++i) rb[i] = *(const u32x4*)(bp + (size_t)(32 * i) * ldb + (kt + 1) * 64);
;     }
;     if (F8) {
;       const int c0 = (g ^ (li & 7)) << 4, c1 = ((4 + g) ^ (li & 7)) << 4;
;       i32x8 wf8[4];
; #pragma unroll
;       for (int j = 0; j < 4; ++j) {
;         const char* rp = smem + wrow + ((j & 1) * 16 + (j >> 1) * 64) * 128;
;         const u32x4 lo = *(const u32x4*)(rp + c0), hi = *(const u32x4*)(rp + c1);
;         wf8[j] = (i32x8){(int)lo.x, (int)lo.y, (int)lo.z, (int)lo.w, (int)hi.x, (int)hi.y, (int)hi.z, (int)hi.w};
;       }
; #pragma unroll
;       for (int i = 0; i < MI; ++i) {
;         const char* rp = smem + xrow + i * 2048;
;         const u32x4 lo = *(const u32x4*)(rp + c0), hi = *(const u32x4*)(rp + c1);
;         const i32x8 xf8 = {(int)lo.x, (int)lo.y, (int)lo.z, (int)lo.w, (int)hi.x, (int)hi.y, (int)hi.z, (int)hi.w};
; #pragma unroll
;         for (int j = 0; j < 4; ++j)
;           acc[i][j] = __builtin_amdgcn_mfma_scale_f32_16x16x128_f8f6f4(wf8[j], xf8, acc[i][j], 0, 0, 0, 0x77777777, 0, 0x7f7f7f7f);
;       }
;     } else {
; #pragma unroll
;     for (int kk = 0; kk < 2; ++kk) {
;       const int ch = ((kk * 4 + g) ^ (li & 7)) << 4;
;       bf16x8 xf[MI], wf[4];
; #pragma unroll
;       for (int j = 0; j < 4; ++j) wf[j] = *(const bf16x8*)(smem + wrow + ((j & 1) * 16 + (j >> 1) * 64) * 128 + ch);
; #pragma unroll
;       for (int i = 0; i < MI; ++i) xf[i] = *(const bf16x8*)(smem + xrow + i * 2048 + ch);
; #pragma unroll
;       for (int i = 0; i < MI; ++i)
; #pragma unroll
;         for (int j = 0; j < 4; ++j) {
	v_mfma_f32_16x16x32_bf16 v[88:91], v[172:175], v[148:151], v[88:91]
	ds_read_b128 v[156:159], v206 offset:12288
	ds_read_b128 v[216:219], v206 offset:14336
	v_mfma_f32_16x16x32_bf16 v[84:87], v[180:183], v[148:151], v[84:87]
	v_mfma_f32_16x16x32_bf16 v[80:83], v[192:195], v[148:151], v[80:83]
	v_mfma_f32_16x16x32_bf16 v[60:63], v[196:199], v[148:151], v[60:63]
	ds_read_b128 v[148:151], v206 offset:8192
	s_waitcnt lgkmcnt(3)
	v_mfma_f32_16x16x32_bf16 v[56:59], v[172:175], v[152:155], v[56:59]
	v_mfma_f32_16x16x32_bf16 v[52:55], v[180:183], v[152:155], v[52:55]
	v_mfma_f32_16x16x32_bf16 v[48:51], v[192:195], v[152:155], v[48:51]
	v_mfma_f32_16x16x32_bf16 v[44:47], v[196:199], v[152:155], v[44:47]
	ds_read_b128 v[152:155], v206 offset:10240
	s_waitcnt lgkmcnt(1)
	v_mfma_f32_16x16x32_bf16 v[40:43], v[172:175], v[148:151], v[40:43]
	v_mfma_f32_16x16x32_bf16 v[36:39], v[180:183], v[148:151], v[36:39]
	v_mfma_f32_16x16x32_bf16 v[32:35], v[192:195], v[148:151], v[32:35]
	v_mfma_f32_16x16x32_bf16 v[28:31], v[196:199], v[148:151], v[28:31]
	s_waitcnt lgkmcnt(0)
	v_mfma_f32_16x16x32_bf16 v[24:27], v[172:175], v[152:155], v[24:27]
	v_mfma_f32_16x16x32_bf16 v[20:23], v[180:183], v[152:155], v[20:23]
	v_mfma_f32_16x16x32_bf16 v[68:71], v[192:195], v[152:155], v[68:71]
	v_mfma_f32_16x16x32_bf16 v[64:67], v[196:199], v[152:155], v[64:67]
	v_mfma_f32_16x16x32_bf16 v[72:75], v[172:175], v[156:159], v[72:75]
	v_mfma_f32_16x16x32_bf16 v[76:79], v[180:183], v[156:159], v[76:79]
	v_mfma_f32_16x16x32_bf16 v[128:131], v[192:195], v[156:159], v[128:131]
	v_mfma_f32_16x16x32_bf16 v[120:123], v[196:199], v[156:159], v[120:123]
	v_mfma_f32_16x16x32_bf16 v[116:119], v[172:175], v[216:219], v[116:119]
	v_mfma_f32_16x16x32_bf16 v[112:115], v[180:183], v[216:219], v[112:115]
	v_mfma_f32_16x16x32_bf16 v[100:103], v[192:195], v[216:219], v[100:103]
	v_mfma_f32_16x16x32_bf16 v[144:147], v[196:199], v[216:219], v[144:147]
	s_add_u32 s20, s20, 0x80
	s_addc_u32 s21, s21, 0
	s_cmpk_lg_i32 s20, 0x780
	s_cbranch_scc1 .LBB0_236
	s_barrier
	s_mov_b32 m0, s62
	s_nop 0
	global_load_lds_dwordx4 v252, s[56:57]
	s_add_u32 m0, s62, 0x1000
	s_nop 0
	global_load_lds_dwordx4 v253, s[56:57]
	s_add_u32 s56, s56, 0x20000
	s_addc_u32 s57, s57, 0
	s_add_u32 m0, s62, 0x2000
	s_nop 0
	global_load_lds_dwordx4 v252, s[56:57]
	s_add_u32 m0, s62, 0x3000
	s_nop 0
	global_load_lds_dwordx4 v253, s[56:57]
	s_add_u32 s56, s56, 0x20000
	s_addc_u32 s57, s57, 0
	s_add_u32 m0, s62, 0x4000
	s_nop 0
	global_load_lds_dwordx4 v252, s[56:57]
	s_add_u32 m0, s62, 0x5000
	s_nop 0
	global_load_lds_dwordx4 v253, s[56:57]
	s_add_u32 s56, s56, 0x20000
	s_addc_u32 s57, s57, 0
	s_add_u32 m0, s62, 0x6000
	s_nop 0
	global_load_lds_dwordx4 v252, s[56:57]
	s_add_u32 m0, s62, 0x7000
	s_nop 0
	global_load_lds_dwordx4 v253, s[56:57]
	s_sub_u32 s56, s56, 0x60000
	s_subb_u32 s57, s57, 0
	s_add_u32 m0, s62, 0x8000
	s_nop 0
	global_load_lds_dwordx4 v252, s[58:59]
	s_add_u32 m0, s62, 0x9000
	s_nop 0
	global_load_lds_dwordx4 v253, s[58:59]
	s_add_u32 s58, s58, 0x20000
	s_addc_u32 s59, s59, 0
	s_add_u32 m0, s62, 0xa000
	s_nop 0
	global_load_lds_dwordx4 v252, s[58:59]
	s_add_u32 m0, s62, 0xb000
	s_nop 0
	global_load_lds_dwordx4 v253, s[58:59]
	s_sub_u32 s58, s58, 0x20000
	s_subb_u32 s59, s59, 0
	s_waitcnt vmcnt(0)
	s_barrier
	ds_read_b128 v[148:151], v215 offset:32768
	ds_read_b128 v[152:155], v215 offset:34816
	ds_read_b128 v[156:159], v215 offset:40960
	ds_read_b128 v[160:163], v215 offset:43008
	ds_read_b128 v[164:167], v213
	ds_read_b128 v[168:171], v213 offset:2048
	ds_read_b128 v[172:175], v213 offset:4096
	ds_read_b128 v[176:179], v213 offset:6144
	ds_read_b128 v[180:183], v213 offset:8192
	ds_read_b128 v[184:187], v213 offset:10240
	ds_read_b128 v[188:191], v213 offset:12288
	ds_read_b128 v[192:195], v213 offset:14336
	s_waitcnt lgkmcnt(7)
	v_mfma_f32_16x16x32_bf16 v[132:135], v[156:159], v[164:167], v[132:135]
	s_lshl_b64 s[10:11], s[10:11], 2
	s_add_u32 s10, s16, s10
	s_addc_u32 s11, s17, s11
	v_mfma_f32_16x16x32_bf16 v[140:143], v[148:151], v[164:167], v[140:143]
	s_lshl_b32 s20, s26, 2
	s_add_u32 s10, s10, s20
	s_addc_u32 s11, s11, 0
	v_mfma_f32_16x16x32_bf16 v[136:139], v[152:155], v[164:167], v[136:139]
	s_add_i32 s25, s25, s78
	s_add_i32 s24, s24, s71
	s_add_i32 s23, s23, s76
	v_mfma_f32_16x16x32_bf16 v[124:127], v[160:163], v[164:167], v[124:127]
	s_cmpk_gt_i32 s25, 0x1ff
	s_waitcnt lgkmcnt(6)
	v_mfma_f32_16x16x32_bf16 v[108:111], v[148:151], v[168:171], v[108:111]
	v_mfma_f32_16x16x32_bf16 v[104:107], v[152:155], v[168:171], v[104:107]
	v_mfma_f32_16x16x32_bf16 v[96:99], v[156:159], v[168:171], v[96:99]
	v_mfma_f32_16x16x32_bf16 v[92:95], v[160:163], v[168:171], v[92:95]
	s_waitcnt lgkmcnt(5)
	v_mfma_f32_16x16x32_bf16 v[88:91], v[148:151], v[172:175], v[88:91]
	v_mfma_f32_16x16x32_bf16 v[84:87], v[152:155], v[172:175], v[84:87]
	v_mfma_f32_16x16x32_bf16 v[80:83], v[156:159], v[172:175], v[80:83]
	v_mfma_f32_16x16x32_bf16 v[60:63], v[160:163], v[172:175], v[60:63]
	s_waitcnt lgkmcnt(4)
	v_mfma_f32_16x16x32_bf16 v[56:59], v[148:151], v[176:179], v[56:59]
	v_mfma_f32_16x16x32_bf16 v[52:55], v[152:155], v[176:179], v[52:55]
	v_mfma_f32_16x16x32_bf16 v[48:51], v[156:159], v[176:179], v[48:51]
	v_mfma_f32_16x16x32_bf16 v[44:47], v[160:163], v[176:179], v[44:47]
	s_waitcnt lgkmcnt(3)
	v_mfma_f32_16x16x32_bf16 v[40:43], v[148:151], v[180:183], v[40:43]
	v_mfma_f32_16x16x32_bf16 v[36:39], v[152:155], v[180:183], v[36:39]
	v_mfma_f32_16x16x32_bf16 v[32:35], v[156:159], v[180:183], v[32:35]
	v_mfma_f32_16x16x32_bf16 v[28:31], v[160:163], v[180:183], v[28:31]
	s_waitcnt lgkmcnt(2)
; template <int MI, bool SWAP, bool F8 = false>
; __device__ __forceinline__ void gemm_core(const bf16_t* __restrict__ A, int lda, const bf16_t* __restrict__ B, int ldb,
;                                           int K, char* smem, f32x4 (&acc)[MI][4]) {
;     ...
;     for (int kk = 0; kk < 2; ++kk) {
;       const int ch = ((kk * 4 + g) ^ (li & 7)) << 4;
;       bf16x8 xf[MI], wf[4];
; #pragma unroll
;       for (int j = 0; j < 4; ++j) wf[j] = *(const bf16x8*)(smem + wrow + ((j & 1) * 16 + (j >> 1) * 64) * 128 + ch);
; #pragma unroll
;       for (int i = 0; i < MI; ++i) xf[i] = *(const bf16x8*)(smem + xrow + i * 2048 + ch);
; #pragma unroll
;       for (int i = 0; i < MI; ++i)
; #pragma unroll
;         for (int j = 0; j < 4; ++j) {
;           if (SWAP) acc[i][j] = __builtin_amdgcn_mfma_f32_16x16x32_bf16(xf[i], wf[j], acc[i][j], 0, 0, 0);
;           else acc[i][j] = __builtin_amdgcn_mfma_f32_16x16x32_bf16(wf[j], xf[i], acc[i][j], 0, 0, 0);
;         }
; template <bool ACCUM, int MI>
; __device__ void gemm_tile_f32(const bf16_t* A, int lda, const bf16_t* B, int ldb, int K, float* C, int ldc, char* smem) {
;     ...
; #pragma unroll
;   for (int i = 0; i < MI; ++i)
; #pragma unroll
;     for (int j = 0; j < 4; ++j) {
;       f32x4* cp = (f32x4*)(C + (size_t)MROW(i) * ldc + NCOL(j));
;       f32x4 v = acc[i][j];
;       if (ACCUM) v += *cp;
;       *cp = v;
;     }
	v_mfma_f32_16x16x32_bf16 v[24:27], v[148:151], v[184:187], v[24:27]
	v_mfma_f32_16x16x32_bf16 v[20:23], v[152:155], v[184:187], v[20:23]
	v_mfma_f32_16x16x32_bf16 v[164:167], v[156:159], v[184:187], v[68:71]
	v_mfma_f32_16x16x32_bf16 v[168:171], v[160:163], v[184:187], v[64:67]
	s_waitcnt lgkmcnt(1)
	v_mfma_f32_16x16x32_bf16 v[172:175], v[148:151], v[188:191], v[72:75]
	v_mfma_f32_16x16x32_bf16 v[176:179], v[152:155], v[188:191], v[76:79]
	v_mfma_f32_16x16x32_bf16 v[180:183], v[156:159], v[188:191], v[128:131]
	v_mfma_f32_16x16x32_bf16 v[184:187], v[160:163], v[188:191], v[120:123]
	s_waitcnt lgkmcnt(0)
	v_mfma_f32_16x16x32_bf16 v[148:151], v[148:151], v[192:195], v[116:119]
	v_mfma_f32_16x16x32_bf16 v[152:155], v[152:155], v[192:195], v[112:115]
	v_mfma_f32_16x16x32_bf16 v[156:159], v[156:159], v[192:195], v[100:103]
	v_mfma_f32_16x16x32_bf16 v[144:147], v[160:163], v[192:195], v[144:147]
	ds_read_b128 v[160:163], v207 offset:32768
	ds_read_b128 v[188:191], v207 offset:34816
	ds_read_b128 v[192:195], v207 offset:40960
	ds_read_b128 v[196:199], v207 offset:43008
	ds_read_b128 v[64:67], v206
	ds_read_b128 v[68:71], v206 offset:2048
	ds_read_b128 v[72:75], v206 offset:4096
	ds_read_b128 v[76:79], v206 offset:6144
	ds_read_b128 v[200:203], v206 offset:8192
	ds_read_b128 v[216:219], v206 offset:10240
	ds_read_b128 v[220:223], v206 offset:12288
	ds_read_b128 v[204:207], v206 offset:14336
	s_waitcnt lgkmcnt(7)
	v_mfma_f32_16x16x32_bf16 v[224:227], v[192:195], v[64:67], v[132:135]
	s_nop 2
	v_mov_b32_e32 v132, v208
	v_mfma_f32_16x16x32_bf16 v[228:231], v[196:199], v[64:67], v[124:127]
	v_lshrrev_b32_e32 v0, 1, v132
	v_and_b32_e32 v2, 0xffffff8f, v132
	v_and_b32_e32 v0, 32, v0
	v_lshrrev_b32_e32 v3, 2, v132
	v_and_or_b32 v0, v3, 12, v0
	v_ashrrev_i32_e32 v3, 31, v2
	v_lshlrev_b64 v[134:135], 12, v[2:3]
	v_lshl_add_u64 v[134:135], s[10:11], 0, v[134:135]
	v_lshlrev_b32_e32 v0, 2, v0
	s_waitcnt lgkmcnt(6)
	v_mfma_f32_16x16x32_bf16 v[128:131], v[160:163], v[68:71], v[108:111]
	v_mfma_f32_16x16x32_bf16 v[124:127], v[188:191], v[68:71], v[104:107]
	s_waitcnt lgkmcnt(5)
	v_mfma_f32_16x16x32_bf16 v[112:115], v[160:163], v[72:75], v[88:91]
	v_mfma_f32_16x16x32_bf16 v[108:111], v[188:191], v[72:75], v[84:87]
	v_mfma_f32_16x16x32_bf16 v[104:107], v[192:195], v[72:75], v[80:83]
	v_mfma_f32_16x16x32_bf16 v[100:103], v[196:199], v[72:75], v[60:63]
	s_waitcnt lgkmcnt(3)
	v_mfma_f32_16x16x32_bf16 v[72:75], v[192:195], v[200:203], v[32:35]
	s_waitcnt lgkmcnt(0)
	v_mfma_f32_16x16x32_bf16 v[32:35], v[160:163], v[204:207], v[148:151]
	s_nop 2
	v_lshl_add_u64 v[148:149], v[134:135], 0, v[0:1]
	v_mfma_f32_16x16x32_bf16 v[60:63], v[188:191], v[216:219], v[20:23]
	v_mfma_f32_16x16x32_bf16 v[20:23], v[196:199], v[204:207], v[144:147]
	s_nop 2
	global_load_dwordx4 v[144:147], v[148:149], off
	v_mfma_f32_16x16x32_bf16 v[140:143], v[160:163], v[64:67], v[140:143]
	v_mfma_f32_16x16x32_bf16 v[136:139], v[188:191], v[64:67], v[136:139]
	v_mfma_f32_16x16x32_bf16 v[120:123], v[192:195], v[68:71], v[96:99]
	s_waitcnt vmcnt(0)
	s_nop 4
	v_pk_add_f32 v[142:143], v[142:143], v[146:147]
	v_pk_add_f32 v[140:141], v[140:141], v[144:145]
	global_store_dwordx4 v[148:149], v[140:143], off
	global_load_dwordx4 v[140:143], v[148:149], off offset:64
	v_mfma_f32_16x16x32_bf16 v[116:119], v[196:199], v[68:71], v[92:95]
	s_waitcnt vmcnt(0)
	v_pk_add_f32 v[138:139], v[138:139], v[142:143]
	v_pk_add_f32 v[136:137], v[136:137], v[140:141]
	global_store_dwordx4 v[148:149], v[136:139], off offset:64
	global_load_dwordx4 v[134:137], v[148:149], off offset:256
	v_mfma_f32_16x16x32_bf16 v[96:99], v[160:163], v[76:79], v[56:59]
	s_waitcnt vmcnt(0)
	v_pk_add_f32 v[136:137], v[226:227], v[136:137]
	v_pk_add_f32 v[134:135], v[224:225], v[134:135]
	global_store_dwordx4 v[148:149], v[134:137], off offset:256
	global_load_dwordx4 v[134:137], v[148:149], off offset:320
	v_mfma_f32_16x16x32_bf16 v[92:95], v[188:191], v[76:79], v[52:55]
	s_waitcnt vmcnt(0)
	v_pk_add_f32 v[136:137], v[230:231], v[136:137]
	v_pk_add_f32 v[134:135], v[228:229], v[134:135]
	global_store_dwordx4 v[148:149], v[134:137], off offset:320
	v_mfma_f32_16x16x32_bf16 v[88:91], v[192:195], v[76:79], v[48:51]
	s_nop 0
	v_or_b32_e32 v134, 16, v2
	v_ashrrev_i32_e32 v135, 31, v134
	v_lshlrev_b64 v[134:135], 12, v[134:135]
	v_lshl_add_u64 v[134:135], s[10:11], 0, v[134:135]
	v_lshl_add_u64 v[138:139], v[134:135], 0, v[0:1]
	global_load_dwordx4 v[134:137], v[138:139], off
	v_mfma_f32_16x16x32_bf16 v[84:87], v[196:199], v[76:79], v[44:47]
	s_waitcnt vmcnt(0)
	v_pk_add_f32 v[130:131], v[130:131], v[136:137]
	v_pk_add_f32 v[128:129], v[128:129], v[134:135]
	global_store_dwordx4 v[138:139], v[128:131], off
	global_load_dwordx4 v[128:131], v[138:139], off offset:64
	v_mfma_f32_16x16x32_bf16 v[80:83], v[160:163], v[200:203], v[40:43]
	s_waitcnt vmcnt(0)
	v_pk_add_f32 v[126:127], v[126:127], v[130:131]
	v_pk_add_f32 v[124:125], v[124:125], v[128:129]
	global_store_dwordx4 v[138:139], v[124:127], off offset:64
	global_load_dwordx4 v[124:127], v[138:139], off offset:256
	v_mfma_f32_16x16x32_bf16 v[76:79], v[188:191], v[200:203], v[36:39]
	s_waitcnt vmcnt(0)
	v_pk_add_f32 v[122:123], v[122:123], v[126:127]
	v_pk_add_f32 v[120:121], v[120:121], v[124:125]
	global_store_dwordx4 v[138:139], v[120:123], off offset:256
	global_load_dwordx4 v[120:123], v[138:139], off offset:320
	v_mfma_f32_16x16x32_bf16 v[68:71], v[196:199], v[200:203], v[28:31]
	s_waitcnt vmcnt(0)
; template <bool ACCUM, int MI>
; __device__ void gemm_tile_f32(const bf16_t* A, int lda, const bf16_t* B, int ldb, int K, float* C, int ldc, char* smem) {
;     ...
; #pragma unroll
;   for (int i = 0; i < MI; ++i)
; #pragma unroll
;     for (int j = 0; j < 4; ++j) {
;       f32x4* cp = (f32x4*)(C + (size_t)MROW(i) * ldc + NCOL(j));
;       f32x4 v = acc[i][j];
;       if (ACCUM) v += *cp;
;       *cp = v;
;     }
	v_pk_add_f32 v[118:119], v[118:119], v[122:123]
	v_pk_add_f32 v[116:117], v[116:117], v[120:121]
	global_store_dwordx4 v[138:139], v[116:119], off offset:320
	v_mfma_f32_16x16x32_bf16 v[64:67], v[160:163], v[216:219], v[24:27]
	s_nop 0
	v_or_b32_e32 v116, 32, v2
	v_ashrrev_i32_e32 v117, 31, v116
	v_lshlrev_b64 v[116:117], 12, v[116:117]
	v_lshl_add_u64 v[116:117], s[10:11], 0, v[116:117]
	v_lshl_add_u64 v[120:121], v[116:117], 0, v[0:1]
	global_load_dwordx4 v[116:119], v[120:121], off
	v_mfma_f32_16x16x32_bf16 v[56:59], v[192:195], v[216:219], v[164:167]
	s_waitcnt vmcnt(0)
	v_pk_add_f32 v[114:115], v[114:115], v[118:119]
	v_pk_add_f32 v[112:113], v[112:113], v[116:117]
	global_store_dwordx4 v[120:121], v[112:115], off
	global_load_dwordx4 v[112:115], v[120:121], off offset:64
	v_mfma_f32_16x16x32_bf16 v[52:55], v[196:199], v[216:219], v[168:171]
	s_waitcnt vmcnt(0)
	v_pk_add_f32 v[110:111], v[110:111], v[114:115]
	v_pk_add_f32 v[108:109], v[108:109], v[112:113]
	global_store_dwordx4 v[120:121], v[108:111], off offset:64
	global_load_dwordx4 v[108:111], v[120:121], off offset:256
	v_mfma_f32_16x16x32_bf16 v[48:51], v[160:163], v[220:223], v[172:175]
	s_waitcnt vmcnt(0)
	v_pk_add_f32 v[106:107], v[106:107], v[110:111]
	v_pk_add_f32 v[104:105], v[104:105], v[108:109]
	global_store_dwordx4 v[120:121], v[104:107], off offset:256
	global_load_dwordx4 v[104:107], v[120:121], off offset:320
	v_mfma_f32_16x16x32_bf16 v[44:47], v[188:191], v[220:223], v[176:179]
	s_waitcnt vmcnt(0)
	v_pk_add_f32 v[102:103], v[102:103], v[106:107]
	v_pk_add_f32 v[100:101], v[100:101], v[104:105]
	global_store_dwordx4 v[120:121], v[100:103], off offset:320
	v_mfma_f32_16x16x32_bf16 v[40:43], v[192:195], v[220:223], v[180:183]
	s_nop 0
	v_or_b32_e32 v100, 48, v2
	v_ashrrev_i32_e32 v101, 31, v100
	v_lshlrev_b64 v[100:101], 12, v[100:101]
	v_lshl_add_u64 v[100:101], s[10:11], 0, v[100:101]
	v_lshl_add_u64 v[104:105], v[100:101], 0, v[0:1]
	global_load_dwordx4 v[100:103], v[104:105], off
	v_mfma_f32_16x16x32_bf16 v[36:39], v[196:199], v[220:223], v[184:187]
	s_waitcnt vmcnt(0)
	v_pk_add_f32 v[98:99], v[98:99], v[102:103]
	v_pk_add_f32 v[96:97], v[96:97], v[100:101]
	global_store_dwordx4 v[104:105], v[96:99], off
	global_load_dwordx4 v[96:99], v[104:105], off offset:64
	v_mfma_f32_16x16x32_bf16 v[28:31], v[188:191], v[204:207], v[152:155]
	s_waitcnt vmcnt(0)
	v_pk_add_f32 v[94:95], v[94:95], v[98:99]
	v_pk_add_f32 v[92:93], v[92:93], v[96:97]
	global_store_dwordx4 v[104:105], v[92:95], off offset:64
	global_load_dwordx4 v[92:95], v[104:105], off offset:256
	v_mfma_f32_16x16x32_bf16 v[24:27], v[192:195], v[204:207], v[156:159]
	s_waitcnt vmcnt(0)
	v_pk_add_f32 v[90:91], v[90:91], v[94:95]
	v_pk_add_f32 v[88:89], v[88:89], v[92:93]
	global_store_dwordx4 v[104:105], v[88:91], off offset:256
	global_load_dwordx4 v[88:91], v[104:105], off offset:320
	s_waitcnt vmcnt(0)
	v_pk_add_f32 v[86:87], v[86:87], v[90:91]
	v_pk_add_f32 v[84:85], v[84:85], v[88:89]
	global_store_dwordx4 v[104:105], v[84:87], off offset:320
	s_nop 1
	v_or_b32_e32 v84, 64, v2
	v_ashrrev_i32_e32 v85, 31, v84
	v_lshlrev_b64 v[84:85], 12, v[84:85]
	v_lshl_add_u64 v[84:85], s[10:11], 0, v[84:85]
	v_lshl_add_u64 v[88:89], v[84:85], 0, v[0:1]
	global_load_dwordx4 v[84:87], v[88:89], off
	s_waitcnt vmcnt(0)
	v_pk_add_f32 v[82:83], v[82:83], v[86:87]
	v_pk_add_f32 v[80:81], v[80:81], v[84:85]
	global_store_dwordx4 v[88:89], v[80:83], off
	global_load_dwordx4 v[80:83], v[88:89], off offset:64
	s_waitcnt vmcnt(0)
; template <bool ACCUM, int MI>
; __device__ void gemm_tile_f32(const bf16_t* A, int lda, const bf16_t* B, int ldb, int K, float* C, int ldc, char* smem) {
;     ...
; #pragma unroll
;   for (int i = 0; i < MI; ++i)
; #pragma unroll
;     for (int j = 0; j < 4; ++j) {
;       f32x4* cp = (f32x4*)(C + (size_t)MROW(i) * ldc + NCOL(j));
;       f32x4 v = acc[i][j];
;       if (ACCUM) v += *cp;
;       *cp = v;
;     }
; __global__ void __launch_bounds__(256, 2) fwd_kernel(P p) {
;     ...
;       for (int it = blockIdx.x; it < 64 * 8; it += G) {
;         const int tm = (it & 7) * 8 + ((it >> 3) >> 3), tn = (it >> 3) & 7;
;         gemm_tile_f32<true, 8>((const bf16_t*)(ws + OFF_AO) + (size_t)tm * 256 * 1024, 1024,
;                             (const bf16_t*)(ws + OFF_WOOUT) + ((size_t)li2 * 1024 + tn * 128) * 1024, 1024, 1024,
;                             H + (size_t)tm * 256 * 1024 + tn * 128, 1024, smem);
;       }
	v_pk_add_f32 v[78:79], v[78:79], v[82:83]
	v_pk_add_f32 v[76:77], v[76:77], v[80:81]
	global_store_dwordx4 v[88:89], v[76:79], off offset:64
	global_load_dwordx4 v[76:79], v[88:89], off offset:256
	s_waitcnt vmcnt(0)
	v_pk_add_f32 v[74:75], v[74:75], v[78:79]
	v_pk_add_f32 v[72:73], v[72:73], v[76:77]
	global_store_dwordx4 v[88:89], v[72:75], off offset:256
	global_load_dwordx4 v[72:75], v[88:89], off offset:320
	s_waitcnt vmcnt(0)
	v_pk_add_f32 v[70:71], v[70:71], v[74:75]
	v_pk_add_f32 v[68:69], v[68:69], v[72:73]
	global_store_dwordx4 v[88:89], v[68:71], off offset:320
	s_nop 1
	v_or_b32_e32 v68, 0x50, v2
	v_ashrrev_i32_e32 v69, 31, v68
	v_lshlrev_b64 v[68:69], 12, v[68:69]
	v_lshl_add_u64 v[68:69], s[10:11], 0, v[68:69]
	v_lshl_add_u64 v[72:73], v[68:69], 0, v[0:1]
	global_load_dwordx4 v[68:71], v[72:73], off
	v_or_b32_e32 v2, 0x60, v2
	v_ashrrev_i32_e32 v3, 31, v2
	v_lshlrev_b64 v[2:3], 12, v[2:3]
	v_lshl_add_u64 v[2:3], s[10:11], 0, v[2:3]
	v_lshl_add_u64 v[2:3], v[2:3], 0, v[0:1]
	s_waitcnt vmcnt(0)
	v_pk_add_f32 v[66:67], v[66:67], v[70:71]
	v_pk_add_f32 v[64:65], v[64:65], v[68:69]
	global_store_dwordx4 v[72:73], v[64:67], off
	global_load_dwordx4 v[64:67], v[72:73], off offset:64
	s_waitcnt vmcnt(0)
	v_pk_add_f32 v[62:63], v[62:63], v[66:67]
	v_pk_add_f32 v[60:61], v[60:61], v[64:65]
	global_store_dwordx4 v[72:73], v[60:63], off offset:64
	global_load_dwordx4 v[60:63], v[72:73], off offset:256
	s_waitcnt vmcnt(0)
	v_pk_add_f32 v[58:59], v[58:59], v[62:63]
	v_pk_add_f32 v[56:57], v[56:57], v[60:61]
	global_store_dwordx4 v[72:73], v[56:59], off offset:256
	global_load_dwordx4 v[56:59], v[72:73], off offset:320
	s_waitcnt vmcnt(0)
	v_pk_add_f32 v[54:55], v[54:55], v[58:59]
	v_pk_add_f32 v[52:53], v[52:53], v[56:57]
	global_store_dwordx4 v[72:73], v[52:55], off offset:320
	global_load_dwordx4 v[52:55], v[2:3], off
	s_waitcnt vmcnt(0)
	v_pk_add_f32 v[50:51], v[50:51], v[54:55]
	v_pk_add_f32 v[48:49], v[48:49], v[52:53]
	global_store_dwordx4 v[2:3], v[48:51], off
	global_load_dwordx4 v[48:51], v[2:3], off offset:64
	s_waitcnt vmcnt(0)
	v_pk_add_f32 v[46:47], v[46:47], v[50:51]
	v_pk_add_f32 v[44:45], v[44:45], v[48:49]
	global_store_dwordx4 v[2:3], v[44:47], off offset:64
	global_load_dwordx4 v[44:47], v[2:3], off offset:256
	s_waitcnt vmcnt(0)
	v_pk_add_f32 v[42:43], v[42:43], v[46:47]
	v_pk_add_f32 v[40:41], v[40:41], v[44:45]
	global_store_dwordx4 v[2:3], v[40:43], off offset:256
	global_load_dwordx4 v[40:43], v[2:3], off offset:320
	s_waitcnt vmcnt(0)
	v_pk_add_f32 v[38:39], v[38:39], v[42:43]
	v_pk_add_f32 v[36:37], v[36:37], v[40:41]
	global_store_dwordx4 v[2:3], v[36:39], off offset:320
	v_or_b32_e32 v2, 0x70, v132
	v_ashrrev_i32_e32 v3, 31, v2
	v_lshlrev_b64 v[2:3], 12, v[2:3]
	v_lshl_add_u64 v[2:3], s[10:11], 0, v[2:3]
	v_lshl_add_u64 v[2:3], v[2:3], 0, v[0:1]
	global_load_dwordx4 v[36:39], v[2:3], off
	s_waitcnt vmcnt(0)
	v_pk_add_f32 v[34:35], v[34:35], v[38:39]
	v_pk_add_f32 v[32:33], v[32:33], v[36:37]
	global_store_dwordx4 v[2:3], v[32:35], off
	global_load_dwordx4 v[32:35], v[2:3], off offset:64
	s_waitcnt vmcnt(0)
	v_pk_add_f32 v[30:31], v[30:31], v[34:35]
	v_pk_add_f32 v[28:29], v[28:29], v[32:33]
	global_store_dwordx4 v[2:3], v[28:31], off offset:64
	global_load_dwordx4 v[28:31], v[2:3], off offset:256
	s_waitcnt vmcnt(0)
	v_pk_add_f32 v[26:27], v[26:27], v[30:31]
	v_pk_add_f32 v[24:25], v[24:25], v[28:29]
	global_store_dwordx4 v[2:3], v[24:27], off offset:256
	global_load_dwordx4 v[24:27], v[2:3], off offset:320
	s_waitcnt vmcnt(0)
	v_pk_add_f32 v[22:23], v[22:23], v[26:27]
	v_pk_add_f32 v[20:21], v[20:21], v[24:25]
	global_store_dwordx4 v[2:3], v[20:23], off offset:320
	s_cbranch_scc0 .LBB0_235

; __device__ __forceinline__ int otid() { int t = threadIdx.x; asm volatile("" : "+v"(t)); return t; }
; template <int MI, bool SWAP, bool F8 = false>
; __device__ __forceinline__ void gemm_core(const bf16_t* __restrict__ A, int lda, const bf16_t* __restrict__ B, int ldb,
;                                           int K, char* smem, f32x4 (&acc)[MI][4]) {
;   const int tid = otid(), lane = tid & 63, w = tid >> 6, wm = w >> 1, wn = w & 1;
;   const int lr = tid >> 3, lc = tid & 7;
;   const int li = lane & 15, g = lane >> 4;
;   u32x4 ra[MI], rb[4];
;   const bf16_t* ap = A + (size_t)lr * lda + lc * 8;
;   const bf16_t* bp = B + (size_t)lr * ldb + lc * 8;
; #pragma unroll
;   for (int i = 0; i < MI; ++i)
; #pragma unroll
;     for (int j = 0; j < 4; ++j) acc[i][j] = (f32x4){0.f, 0.f, 0.f, 0.f};
;   const int nk = K >> 6;
; #pragma unroll
;   for (int i = 0; i < MI; ++i) ra[i] = *(const u32x4*)(ap + (size_t)(32 * i) * lda);
; #pragma unroll
;   for (int i = 0; i < 4; ++i) rb[i] = *(const u32x4*)(bp + (size_t)(32 * i) * ldb);
;   const int woff = lr * 128 + ((lc ^ (lr & 7)) << 4);
;   const int xrow = (wm * 16 * MI + li) * 128;
;   const int wrow = 32768 + (wn * 32 + li) * 128;
; __device__ void even_in_tile(const P& p, int li_even, int tm, int tn, char* smem) {
;     ...
;   const bf16_t* A = (const bf16_t*)(ws + OFF_XN) + (size_t)tm * 256 * 1024;
;   const bf16_t* B = (const bf16_t*)(ws + OFF_WEIN) + ((size_t)li_even * 3584 + (size_t)tn * 128) * 1024;
;   const int seg = tn >> 2, hd = tn & 3;
;   const int t0 = tm * 256, b = t0 >> 12, s0 = t0 & 4095, bh = b * 4 + hd;
.LBB0_299:
	s_ashr_i32 s25, s28, 2
	s_and_b32 s49, s24, 3
	s_lshl_b32 s54, s28, 8
	s_and_b32 s25, s25, -4
	s_and_b32 s44, s19, 56
	s_and_b32 s41, s54, 0xf00
	s_andn2_b64 vcc, exec, s[6:7]
	s_or_b32 s6, s25, s49
	s_cbranch_vccnz .LBB0_311
	s_waitcnt vmcnt(17)
	v_mov_b32_e32 v30, v208
	s_add_i32 s26, s43, s44
	v_ashrrev_i32_e32 v2, 3, v30
	v_ashrrev_i32_e32 v3, 31, v2
	v_lshlrev_b64 v[20:21], 11, v[2:3]
	v_lshlrev_b32_e32 v0, 4, v30
	v_lshl_add_u64 v[24:25], s[20:21], 0, v[20:21]
	v_and_b32_e32 v0, 0x70, v0
	v_lshl_add_u64 v[24:25], v[24:25], 0, v[0:1]
	v_add_co_u32_e32 v26, vcc, 0x10000, v24
	v_lshl_add_u64 v[22:23], s[22:23], 0, v[20:21]
	s_nop 0
	v_addc_co_u32_e32 v27, vcc, 0, v25, vcc
	v_lshrrev_b32_e32 v254, 3, v208
	v_and_b32_e32 v254, 7, v254
	v_xor_b32_e32 v252, v254, v208
	v_and_b32_e32 v252, 7, v252
	v_lshlrev_b32_e32 v252, 4, v252
	v_lshl_or_b32 v252, v254, 11, v252
	v_add_u32_e32 v253, 0x10000, v252
	v_lshrrev_b32_e32 v254, 6, v208
	s_nop 0
	v_readfirstlane_b32 s62, v254
	s_lshl_b32 s62, s62, 10
	v_readfirstlane_b32 s56, v24
	v_readfirstlane_b32 s57, v25
	v_add_co_u32_e32 v26, vcc, 0x20000, v24
	v_lshl_add_u64 v[22:23], v[22:23], 0, v[0:1]
	s_nop 0
	v_addc_co_u32_e32 v27, vcc, 0, v25, vcc
	v_add_co_u32_e32 v28, vcc, 0x30000, v24
	s_ashr_i32 s27, s26, 31
	s_nop 0
	v_addc_co_u32_e32 v29, vcc, 0, v25, vcc
	v_add_co_u32_e32 v26, vcc, 0x40000, v24
	v_and_b32_e32 v3, 15, v30
	s_nop 0
	v_addc_co_u32_e32 v27, vcc, 0, v25, vcc
	v_add_co_u32_e32 v28, vcc, 0x50000, v24
	s_lshl_b64 s[26:27], s[26:27], 19
	s_nop 0
	v_addc_co_u32_e32 v29, vcc, 0, v25, vcc
	v_add_co_u32_e32 v26, vcc, 0x60000, v24
	v_lshrrev_b32_e32 v31, 4, v30
	s_nop 0
	v_addc_co_u32_e32 v27, vcc, 0, v25, vcc
	v_add_co_u32_e32 v24, vcc, 0x70000, v24
	s_add_u32 s26, s8, s26
	s_nop 0
	v_addc_co_u32_e32 v25, vcc, 0, v25, vcc
	v_add_co_u32_e32 v24, vcc, s93, v22
	s_addc_u32 s27, s9, s27
	s_nop 0
	v_addc_co_u32_e32 v25, vcc, 0, v23, vcc
	s_nop 0
	v_readfirstlane_b32 s58, v22
	v_readfirstlane_b32 s59, v23
	v_add_co_u32_e32 v24, vcc, s46, v22
	v_bfe_u32 v0, v30, 4, 2
	s_nop 0
	v_addc_co_u32_e32 v25, vcc, 0, v23, vcc
	v_add_co_u32_e32 v22, vcc, s47, v22
	v_mov_b32_e32 v160, 0
	s_nop 0
	v_addc_co_u32_e32 v23, vcc, 0, v23, vcc
	v_lshlrev_b32_e32 v22, 7, v2
	v_xor_b32_e32 v2, v2, v30
	v_lshlrev_b32_e32 v2, 4, v2
	v_and_or_b32 v202, v2, s33, v22
	v_lshlrev_b32_e32 v2, 7, v30
	v_and_b32_e32 v203, 0xffffc780, v2
	v_lshrrev_b32_e32 v2, 1, v30
	v_and_or_b32 v2, v2, 32, v3
	v_and_b32_e32 v22, 7, v30
	v_lshlrev_b32_e32 v204, 7, v2
	v_bitop3_b32 v2, v31, v22, 3 bitop3:0x6c
	v_lshlrev_b32_e32 v205, 4, v2
	v_lshl_add_u64 v[2:3], s[26:27], 0, v[20:21]
	s_add_u32 s26, s8, s10
	v_bitop3_b32 v0, v0, v22, 4 bitop3:0x36
	s_addc_u32 s27, s9, s11
	v_lshlrev_b32_e32 v206, 4, v0
	v_lshlrev_b32_e32 v0, 4, v22
	v_lshl_add_u64 v[20:21], s[26:27], 0, v[20:21]
	v_lshl_add_u64 v[2:3], v[2:3], 0, v[0:1]
	v_lshl_add_u64 v[20:21], v[20:21], 0, v[0:1]
	v_lshl_add_u64 v[2:3], s[68:69], 0, v[2:3]
	v_lshl_add_u64 v[200:201], s[0:1], 0, v[20:21]
	s_mov_b64 s[26:27], 0
	v_mov_b32_e32 v161, v160
	v_mov_b32_e32 v162, v160
	v_mov_b32_e32 v163, v160
	v_mov_b32_e32 v20, v160
	v_mov_b32_e32 v21, v160
	v_mov_b32_e32 v22, v160
	v_mov_b32_e32 v23, v160
	s_waitcnt vmcnt(28)
	v_mov_b32_e32 v32, v160
	v_mov_b32_e32 v33, v160
	v_mov_b32_e32 v34, v160
	v_mov_b32_e32 v35, v160
	v_mov_b32_e32 v52, v160
	v_mov_b32_e32 v53, v160
	v_mov_b32_e32 v54, v160
	v_mov_b32_e32 v55, v160
	v_mov_b32_e32 v72, v160
	v_mov_b32_e32 v73, v160
	v_mov_b32_e32 v74, v160
	v_mov_b32_e32 v75, v160
	v_mov_b32_e32 v76, v160
	v_mov_b32_e32 v77, v160
	v_mov_b32_e32 v78, v160
	v_mov_b32_e32 v79, v160
	v_mov_b32_e32 v24, v160
	v_mov_b32_e32 v25, v160
	v_mov_b32_e32 v26, v160
	v_mov_b32_e32 v27, v160
	v_mov_b32_e32 v28, v160
	v_mov_b32_e32 v29, v160
	v_mov_b32_e32 v30, v160
	v_mov_b32_e32 v31, v160
	s_waitcnt vmcnt(27)
	v_mov_b32_e32 v36, v160
	v_mov_b32_e32 v37, v160
	v_mov_b32_e32 v38, v160
	v_mov_b32_e32 v39, v160
	s_waitcnt vmcnt(26)
	v_mov_b32_e32 v40, v160
	v_mov_b32_e32 v41, v160
	v_mov_b32_e32 v42, v160
	v_mov_b32_e32 v43, v160
	s_waitcnt vmcnt(25)
	v_mov_b32_e32 v44, v160
	v_mov_b32_e32 v45, v160
	v_mov_b32_e32 v46, v160
	v_mov_b32_e32 v47, v160
	s_waitcnt vmcnt(24)
	v_mov_b32_e32 v48, v160
	v_mov_b32_e32 v49, v160
	v_mov_b32_e32 v50, v160
	v_mov_b32_e32 v51, v160
	s_waitcnt vmcnt(23)
	v_mov_b32_e32 v56, v160
	v_mov_b32_e32 v57, v160
	v_mov_b32_e32 v58, v160
	v_mov_b32_e32 v59, v160
	v_mov_b32_e32 v60, v160
	v_mov_b32_e32 v61, v160
	v_mov_b32_e32 v62, v160
	v_mov_b32_e32 v63, v160
	s_waitcnt vmcnt(22)
	v_mov_b32_e32 v64, v160
	v_mov_b32_e32 v65, v160
	v_mov_b32_e32 v66, v160
	v_mov_b32_e32 v67, v160
	v_mov_b32_e32 v68, v160
	v_mov_b32_e32 v69, v160
	v_mov_b32_e32 v70, v160
	v_mov_b32_e32 v71, v160
	v_mov_b32_e32 v80, v160
	v_mov_b32_e32 v81, v160
	v_mov_b32_e32 v82, v160
	v_mov_b32_e32 v83, v160
	s_waitcnt vmcnt(21)
	v_mov_b32_e32 v84, v160
	v_mov_b32_e32 v85, v160
	v_mov_b32_e32 v86, v160
	v_mov_b32_e32 v87, v160
	s_waitcnt vmcnt(20)
	v_mov_b32_e32 v88, v160
	v_mov_b32_e32 v89, v160
	v_mov_b32_e32 v90, v160
	v_mov_b32_e32 v91, v160
	v_mov_b32_e32 v92, v160
	v_mov_b32_e32 v93, v160
	v_mov_b32_e32 v94, v160
	v_mov_b32_e32 v95, v160
	v_mov_b32_e32 v96, v160
	v_mov_b32_e32 v97, v160
	v_mov_b32_e32 v98, v160
	v_mov_b32_e32 v99, v160
	v_mov_b32_e32 v100, v160
	v_mov_b32_e32 v101, v160
	v_mov_b32_e32 v102, v160
	v_mov_b32_e32 v103, v160
	v_mov_b32_e32 v104, v160
	v_mov_b32_e32 v105, v160
	v_mov_b32_e32 v106, v160
	v_mov_b32_e32 v107, v160
	v_mov_b32_e32 v108, v160
	v_mov_b32_e32 v109, v160
	v_mov_b32_e32 v110, v160
	v_mov_b32_e32 v111, v160
	v_mov_b32_e32 v112, v160
	v_mov_b32_e32 v113, v160
	v_mov_b32_e32 v114, v160
	v_mov_b32_e32 v115, v160
	v_mov_b32_e32 v116, v160
	v_mov_b32_e32 v117, v160
	v_mov_b32_e32 v118, v160
	v_mov_b32_e32 v119, v160
	v_mov_b32_e32 v120, v160
	v_mov_b32_e32 v121, v160
	v_mov_b32_e32 v122, v160
	v_mov_b32_e32 v123, v160
	v_mov_b32_e32 v124, v160
	v_mov_b32_e32 v125, v160
	v_mov_b32_e32 v126, v160
	v_mov_b32_e32 v127, v160
	v_mov_b32_e32 v128, v160
	v_mov_b32_e32 v129, v160
	v_mov_b32_e32 v130, v160
	v_mov_b32_e32 v131, v160
	v_mov_b32_e32 v132, v160
	v_mov_b32_e32 v133, v160
	v_mov_b32_e32 v134, v160
	v_mov_b32_e32 v135, v160
	v_mov_b32_e32 v140, v160
	v_mov_b32_e32 v141, v160
	v_mov_b32_e32 v142, v160
	v_mov_b32_e32 v143, v160
	v_mov_b32_e32 v148, v160
	v_mov_b32_e32 v149, v160
	v_mov_b32_e32 v150, v160
	v_mov_b32_e32 v151, v160
	s_mov_b32 s7, 0x284000
	s_mov_b32 s25, 0x294000
; template <int MI, bool SWAP, bool F8 = false>
; __device__ __forceinline__ void gemm_core(const bf16_t* __restrict__ A, int lda, const bf16_t* __restrict__ B, int ldb,
;                                           int K, char* smem, f32x4 (&acc)[MI][4]) {
;     ...
;   for (int kt = 0; kt < nk; ++kt) {
;     __syncthreads();
; #pragma unroll
;     for (int i = 0; i < MI; ++i) *(u32x4*)(smem + woff + i * 4096) = ra[i];
; #pragma unroll
;     for (int i = 0; i < 4; ++i) *(u32x4*)(smem + 32768 + woff + i * 4096) = rb[i];
;     __syncthreads();
;     if (kt + 1 < nk) {
; #pragma unroll
;       for (int i = 0; i < MI; ++i) ra[i] = *(const u32x4*)(ap + (size_t)(32 * i) * lda + (kt + 1) * 64);
; #pragma unroll
;       for (int i = 0; i < 4; ++i) rb[i] = *(const u32x4*)(bp + (size_t)(32 * i) * ldb + (kt + 1) * 64);
;     }
;     if (F8) {
;       const int c0 = (g ^ (li & 7)) << 4, c1 = ((4 + g) ^ (li & 7)) << 4;
;       i32x8 wf8[4];
; #pragma unroll
;       for (int j = 0; j < 4; ++j) {
;         const char* rp = smem + wrow + ((j & 1) * 16 + (j >> 1) * 64) * 128;
;         const u32x4 lo = *(const u32x4*)(rp + c0), hi = *(const u32x4*)(rp + c1);
;         wf8[j] = (i32x8){(int)lo.x, (int)lo.y, (int)lo.z, (int)lo.w, (int)hi.x, (int)hi.y, (int)hi.z, (int)hi.w};
;       }
; #pragma unroll
;       for (int i = 0; i < MI; ++i) {
;         const char* rp = smem + xrow + i * 2048;
;         const u32x4 lo = *(const u32x4*)(rp + c0), hi = *(const u32x4*)(rp + c1);
;         const i32x8 xf8 = {(int)lo.x, (int)lo.y, (int)lo.z, (int)lo.w, (int)hi.x, (int)hi.y, (int)hi.z, (int)hi.w};
; #pragma unroll
;         for (int j = 0; j < 4; ++j)
;           acc[i][j] = __builtin_amdgcn_mfma_scale_f32_16x16x128_f8f6f4(wf8[j], xf8, acc[i][j], 0, 0, 0, 0x77777777, 0, 0x7f7f7f7f);
;       }
;     } else {
; #pragma unroll
;     for (int kk = 0; kk < 2; ++kk) {
;       const int ch = ((kk * 4 + g) ^ (li & 7)) << 4;
;       bf16x8 xf[MI], wf[4];
; #pragma unroll
;       for (int j = 0; j < 4; ++j) wf[j] = *(const bf16x8*)(smem + wrow + ((j & 1) * 16 + (j >> 1) * 64) * 128 + ch);
; #pragma unroll
;       for (int i = 0; i < MI; ++i) xf[i] = *(const bf16x8*)(smem + xrow + i * 2048 + ch);
; #pragma unroll
;       for (int i = 0; i < MI; ++i)
; #pragma unroll
;         for (int j = 0; j < 4; ++j) {
.LBB0_301:
	v_add_u32_e32 v213, v204, v205
	s_barrier
	s_mov_b32 m0, s62
	s_nop 0
	global_load_lds_dwordx4 v252, s[56:57]
	s_add_u32 m0, s62, 0x1000
	s_nop 0
	global_load_lds_dwordx4 v253, s[56:57]
	s_add_u32 s56, s56, 0x20000
	s_addc_u32 s57, s57, 0
	s_add_u32 m0, s62, 0x2000
	s_nop 0
	global_load_lds_dwordx4 v252, s[56:57]
	s_add_u32 m0, s62, 0x3000
	s_nop 0
	global_load_lds_dwordx4 v253, s[56:57]
	s_add_u32 s56, s56, 0x20000
	s_addc_u32 s57, s57, 0
	s_add_u32 m0, s62, 0x4000
	s_nop 0
	global_load_lds_dwordx4 v252, s[56:57]
	s_add_u32 m0, s62, 0x5000
	s_nop 0
	global_load_lds_dwordx4 v253, s[56:57]
	s_add_u32 s56, s56, 0x20000
	s_addc_u32 s57, s57, 0
	s_add_u32 m0, s62, 0x6000
	s_nop 0
	global_load_lds_dwordx4 v252, s[56:57]
	s_add_u32 m0, s62, 0x7000
	s_nop 0
	global_load_lds_dwordx4 v253, s[56:57]
	s_sub_u32 s56, s56, 0x60000
	s_subb_u32 s57, s57, 0
	s_add_u32 m0, s62, 0x8000
	s_nop 0
	global_load_lds_dwordx4 v252, s[58:59]
	s_add_u32 m0, s62, 0x9000
	s_nop 0
	global_load_lds_dwordx4 v253, s[58:59]
	s_add_u32 s58, s58, 0x20000
	s_addc_u32 s59, s59, 0
	s_add_u32 m0, s62, 0xa000
	s_nop 0
	global_load_lds_dwordx4 v252, s[58:59]
	s_add_u32 m0, s62, 0xb000
	s_nop 0
	global_load_lds_dwordx4 v253, s[58:59]
	s_sub_u32 s58, s58, 0x20000
	s_subb_u32 s59, s59, 0
	v_add_u32_e32 v252, 0x80, v252
	v_add_u32_e32 v253, 0x80, v253
	s_waitcnt vmcnt(0)
	s_barrier
	v_add_u32_e32 v0, v203, v205
	ds_read_b128 v[136:139], v213 offset:32768
	ds_read_b128 v[144:147], v213 offset:34816
	ds_read_b128 v[152:155], v0
	ds_read_b128 v[156:159], v0 offset:2048
	ds_read_b128 v[164:167], v213 offset:40960
	ds_read_b128 v[168:171], v213 offset:43008
	s_waitcnt lgkmcnt(3)
	v_mfma_f32_16x16x32_bf16 v[148:151], v[136:139], v[152:155], v[148:151]
	v_add_u32_e32 v215, v204, v206
	v_add_u32_e32 v207, v203, v206
	v_mfma_f32_16x16x32_bf16 v[140:143], v[144:147], v[152:155], v[140:143]
	s_waitcnt lgkmcnt(1)
	v_mfma_f32_16x16x32_bf16 v[132:135], v[164:167], v[152:155], v[132:135]
	s_waitcnt lgkmcnt(0)
	v_mfma_f32_16x16x32_bf16 v[128:131], v[168:171], v[152:155], v[128:131]
	v_mfma_f32_16x16x32_bf16 v[124:127], v[136:139], v[156:159], v[124:127]
	v_mfma_f32_16x16x32_bf16 v[120:123], v[144:147], v[156:159], v[120:123]
	v_mfma_f32_16x16x32_bf16 v[116:119], v[164:167], v[156:159], v[116:119]
	v_mfma_f32_16x16x32_bf16 v[112:115], v[168:171], v[156:159], v[112:115]
	ds_read_b128 v[152:155], v0 offset:4096
	ds_read_b128 v[156:159], v0 offset:6144
	s_waitcnt lgkmcnt(1)
	v_mfma_f32_16x16x32_bf16 v[108:111], v[136:139], v[152:155], v[108:111]
	v_mfma_f32_16x16x32_bf16 v[104:107], v[144:147], v[152:155], v[104:107]
	v_mfma_f32_16x16x32_bf16 v[100:103], v[164:167], v[152:155], v[100:103]
	v_mfma_f32_16x16x32_bf16 v[96:99], v[168:171], v[152:155], v[96:99]
	s_waitcnt lgkmcnt(0)
	v_mfma_f32_16x16x32_bf16 v[92:95], v[136:139], v[156:159], v[92:95]
	v_mfma_f32_16x16x32_bf16 v[88:91], v[144:147], v[156:159], v[88:91]
	v_mfma_f32_16x16x32_bf16 v[84:87], v[164:167], v[156:159], v[84:87]
	v_mfma_f32_16x16x32_bf16 v[80:83], v[168:171], v[156:159], v[80:83]
	ds_read_b128 v[152:155], v0 offset:8192
	ds_read_b128 v[156:159], v0 offset:10240
	s_waitcnt lgkmcnt(1)
	v_mfma_f32_16x16x32_bf16 v[68:71], v[136:139], v[152:155], v[68:71]
	v_mfma_f32_16x16x32_bf16 v[64:67], v[144:147], v[152:155], v[64:67]
	v_mfma_f32_16x16x32_bf16 v[60:63], v[164:167], v[152:155], v[60:63]
	v_mfma_f32_16x16x32_bf16 v[56:59], v[168:171], v[152:155], v[56:59]
	s_waitcnt lgkmcnt(0)
	v_mfma_f32_16x16x32_bf16 v[48:51], v[136:139], v[156:159], v[48:51]
	v_mfma_f32_16x16x32_bf16 v[44:47], v[144:147], v[156:159], v[44:47]
	v_mfma_f32_16x16x32_bf16 v[40:43], v[164:167], v[156:159], v[40:43]
	v_mfma_f32_16x16x32_bf16 v[36:39], v[168:171], v[156:159], v[36:39]
	ds_read_b128 v[152:155], v0 offset:12288
	ds_read_b128 v[156:159], v0 offset:14336
	ds_read_b128 v[172:175], v215 offset:32768
	ds_read_b128 v[180:183], v215 offset:34816
	s_waitcnt lgkmcnt(3)
	v_mfma_f32_16x16x32_bf16 v[28:31], v[136:139], v[152:155], v[28:31]
	v_mfma_f32_16x16x32_bf16 v[24:27], v[144:147], v[152:155], v[24:27]
	v_mfma_f32_16x16x32_bf16 v[76:79], v[164:167], v[152:155], v[76:79]
	v_mfma_f32_16x16x32_bf16 v[72:75], v[168:171], v[152:155], v[72:75]
	s_waitcnt lgkmcnt(2)
	v_mfma_f32_16x16x32_bf16 v[52:55], v[136:139], v[156:159], v[52:55]
	v_mfma_f32_16x16x32_bf16 v[32:35], v[144:147], v[156:159], v[32:35]
	ds_read_b128 v[136:139], v207
	ds_read_b128 v[144:147], v207 offset:2048
	ds_read_b128 v[192:195], v215 offset:40960
	ds_read_b128 v[196:199], v215 offset:43008
	v_mfma_f32_16x16x32_bf16 v[20:23], v[164:167], v[156:159], v[20:23]
	v_mfma_f32_16x16x32_bf16 v[160:163], v[168:171], v[156:159], v[160:163]
	s_waitcnt lgkmcnt(3)
	v_mfma_f32_16x16x32_bf16 v[148:151], v[172:175], v[136:139], v[148:151]
	v_mfma_f32_16x16x32_bf16 v[140:143], v[180:183], v[136:139], v[140:143]
	s_waitcnt lgkmcnt(1)
	v_mfma_f32_16x16x32_bf16 v[132:135], v[192:195], v[136:139], v[132:135]
	s_waitcnt lgkmcnt(0)
	v_mfma_f32_16x16x32_bf16 v[128:131], v[196:199], v[136:139], v[128:131]
	v_mfma_f32_16x16x32_bf16 v[124:127], v[172:175], v[144:147], v[124:127]
	v_mfma_f32_16x16x32_bf16 v[120:123], v[180:183], v[144:147], v[120:123]
	v_mfma_f32_16x16x32_bf16 v[116:119], v[192:195], v[144:147], v[116:119]
	v_mfma_f32_16x16x32_bf16 v[112:115], v[196:199], v[144:147], v[112:115]
	ds_read_b128 v[136:139], v207 offset:4096
	ds_read_b128 v[144:147], v207 offset:6144
	s_waitcnt lgkmcnt(1)
; template <int MI, bool SWAP, bool F8 = false>
; __device__ __forceinline__ void gemm_core(const bf16_t* __restrict__ A, int lda, const bf16_t* __restrict__ B, int ldb,
;                                           int K, char* smem, f32x4 (&acc)[MI][4]) {
;     ...
;   for (int kt = 0; kt < nk; ++kt) {
;     __syncthreads();
; #pragma unroll
;     for (int i = 0; i < MI; ++i) *(u32x4*)(smem + woff + i * 4096) = ra[i];
; #pragma unroll
;     for (int i = 0; i < 4; ++i) *(u32x4*)(smem + 32768 + woff + i * 4096) = rb[i];
;     __syncthreads();
;     if (kt + 1 < nk) {
; #pragma unroll
;       for (int i = 0; i < MI; ++i) ra[i] = *(const u32x4*)(ap + (size_t)(32 * i) * lda + (kt + 1) * 64);
; #pragma unroll
;       for (int i = 0; i < 4; ++i) rb[i] = *(const u32x4*)(bp + (size_t)(32 * i) * ldb + (kt + 1) * 64);
;     }
;     if (F8) {
;       const int c0 = (g ^ (li & 7)) << 4, c1 = ((4 + g) ^ (li & 7)) << 4;
;       i32x8 wf8[4];
; #pragma unroll
;       for (int j = 0; j < 4; ++j) {
;         const char* rp = smem + wrow + ((j & 1) * 16 + (j >> 1) * 64) * 128;
;         const u32x4 lo = *(const u32x4*)(rp + c0), hi = *(const u32x4*)(rp + c1);
;         wf8[j] = (i32x8){(int)lo.x, (int)lo.y, (int)lo.z, (int)lo.w, (int)hi.x, (int)hi.y, (int)hi.z, (int)hi.w};
;       }
; #pragma unroll
;       for (int i = 0; i < MI; ++i) {
;         const char* rp = smem + xrow + i * 2048;
;         const u32x4 lo = *(const u32x4*)(rp + c0), hi = *(const u32x4*)(rp + c1);
;         const i32x8 xf8 = {(int)lo.x, (int)lo.y, (int)lo.z, (int)lo.w, (int)hi.x, (int)hi.y, (int)hi.z, (int)hi.w};
; #pragma unroll
;         for (int j = 0; j < 4; ++j)
;           acc[i][j] = __builtin_amdgcn_mfma_scale_f32_16x16x128_f8f6f4(wf8[j], xf8, acc[i][j], 0, 0, 0, 0x77777777, 0, 0x7f7f7f7f);
;       }
;     } else {
; #pragma unroll
;     for (int kk = 0; kk < 2; ++kk) {
;       const int ch = ((kk * 4 + g) ^ (li & 7)) << 4;
;       bf16x8 xf[MI], wf[4];
; #pragma unroll
;       for (int j = 0; j < 4; ++j) wf[j] = *(const bf16x8*)(smem + wrow + ((j & 1) * 16 + (j >> 1) * 64) * 128 + ch);
; #pragma unroll
;       for (int i = 0; i < MI; ++i) xf[i] = *(const bf16x8*)(smem + xrow + i * 2048 + ch);
; #pragma unroll
;       for (int i = 0; i < MI; ++i)
; #pragma unroll
;         for (int j = 0; j < 4; ++j) {
	v_mfma_f32_16x16x32_bf16 v[108:111], v[172:175], v[136:139], v[108:111]
	ds_read_b128 v[152:155], v207 offset:12288
	ds_read_b128 v[216:219], v207 offset:14336
	v_mfma_f32_16x16x32_bf16 v[104:107], v[180:183], v[136:139], v[104:107]
	v_mfma_f32_16x16x32_bf16 v[100:103], v[192:195], v[136:139], v[100:103]
	v_mfma_f32_16x16x32_bf16 v[96:99], v[196:199], v[136:139], v[96:99]
	ds_read_b128 v[136:139], v207 offset:8192
	s_waitcnt lgkmcnt(3)
	v_mfma_f32_16x16x32_bf16 v[92:95], v[172:175], v[144:147], v[92:95]
	v_mfma_f32_16x16x32_bf16 v[88:91], v[180:183], v[144:147], v[88:91]
	v_mfma_f32_16x16x32_bf16 v[84:87], v[192:195], v[144:147], v[84:87]
	v_mfma_f32_16x16x32_bf16 v[80:83], v[196:199], v[144:147], v[80:83]
	ds_read_b128 v[144:147], v207 offset:10240
	s_waitcnt lgkmcnt(1)
	v_mfma_f32_16x16x32_bf16 v[68:71], v[172:175], v[136:139], v[68:71]
	v_mfma_f32_16x16x32_bf16 v[64:67], v[180:183], v[136:139], v[64:67]
	v_mfma_f32_16x16x32_bf16 v[60:63], v[192:195], v[136:139], v[60:63]
	v_mfma_f32_16x16x32_bf16 v[56:59], v[196:199], v[136:139], v[56:59]
	s_waitcnt lgkmcnt(0)
	v_mfma_f32_16x16x32_bf16 v[48:51], v[172:175], v[144:147], v[48:51]
	v_mfma_f32_16x16x32_bf16 v[44:47], v[180:183], v[144:147], v[44:47]
	v_mfma_f32_16x16x32_bf16 v[40:43], v[192:195], v[144:147], v[40:43]
	v_mfma_f32_16x16x32_bf16 v[36:39], v[196:199], v[144:147], v[36:39]
	v_mfma_f32_16x16x32_bf16 v[28:31], v[172:175], v[152:155], v[28:31]
	v_mfma_f32_16x16x32_bf16 v[24:27], v[180:183], v[152:155], v[24:27]
	v_mfma_f32_16x16x32_bf16 v[76:79], v[192:195], v[152:155], v[76:79]
	v_mfma_f32_16x16x32_bf16 v[72:75], v[196:199], v[152:155], v[72:75]
	v_mfma_f32_16x16x32_bf16 v[52:55], v[172:175], v[216:219], v[52:55]
	v_mfma_f32_16x16x32_bf16 v[32:35], v[180:183], v[216:219], v[32:35]
	v_mfma_f32_16x16x32_bf16 v[20:23], v[192:195], v[216:219], v[20:23]
	v_mfma_f32_16x16x32_bf16 v[160:163], v[196:199], v[216:219], v[160:163]
	s_add_u32 s26, s26, 0x80
	s_addc_u32 s27, s27, 0
	s_cmpk_lg_i32 s26, 0x780
	s_cbranch_scc1 .LBB0_301
	s_barrier
	s_mov_b32 m0, s62
	s_nop 0
	global_load_lds_dwordx4 v252, s[56:57]
	s_add_u32 m0, s62, 0x1000
	s_nop 0
	global_load_lds_dwordx4 v253, s[56:57]
	s_add_u32 s56, s56, 0x20000
	s_addc_u32 s57, s57, 0
	s_add_u32 m0, s62, 0x2000
	s_nop 0
	global_load_lds_dwordx4 v252, s[56:57]
	s_add_u32 m0, s62, 0x3000
	s_nop 0
	global_load_lds_dwordx4 v253, s[56:57]
	s_add_u32 s56, s56, 0x20000
	s_addc_u32 s57, s57, 0
	s_add_u32 m0, s62, 0x4000
	s_nop 0
	global_load_lds_dwordx4 v252, s[56:57]
	s_add_u32 m0, s62, 0x5000
	s_nop 0
	global_load_lds_dwordx4 v253, s[56:57]
	s_add_u32 s56, s56, 0x20000
	s_addc_u32 s57, s57, 0
	s_add_u32 m0, s62, 0x6000
	s_nop 0
	global_load_lds_dwordx4 v252, s[56:57]
	s_add_u32 m0, s62, 0x7000
	s_nop 0
	global_load_lds_dwordx4 v253, s[56:57]
	s_sub_u32 s56, s56, 0x60000
	s_subb_u32 s57, s57, 0
	s_add_u32 m0, s62, 0x8000
	s_nop 0
	global_load_lds_dwordx4 v252, s[58:59]
	s_add_u32 m0, s62, 0x9000
	s_nop 0
	global_load_lds_dwordx4 v253, s[58:59]
	s_add_u32 s58, s58, 0x20000
	s_addc_u32 s59, s59, 0
	s_add_u32 m0, s62, 0xa000
	s_nop 0
	global_load_lds_dwordx4 v252, s[58:59]
	s_add_u32 m0, s62, 0xb000
	s_nop 0
	global_load_lds_dwordx4 v253, s[58:59]
	s_sub_u32 s58, s58, 0x20000
	s_subb_u32 s59, s59, 0
	s_waitcnt vmcnt(0)
	s_barrier
	ds_read_b128 v[136:139], v213 offset:32768
	ds_read_b128 v[144:147], v213 offset:34816
	ds_read_b128 v[152:155], v0
	ds_read_b128 v[156:159], v0 offset:2048
	ds_read_b128 v[164:167], v213 offset:40960
	ds_read_b128 v[168:171], v213 offset:43008
	s_waitcnt lgkmcnt(3)
	v_mfma_f32_16x16x32_bf16 v[148:151], v[136:139], v[152:155], v[148:151]
	s_cmp_eq_u32 s42, 6
	s_cselect_b64 s[26:27], -1, 0
	s_cmp_lg_u32 s42, 6
	v_mfma_f32_16x16x32_bf16 v[140:143], v[144:147], v[152:155], v[140:143]
	s_cselect_b64 s[30:31], -1, 0
	s_and_b64 vcc, exec, s[26:27]
	s_waitcnt lgkmcnt(1)
	v_mfma_f32_16x16x32_bf16 v[132:135], v[164:167], v[152:155], v[132:135]
	s_waitcnt lgkmcnt(0)
	v_mfma_f32_16x16x32_bf16 v[128:131], v[168:171], v[152:155], v[128:131]
	v_mfma_f32_16x16x32_bf16 v[172:175], v[136:139], v[156:159], v[124:127]
	s_nop 2
	ds_read_b128 v[124:127], v0 offset:4096
	ds_read_b128 v[152:155], v0 offset:6144
	s_waitcnt lgkmcnt(0)
	v_mfma_f32_16x16x32_bf16 v[176:179], v[164:167], v[152:155], v[84:87]
	v_mfma_f32_16x16x32_bf16 v[180:183], v[168:171], v[152:155], v[80:83]
	s_nop 2
	ds_read_b128 v[80:83], v0 offset:8192
	ds_read_b128 v[84:87], v0 offset:10240
	s_waitcnt lgkmcnt(1)
	v_mfma_f32_16x16x32_bf16 v[196:199], v[168:171], v[80:83], v[56:59]
	s_waitcnt lgkmcnt(0)
	v_mfma_f32_16x16x32_bf16 v[200:203], v[136:139], v[84:87], v[48:51]
	s_nop 2
	ds_read_b128 v[48:51], v0 offset:12288
	ds_read_b128 v[56:59], v0 offset:14336
	v_mfma_f32_16x16x32_bf16 v[116:119], v[164:167], v[156:159], v[116:119]
	v_mfma_f32_16x16x32_bf16 v[112:115], v[168:171], v[156:159], v[112:115]
	v_mfma_f32_16x16x32_bf16 v[100:103], v[164:167], v[124:127], v[100:103]
	v_mfma_f32_16x16x32_bf16 v[96:99], v[168:171], v[124:127], v[96:99]
	v_mfma_f32_16x16x32_bf16 v[192:195], v[164:167], v[80:83], v[60:63]
	v_mfma_f32_16x16x32_bf16 v[40:43], v[164:167], v[84:87], v[40:43]
	v_mfma_f32_16x16x32_bf16 v[36:39], v[168:171], v[84:87], v[36:39]
	s_waitcnt lgkmcnt(1)
	v_mfma_f32_16x16x32_bf16 v[28:31], v[136:139], v[48:51], v[28:31]
	v_mfma_f32_16x16x32_bf16 v[24:27], v[144:147], v[48:51], v[24:27]
	v_mfma_f32_16x16x32_bf16 v[76:79], v[164:167], v[48:51], v[76:79]
	v_mfma_f32_16x16x32_bf16 v[216:219], v[168:171], v[48:51], v[72:75]
	s_waitcnt lgkmcnt(0)
; template <int MI, bool SWAP, bool F8 = false>
; __device__ __forceinline__ void gemm_core(const bf16_t* __restrict__ A, int lda, const bf16_t* __restrict__ B, int ldb,
;                                           int K, char* smem, f32x4 (&acc)[MI][4]) {
;     ...
;     for (int kk = 0; kk < 2; ++kk) {
;       const int ch = ((kk * 4 + g) ^ (li & 7)) << 4;
;       bf16x8 xf[MI], wf[4];
; #pragma unroll
;       for (int j = 0; j < 4; ++j) wf[j] = *(const bf16x8*)(smem + wrow + ((j & 1) * 16 + (j >> 1) * 64) * 128 + ch);
; #pragma unroll
;       for (int i = 0; i < MI; ++i) xf[i] = *(const bf16x8*)(smem + xrow + i * 2048 + ch);
; #pragma unroll
;       for (int i = 0; i < MI; ++i)
; #pragma unroll
;         for (int j = 0; j < 4; ++j) {
;           if (SWAP) acc[i][j] = __builtin_amdgcn_mfma_f32_16x16x32_bf16(xf[i], wf[j], acc[i][j], 0, 0, 0);
;           else acc[i][j] = __builtin_amdgcn_mfma_f32_16x16x32_bf16(wf[j], xf[i], acc[i][j], 0, 0, 0);
;         }
; __device__ void even_in_tile(const P& p, int li_even, int tm, int tn, char* smem) {
;     ...
;   if (seg != 6) {
;     const float* ctab = (const float*)(ws + OFF_COS);
;     const float* stab = (const float*)(ws + OFF_SIN);
; #pragma unroll
;     for (int i = 0; i < MI; ++i) {
;       const int s = s0 + MROW(i);
; #pragma unroll
;       for (int jj = 0; jj < 2; ++jj) {
;         const int d = wn * 32 + jj * 16 + g * 4;
;         const f32x4 c = *(const f32x4*)(ctab + s * 64 + d);
;         const f32x4 sn = *(const f32x4*)(stab + s * 64 + d);
; #pragma unroll
;         for (int r = 0; r < 4; ++r) {
;           const float a = acc[i][jj][r], bb = acc[i][jj + 2][r];
;           acc[i][jj][r] = a * c[r] - bb * sn[r];
;           acc[i][jj + 2][r] = bb * c[r] + a * sn[r];
;         }
;       }
;     }
;   }
	v_mfma_f32_16x16x32_bf16 v[224:227], v[144:147], v[56:59], v[32:35]
	v_mfma_f32_16x16x32_bf16 v[20:23], v[164:167], v[56:59], v[20:23]
	ds_read_b128 v[164:167], v215 offset:32768
	v_mfma_f32_16x16x32_bf16 v[160:163], v[168:171], v[56:59], v[160:163]
	ds_read_b128 v[168:171], v215 offset:34816
	ds_read_b128 v[32:35], v207
	ds_read_b128 v[48:51], v207 offset:2048
	ds_read_b128 v[228:231], v215 offset:40960
	ds_read_b128 v[232:235], v215 offset:43008
	v_mfma_f32_16x16x32_bf16 v[120:123], v[144:147], v[156:159], v[120:123]
	v_mov_b32_e32 v215, v208
	v_mfma_f32_16x16x32_bf16 v[108:111], v[136:139], v[124:127], v[108:111]
	v_mfma_f32_16x16x32_bf16 v[104:107], v[144:147], v[124:127], v[104:107]
	v_mfma_f32_16x16x32_bf16 v[92:95], v[136:139], v[152:155], v[92:95]
	v_mfma_f32_16x16x32_bf16 v[156:159], v[144:147], v[152:155], v[88:91]
	v_mfma_f32_16x16x32_bf16 v[184:187], v[136:139], v[80:83], v[68:71]
	v_mfma_f32_16x16x32_bf16 v[188:191], v[144:147], v[80:83], v[64:67]
	v_mfma_f32_16x16x32_bf16 v[44:47], v[144:147], v[84:87], v[44:47]
	v_mfma_f32_16x16x32_bf16 v[220:223], v[136:139], v[56:59], v[52:55]
	s_waitcnt lgkmcnt(3)
	v_mfma_f32_16x16x32_bf16 v[124:127], v[164:167], v[32:35], v[148:151]
	v_mfma_f32_16x16x32_bf16 v[150:153], v[168:171], v[32:35], v[140:143]
	s_waitcnt lgkmcnt(1)
	v_mfma_f32_16x16x32_bf16 v[88:91], v[228:231], v[32:35], v[132:135]
	s_waitcnt lgkmcnt(0)
	v_mfma_f32_16x16x32_bf16 v[84:87], v[232:235], v[32:35], v[128:131]
	v_mfma_f32_16x16x32_bf16 v[134:137], v[164:167], v[48:51], v[172:175]
	v_mfma_f32_16x16x32_bf16 v[138:141], v[168:171], v[48:51], v[120:123]
	v_mfma_f32_16x16x32_bf16 v[80:83], v[228:231], v[48:51], v[116:119]
	v_mfma_f32_16x16x32_bf16 v[72:75], v[232:235], v[48:51], v[112:115]
	ds_read_b128 v[32:35], v207 offset:4096
	ds_read_b128 v[48:51], v207 offset:6144
	s_waitcnt lgkmcnt(1)
	v_mfma_f32_16x16x32_bf16 v[142:145], v[164:167], v[32:35], v[108:111]
	v_mfma_f32_16x16x32_bf16 v[146:149], v[168:171], v[32:35], v[104:107]
	v_mfma_f32_16x16x32_bf16 v[68:71], v[228:231], v[32:35], v[100:103]
	v_mfma_f32_16x16x32_bf16 v[64:67], v[232:235], v[32:35], v[96:99]
	s_waitcnt lgkmcnt(0)
	v_mfma_f32_16x16x32_bf16 v[128:131], v[164:167], v[48:51], v[92:95]
	ds_read_b128 v[32:35], v207 offset:8192
	s_nop 1
	ds_read_b128 v[92:95], v207 offset:10240
	v_mfma_f32_16x16x32_bf16 v[120:123], v[168:171], v[48:51], v[156:159]
	v_mfma_f32_16x16x32_bf16 v[60:63], v[228:231], v[48:51], v[176:179]
	v_mfma_f32_16x16x32_bf16 v[56:59], v[232:235], v[48:51], v[180:183]
	s_waitcnt lgkmcnt(1)
	v_mfma_f32_16x16x32_bf16 v[112:115], v[164:167], v[32:35], v[184:187]
	v_mfma_f32_16x16x32_bf16 v[108:111], v[168:171], v[32:35], v[188:191]
	v_mfma_f32_16x16x32_bf16 v[52:55], v[228:231], v[32:35], v[192:195]
	v_mfma_f32_16x16x32_bf16 v[48:51], v[232:235], v[32:35], v[196:199]
	ds_read_b128 v[32:35], v207 offset:12288
	ds_read_b128 v[116:119], v207 offset:14336
	s_waitcnt lgkmcnt(2)
	v_mfma_f32_16x16x32_bf16 v[104:107], v[164:167], v[92:95], v[200:203]
	v_and_b32_e32 v213, 15, v215
	v_mfma_f32_16x16x32_bf16 v[100:103], v[168:171], v[92:95], v[44:47]
	v_mfma_f32_16x16x32_bf16 v[44:47], v[228:231], v[92:95], v[40:43]
	v_mfma_f32_16x16x32_bf16 v[40:43], v[232:235], v[92:95], v[36:39]
	s_waitcnt lgkmcnt(1)
	v_mfma_f32_16x16x32_bf16 v[96:99], v[164:167], v[32:35], v[28:31]
	v_mfma_f32_16x16x32_bf16 v[92:95], v[168:171], v[32:35], v[24:27]
	v_mfma_f32_16x16x32_bf16 v[36:39], v[228:231], v[32:35], v[76:79]
	v_mfma_f32_16x16x32_bf16 v[32:35], v[232:235], v[32:35], v[216:219]
	s_waitcnt lgkmcnt(0)
	v_mfma_f32_16x16x32_bf16 v[76:79], v[164:167], v[116:119], v[220:223]
	s_nop 0
	v_bfe_u32 v218, v215, 6, 1
	v_bfe_u32 v219, v215, 4, 2
	v_mfma_f32_16x16x32_bf16 v[28:31], v[168:171], v[116:119], v[224:227]
	v_mfma_f32_16x16x32_bf16 v[24:27], v[228:231], v[116:119], v[20:23]
	v_mfma_f32_16x16x32_bf16 v[20:23], v[232:235], v[116:119], v[160:163]
	s_cbranch_vccnz .LBB0_315
	v_and_b32_e32 v0, 0x3ffff80, v215
	v_add_u32_e32 v0, s41, v0
	s_add_u32 s34, s45, 0x4000
	v_or_b32_e32 v0, v0, v213
	s_addc_u32 s35, s48, 0
	v_lshlrev_b32_e32 v2, 6, v0
	s_add_u32 s36, s45, 0x104000
	v_ashrrev_i32_e32 v3, 31, v2
	s_addc_u32 s37, s48, 0
	v_lshlrev_b64 v[116:117], 2, v[2:3]
	v_lshlrev_b32_e32 v0, 4, v219
	v_lshl_add_u64 v[118:119], s[34:35], 0, v[116:117]
	v_lshl_add_u64 v[116:117], s[36:37], 0, v[116:117]
	v_lshl_or_b32 v0, v218, 7, v0
	v_lshl_add_u64 v[132:133], v[118:119], 0, v[0:1]
	v_lshl_add_u64 v[162:163], v[116:117], 0, v[0:1]
	global_load_dwordx4 v[154:157], v[132:133], off
	global_load_dwordx4 v[158:161], v[162:163], off
	s_waitcnt vmcnt(0)
	v_pk_mul_f32 v[116:117], v[88:89], v[158:159]
	v_pk_mul_f32 v[118:119], v[124:125], v[158:159]
	v_pk_fma_f32 v[116:117], v[124:125], v[154:155], v[116:117] neg_lo:[0,0,1] neg_hi:[0,0,1]
	v_pk_fma_f32 v[88:89], v[88:89], v[154:155], v[118:119]
	v_mul_f32_e32 v118, v126, v156
	v_mul_f32_e32 v124, v90, v160
	v_mul_f32_e32 v154, v90, v156
	v_mul_f32_e32 v156, v126, v160
	v_mov_b32_e32 v90, v127
	v_mov_b32_e32 v160, v157
	v_mov_b32_e32 v126, v91
	v_pk_mul_f32 v[158:159], v[90:91], v[160:161]
	v_pk_mul_f32 v[90:91], v[126:127], v[160:161]
	v_mov_b32_e32 v119, v158
	v_mov_b32_e32 v155, v90
	v_mov_b32_e32 v157, v91
	v_mov_b32_e32 v125, v159
	v_pk_add_f32 v[90:91], v[154:155], v[156:157]
	global_load_dwordx4 v[154:157], v[132:133], off offset:64
	global_load_dwordx4 v[158:161], v[162:163], off offset:64
	v_pk_add_f32 v[118:119], v[118:119], v[124:125] neg_lo:[0,1] neg_hi:[0,1]
	s_waitcnt vmcnt(0)
; __device__ void even_in_tile(const P& p, int li_even, int tm, int tn, char* smem) {
;     ...
; #pragma unroll
;     for (int i = 0; i < MI; ++i) {
;       const int s = s0 + MROW(i);
; #pragma unroll
;       for (int jj = 0; jj < 2; ++jj) {
;         const int d = wn * 32 + jj * 16 + g * 4;
;         const f32x4 c = *(const f32x4*)(ctab + s * 64 + d);
;         const f32x4 sn = *(const f32x4*)(stab + s * 64 + d);
; #pragma unroll
;         for (int r = 0; r < 4; ++r) {
;           const float a = acc[i][jj][r], bb = acc[i][jj + 2][r];
;           acc[i][jj][r] = a * c[r] - bb * sn[r];
;           acc[i][jj + 2][r] = bb * c[r] + a * sn[r];
;         }
;       }
;     }
	v_pk_mul_f32 v[124:125], v[84:85], v[158:159]
	v_pk_mul_f32 v[126:127], v[150:151], v[158:159]
	v_pk_fma_f32 v[124:125], v[150:151], v[154:155], v[124:125] neg_lo:[0,0,1] neg_hi:[0,0,1]
	v_pk_fma_f32 v[84:85], v[84:85], v[154:155], v[126:127]
	v_mul_f32_e32 v132, v86, v160
	v_mul_f32_e32 v150, v86, v156
	v_mul_f32_e32 v154, v152, v160
	v_mov_b32_e32 v86, v153
	v_mov_b32_e32 v160, v157
	v_mul_f32_e32 v126, v152, v156
	v_pk_mul_f32 v[156:157], v[86:87], v[160:161]
	v_mov_b32_e32 v152, v87
	v_mov_b32_e32 v127, v156
	v_mov_b32_e32 v133, v157
	v_pk_add_f32 v[126:127], v[126:127], v[132:133] neg_lo:[0,1] neg_hi:[0,1]
	v_or_b32_e32 v132, 0x400, v2
	v_pk_mul_f32 v[86:87], v[152:153], v[160:161]
	v_ashrrev_i32_e32 v133, 31, v132
	v_mov_b32_e32 v151, v86
	v_mov_b32_e32 v155, v87
	v_lshlrev_b64 v[132:133], 2, v[132:133]
	v_pk_add_f32 v[86:87], v[150:151], v[154:155]
	v_lshl_add_u64 v[150:151], s[34:35], 0, v[132:133]
	v_lshl_add_u64 v[132:133], s[36:37], 0, v[132:133]
	v_lshl_add_u64 v[158:159], v[150:151], 0, v[0:1]
	v_lshl_add_u64 v[160:161], v[132:133], 0, v[0:1]
	global_load_dwordx4 v[150:153], v[158:159], off
	global_load_dwordx4 v[154:157], v[160:161], off
	s_waitcnt vmcnt(0)
	v_pk_mul_f32 v[132:133], v[80:81], v[154:155]
	s_nop 0
	v_pk_fma_f32 v[132:133], v[134:135], v[150:151], v[132:133] neg_lo:[0,0,1] neg_hi:[0,0,1]
	v_pk_mul_f32 v[134:135], v[134:135], v[154:155]
	v_mul_f32_e32 v154, v136, v156
	v_pk_fma_f32 v[80:81], v[80:81], v[150:151], v[134:135]
	v_mul_f32_e32 v134, v136, v152
	v_mul_f32_e32 v150, v82, v156
	v_mul_f32_e32 v152, v82, v152
	v_mov_b32_e32 v82, v137
	v_mov_b32_e32 v156, v153
	v_mov_b32_e32 v136, v83
	v_pk_mul_f32 v[162:163], v[82:83], v[156:157]
	v_pk_mul_f32 v[82:83], v[136:137], v[156:157]
	v_mov_b32_e32 v135, v162
	v_mov_b32_e32 v151, v163
	v_mov_b32_e32 v153, v82
	v_mov_b32_e32 v155, v83
	v_pk_add_f32 v[134:135], v[134:135], v[150:151] neg_lo:[0,1] neg_hi:[0,1]
	v_pk_add_f32 v[82:83], v[152:153], v[154:155]
	global_load_dwordx4 v[150:153], v[158:159], off offset:64
	global_load_dwordx4 v[154:157], v[160:161], off offset:64
	s_waitcnt vmcnt(0)
	v_pk_mul_f32 v[136:137], v[72:73], v[154:155]
	s_nop 0
	v_pk_fma_f32 v[136:137], v[138:139], v[150:151], v[136:137] neg_lo:[0,0,1] neg_hi:[0,0,1]
	v_pk_mul_f32 v[138:139], v[138:139], v[154:155]
	v_mul_f32_e32 v154, v140, v156
	v_pk_fma_f32 v[72:73], v[72:73], v[150:151], v[138:139]
	v_mul_f32_e32 v138, v140, v152
	v_mul_f32_e32 v150, v74, v156
	v_mul_f32_e32 v152, v74, v152
	v_mov_b32_e32 v74, v141
	v_mov_b32_e32 v156, v153
	v_mov_b32_e32 v140, v75
	v_pk_mul_f32 v[158:159], v[74:75], v[156:157]
	v_pk_mul_f32 v[74:75], v[140:141], v[156:157]
	v_or_b32_e32 v140, 0x800, v2
	v_ashrrev_i32_e32 v141, 31, v140
	v_mov_b32_e32 v139, v158
	v_mov_b32_e32 v151, v159
	v_lshlrev_b64 v[140:141], 2, v[140:141]
	v_pk_add_f32 v[138:139], v[138:139], v[150:151] neg_lo:[0,1] neg_hi:[0,1]
	v_lshl_add_u64 v[150:151], s[34:35], 0, v[140:141]
	v_lshl_add_u64 v[140:141], s[36:37], 0, v[140:141]
	v_mov_b32_e32 v153, v74
	v_mov_b32_e32 v155, v75
	v_lshl_add_u64 v[158:159], v[150:151], 0, v[0:1]
	v_lshl_add_u64 v[160:161], v[140:141], 0, v[0:1]
	v_pk_add_f32 v[74:75], v[152:153], v[154:155]
	global_load_dwordx4 v[150:153], v[158:159], off
	global_load_dwordx4 v[154:157], v[160:161], off
	s_waitcnt vmcnt(0)
	v_pk_mul_f32 v[140:141], v[68:69], v[154:155]
	s_nop 0
	v_pk_fma_f32 v[140:141], v[142:143], v[150:151], v[140:141] neg_lo:[0,0,1] neg_hi:[0,0,1]
	v_pk_mul_f32 v[142:143], v[142:143], v[154:155]
	v_mul_f32_e32 v154, v144, v156
	v_pk_fma_f32 v[68:69], v[68:69], v[150:151], v[142:143]
	v_mul_f32_e32 v142, v144, v152
	v_mul_f32_e32 v150, v70, v156
	v_mul_f32_e32 v152, v70, v152
	v_mov_b32_e32 v70, v145
	v_mov_b32_e32 v156, v153
	v_mov_b32_e32 v144, v71
	v_pk_mul_f32 v[162:163], v[70:71], v[156:157]
	v_pk_mul_f32 v[70:71], v[144:145], v[156:157]
	v_mov_b32_e32 v143, v162
	v_mov_b32_e32 v151, v163
	v_mov_b32_e32 v153, v70
	v_mov_b32_e32 v155, v71
	v_pk_add_f32 v[142:143], v[142:143], v[150:151] neg_lo:[0,1] neg_hi:[0,1]
	v_pk_add_f32 v[70:71], v[152:153], v[154:155]
	global_load_dwordx4 v[150:153], v[158:159], off offset:64
	global_load_dwordx4 v[154:157], v[160:161], off offset:64
	s_waitcnt vmcnt(0)
	v_pk_mul_f32 v[144:145], v[64:65], v[154:155]
	s_nop 0
	v_pk_fma_f32 v[144:145], v[146:147], v[150:151], v[144:145] neg_lo:[0,0,1] neg_hi:[0,0,1]
	v_pk_mul_f32 v[146:147], v[146:147], v[154:155]
	v_mul_f32_e32 v154, v148, v156
	v_pk_fma_f32 v[64:65], v[64:65], v[150:151], v[146:147]
	v_mul_f32_e32 v146, v148, v152
	v_mul_f32_e32 v150, v66, v156
	v_mul_f32_e32 v152, v66, v152
	v_mov_b32_e32 v66, v149
	v_mov_b32_e32 v156, v153
	v_mov_b32_e32 v148, v67
	v_pk_mul_f32 v[158:159], v[66:67], v[156:157]
	v_pk_mul_f32 v[66:67], v[148:149], v[156:157]
	v_or_b32_e32 v148, 0xc00, v2
	v_ashrrev_i32_e32 v149, 31, v148
	v_mov_b32_e32 v147, v158
	v_mov_b32_e32 v151, v159
	v_lshlrev_b64 v[148:149], 2, v[148:149]
	v_pk_add_f32 v[146:147], v[146:147], v[150:151] neg_lo:[0,1] neg_hi:[0,1]
	v_lshl_add_u64 v[150:151], s[34:35], 0, v[148:149]
	v_lshl_add_u64 v[148:149], s[36:37], 0, v[148:149]
	v_mov_b32_e32 v153, v66
	v_mov_b32_e32 v155, v67
	v_lshl_add_u64 v[158:159], v[150:151], 0, v[0:1]
	v_lshl_add_u64 v[160:161], v[148:149], 0, v[0:1]
	v_pk_add_f32 v[66:67], v[152:153], v[154:155]
	global_load_dwordx4 v[150:153], v[158:159], off
	global_load_dwordx4 v[154:157], v[160:161], off
	s_waitcnt vmcnt(0)
; __device__ void even_in_tile(const P& p, int li_even, int tm, int tn, char* smem) {
;     ...
; #pragma unroll
;     for (int i = 0; i < MI; ++i) {
;       const int s = s0 + MROW(i);
; #pragma unroll
;       for (int jj = 0; jj < 2; ++jj) {
;         const int d = wn * 32 + jj * 16 + g * 4;
;         const f32x4 c = *(const f32x4*)(ctab + s * 64 + d);
;         const f32x4 sn = *(const f32x4*)(stab + s * 64 + d);
; #pragma unroll
;         for (int r = 0; r < 4; ++r) {
;           const float a = acc[i][jj][r], bb = acc[i][jj + 2][r];
;           acc[i][jj][r] = a * c[r] - bb * sn[r];
;           acc[i][jj + 2][r] = bb * c[r] + a * sn[r];
;         }
;       }
;     }
	v_pk_mul_f32 v[148:149], v[60:61], v[154:155]
	s_nop 0
	v_pk_fma_f32 v[148:149], v[128:129], v[150:151], v[148:149] neg_lo:[0,0,1] neg_hi:[0,0,1]
	v_pk_mul_f32 v[128:129], v[128:129], v[154:155]
	v_mul_f32_e32 v154, v130, v156
	v_pk_fma_f32 v[60:61], v[60:61], v[150:151], v[128:129]
	v_mul_f32_e32 v128, v130, v152
	v_mul_f32_e32 v150, v62, v156
	v_mul_f32_e32 v152, v62, v152
	v_mov_b32_e32 v62, v131
	v_mov_b32_e32 v156, v153
	v_mov_b32_e32 v130, v63
	v_pk_mul_f32 v[162:163], v[62:63], v[156:157]
	v_pk_mul_f32 v[62:63], v[130:131], v[156:157]
	v_mov_b32_e32 v129, v162
	v_mov_b32_e32 v153, v62
	v_mov_b32_e32 v155, v63
	v_pk_add_f32 v[62:63], v[152:153], v[154:155]
	global_load_dwordx4 v[152:155], v[158:159], off offset:64
	s_nop 0
	global_load_dwordx4 v[156:159], v[160:161], off offset:64
	v_mov_b32_e32 v151, v163
	v_pk_add_f32 v[150:151], v[128:129], v[150:151] neg_lo:[0,1] neg_hi:[0,1]
	s_waitcnt vmcnt(0)
	v_pk_mul_f32 v[128:129], v[56:57], v[156:157]
	s_nop 0
	v_pk_fma_f32 v[128:129], v[120:121], v[152:153], v[128:129] neg_lo:[0,0,1] neg_hi:[0,0,1]
	v_pk_mul_f32 v[120:121], v[120:121], v[156:157]
	v_mul_f32_e32 v130, v58, v158
	v_pk_fma_f32 v[56:57], v[56:57], v[152:153], v[120:121]
	v_mul_f32_e32 v120, v122, v154
	v_mul_f32_e32 v152, v58, v154
	v_mul_f32_e32 v154, v122, v158
	v_mov_b32_e32 v58, v123
	v_mov_b32_e32 v158, v155
	v_pk_mul_f32 v[156:157], v[58:59], v[158:159]
	v_mov_b32_e32 v122, v59
	v_mov_b32_e32 v121, v156
	v_mov_b32_e32 v131, v157
	v_pk_add_f32 v[130:131], v[120:121], v[130:131] neg_lo:[0,1] neg_hi:[0,1]
	v_or_b32_e32 v120, 0x1000, v2
	v_ashrrev_i32_e32 v121, 31, v120
	v_lshlrev_b64 v[120:121], 2, v[120:121]
	v_pk_mul_f32 v[58:59], v[122:123], v[158:159]
	v_lshl_add_u64 v[122:123], s[34:35], 0, v[120:121]
	v_lshl_add_u64 v[120:121], s[36:37], 0, v[120:121]
	v_mov_b32_e32 v153, v58
	v_mov_b32_e32 v155, v59
	v_lshl_add_u64 v[160:161], v[122:123], 0, v[0:1]
	v_lshl_add_u64 v[162:163], v[120:121], 0, v[0:1]
	v_pk_add_f32 v[58:59], v[152:153], v[154:155]
	global_load_dwordx4 v[152:155], v[160:161], off
	global_load_dwordx4 v[156:159], v[162:163], off
	s_waitcnt vmcnt(0)
	v_pk_mul_f32 v[120:121], v[52:53], v[156:157]
	s_nop 0
	v_pk_fma_f32 v[120:121], v[112:113], v[152:153], v[120:121] neg_lo:[0,0,1] neg_hi:[0,0,1]
	v_pk_mul_f32 v[112:113], v[112:113], v[156:157]
	v_mul_f32_e32 v122, v54, v158
	v_pk_fma_f32 v[52:53], v[52:53], v[152:153], v[112:113]
	v_mul_f32_e32 v112, v114, v154
	v_mul_f32_e32 v152, v54, v154
	v_mul_f32_e32 v154, v114, v158
	v_mov_b32_e32 v54, v115
	v_mov_b32_e32 v158, v155
	v_mov_b32_e32 v114, v55
	v_pk_mul_f32 v[156:157], v[54:55], v[158:159]
	v_pk_mul_f32 v[54:55], v[114:115], v[158:159]
	v_mov_b32_e32 v113, v156
	v_mov_b32_e32 v153, v54
	v_mov_b32_e32 v155, v55
	v_mov_b32_e32 v123, v157
	v_pk_add_f32 v[54:55], v[152:153], v[154:155]
	global_load_dwordx4 v[152:155], v[160:161], off offset:64
	global_load_dwordx4 v[156:159], v[162:163], off offset:64
	v_pk_add_f32 v[122:123], v[112:113], v[122:123] neg_lo:[0,1] neg_hi:[0,1]
	s_waitcnt vmcnt(0)
	v_pk_mul_f32 v[112:113], v[48:49], v[156:157]
	s_nop 0
	v_pk_fma_f32 v[112:113], v[108:109], v[152:153], v[112:113] neg_lo:[0,0,1] neg_hi:[0,0,1]
	v_pk_mul_f32 v[108:109], v[108:109], v[156:157]
	v_mul_f32_e32 v114, v50, v158
	v_pk_fma_f32 v[48:49], v[48:49], v[152:153], v[108:109]
	v_mul_f32_e32 v108, v110, v154
	v_mul_f32_e32 v152, v50, v154
	v_mul_f32_e32 v154, v110, v158
	v_mov_b32_e32 v50, v111
	v_mov_b32_e32 v158, v155
	v_pk_mul_f32 v[156:157], v[50:51], v[158:159]
	v_mov_b32_e32 v110, v51
	v_mov_b32_e32 v109, v156
	v_mov_b32_e32 v115, v157
	v_pk_add_f32 v[114:115], v[108:109], v[114:115] neg_lo:[0,1] neg_hi:[0,1]
	v_or_b32_e32 v108, 0x1400, v2
	v_ashrrev_i32_e32 v109, 31, v108
	v_lshlrev_b64 v[108:109], 2, v[108:109]
	v_pk_mul_f32 v[50:51], v[110:111], v[158:159]
	v_lshl_add_u64 v[110:111], s[34:35], 0, v[108:109]
	v_lshl_add_u64 v[108:109], s[36:37], 0, v[108:109]
	v_mov_b32_e32 v153, v50
	v_mov_b32_e32 v155, v51
	v_lshl_add_u64 v[160:161], v[110:111], 0, v[0:1]
	v_lshl_add_u64 v[162:163], v[108:109], 0, v[0:1]
	v_pk_add_f32 v[50:51], v[152:153], v[154:155]
	global_load_dwordx4 v[152:155], v[160:161], off
	global_load_dwordx4 v[156:159], v[162:163], off
	s_waitcnt vmcnt(0)
	v_pk_mul_f32 v[108:109], v[44:45], v[156:157]
	s_nop 0
	v_pk_fma_f32 v[108:109], v[104:105], v[152:153], v[108:109] neg_lo:[0,0,1] neg_hi:[0,0,1]
	v_pk_mul_f32 v[104:105], v[104:105], v[156:157]
	v_mul_f32_e32 v110, v46, v158
	v_pk_fma_f32 v[44:45], v[44:45], v[152:153], v[104:105]
	v_mul_f32_e32 v104, v106, v154
	v_mul_f32_e32 v152, v46, v154
	v_mul_f32_e32 v154, v106, v158
	v_mov_b32_e32 v46, v107
	v_mov_b32_e32 v158, v155
	v_mov_b32_e32 v106, v47
	v_pk_mul_f32 v[156:157], v[46:47], v[158:159]
	v_pk_mul_f32 v[46:47], v[106:107], v[158:159]
	v_mov_b32_e32 v105, v156
	v_mov_b32_e32 v153, v46
	v_mov_b32_e32 v155, v47
	v_mov_b32_e32 v111, v157
	v_pk_add_f32 v[46:47], v[152:153], v[154:155]
	global_load_dwordx4 v[152:155], v[160:161], off offset:64
	global_load_dwordx4 v[156:159], v[162:163], off offset:64
	v_pk_add_f32 v[110:111], v[104:105], v[110:111] neg_lo:[0,1] neg_hi:[0,1]
	s_waitcnt vmcnt(0)
; __device__ void even_in_tile(const P& p, int li_even, int tm, int tn, char* smem) {
;     ...
; #pragma unroll
;     for (int i = 0; i < MI; ++i) {
;       const int s = s0 + MROW(i);
; #pragma unroll
;       for (int jj = 0; jj < 2; ++jj) {
;         const int d = wn * 32 + jj * 16 + g * 4;
;         const f32x4 c = *(const f32x4*)(ctab + s * 64 + d);
;         const f32x4 sn = *(const f32x4*)(stab + s * 64 + d);
; #pragma unroll
;         for (int r = 0; r < 4; ++r) {
;           const float a = acc[i][jj][r], bb = acc[i][jj + 2][r];
;           acc[i][jj][r] = a * c[r] - bb * sn[r];
;           acc[i][jj + 2][r] = bb * c[r] + a * sn[r];
;         }
;       }
;     }
;   }
	v_pk_mul_f32 v[104:105], v[40:41], v[156:157]
	s_nop 0
	v_pk_fma_f32 v[104:105], v[100:101], v[152:153], v[104:105] neg_lo:[0,0,1] neg_hi:[0,0,1]
	v_pk_mul_f32 v[100:101], v[100:101], v[156:157]
	v_mul_f32_e32 v106, v42, v158
	v_pk_fma_f32 v[40:41], v[40:41], v[152:153], v[100:101]
	v_mul_f32_e32 v100, v102, v154
	v_mul_f32_e32 v152, v42, v154
	v_mul_f32_e32 v154, v102, v158
	v_mov_b32_e32 v42, v103
	v_mov_b32_e32 v158, v155
	v_pk_mul_f32 v[156:157], v[42:43], v[158:159]
	v_mov_b32_e32 v102, v43
	v_mov_b32_e32 v101, v156
	v_mov_b32_e32 v107, v157
	v_pk_add_f32 v[106:107], v[100:101], v[106:107] neg_lo:[0,1] neg_hi:[0,1]
	v_or_b32_e32 v100, 0x1800, v2
	v_ashrrev_i32_e32 v101, 31, v100
	v_lshlrev_b64 v[100:101], 2, v[100:101]
	v_pk_mul_f32 v[42:43], v[102:103], v[158:159]
	v_lshl_add_u64 v[102:103], s[34:35], 0, v[100:101]
	v_lshl_add_u64 v[100:101], s[36:37], 0, v[100:101]
	v_mov_b32_e32 v153, v42
	v_mov_b32_e32 v155, v43
	v_lshl_add_u64 v[160:161], v[102:103], 0, v[0:1]
	v_lshl_add_u64 v[162:163], v[100:101], 0, v[0:1]
	v_pk_add_f32 v[42:43], v[152:153], v[154:155]
	global_load_dwordx4 v[152:155], v[160:161], off
	global_load_dwordx4 v[156:159], v[162:163], off
	v_or_b32_e32 v2, 0x1c00, v2
	v_ashrrev_i32_e32 v3, 31, v2
	v_lshlrev_b64 v[2:3], 2, v[2:3]
	s_waitcnt vmcnt(0)
	v_pk_mul_f32 v[100:101], v[36:37], v[156:157]
	s_nop 0
	v_pk_fma_f32 v[100:101], v[96:97], v[152:153], v[100:101] neg_lo:[0,0,1] neg_hi:[0,0,1]
	v_pk_mul_f32 v[96:97], v[96:97], v[156:157]
	v_mul_f32_e32 v102, v38, v158
	v_pk_fma_f32 v[36:37], v[36:37], v[152:153], v[96:97]
	v_mul_f32_e32 v96, v98, v154
	v_mul_f32_e32 v152, v38, v154
	v_mul_f32_e32 v154, v98, v158
	v_mov_b32_e32 v38, v99
	v_mov_b32_e32 v158, v155
	v_mov_b32_e32 v98, v39
	v_pk_mul_f32 v[156:157], v[38:39], v[158:159]
	v_pk_mul_f32 v[38:39], v[98:99], v[158:159]
	v_mov_b32_e32 v97, v156
	v_mov_b32_e32 v153, v38
	v_mov_b32_e32 v155, v39
	v_mov_b32_e32 v103, v157
	v_pk_add_f32 v[38:39], v[152:153], v[154:155]
	global_load_dwordx4 v[152:155], v[160:161], off offset:64
	global_load_dwordx4 v[156:159], v[162:163], off offset:64
	v_pk_add_f32 v[102:103], v[96:97], v[102:103] neg_lo:[0,1] neg_hi:[0,1]
	s_waitcnt vmcnt(0)
	v_pk_mul_f32 v[96:97], v[32:33], v[156:157]
	s_nop 0
	v_pk_fma_f32 v[96:97], v[92:93], v[152:153], v[96:97] neg_lo:[0,0,1] neg_hi:[0,0,1]
	v_pk_mul_f32 v[92:93], v[92:93], v[156:157]
	v_mul_f32_e32 v98, v34, v158
	v_pk_fma_f32 v[32:33], v[32:33], v[152:153], v[92:93]
	v_mul_f32_e32 v92, v94, v154
	v_mul_f32_e32 v152, v34, v154
	v_mul_f32_e32 v154, v94, v158
	v_mov_b32_e32 v34, v95
	v_mov_b32_e32 v158, v155
	v_pk_mul_f32 v[156:157], v[34:35], v[158:159]
	v_mov_b32_e32 v94, v35
	v_mov_b32_e32 v93, v156
	v_mov_b32_e32 v99, v157
	v_pk_add_f32 v[98:99], v[92:93], v[98:99] neg_lo:[0,1] neg_hi:[0,1]
	v_pk_mul_f32 v[34:35], v[94:95], v[158:159]
	v_lshl_add_u64 v[92:93], s[34:35], 0, v[2:3]
	v_lshl_add_u64 v[2:3], s[36:37], 0, v[2:3]
	v_mov_b32_e32 v153, v34
	v_mov_b32_e32 v155, v35
	v_lshl_add_u64 v[160:161], v[92:93], 0, v[0:1]
	v_lshl_add_u64 v[2:3], v[2:3], 0, v[0:1]
	v_pk_add_f32 v[34:35], v[152:153], v[154:155]
	global_load_dwordx4 v[152:155], v[160:161], off
	global_load_dwordx4 v[156:159], v[2:3], off
	s_waitcnt vmcnt(0)
	v_pk_mul_f32 v[92:93], v[24:25], v[156:157]
	s_nop 0
	v_pk_fma_f32 v[92:93], v[76:77], v[152:153], v[92:93] neg_lo:[0,0,1] neg_hi:[0,0,1]
	v_pk_mul_f32 v[76:77], v[76:77], v[156:157]
	v_mul_f32_e32 v94, v26, v158
	v_pk_fma_f32 v[24:25], v[24:25], v[152:153], v[76:77]
	v_mul_f32_e32 v76, v78, v154
	v_mul_f32_e32 v152, v26, v154
	v_mul_f32_e32 v154, v78, v158
	v_mov_b32_e32 v26, v79
	v_mov_b32_e32 v158, v155
	v_mov_b32_e32 v78, v27
	v_pk_mul_f32 v[156:157], v[26:27], v[158:159]
	v_pk_mul_f32 v[26:27], v[78:79], v[158:159]
	v_mov_b32_e32 v77, v156
	v_mov_b32_e32 v95, v157
	v_mov_b32_e32 v153, v26
	v_mov_b32_e32 v155, v27
	v_pk_add_f32 v[94:95], v[76:77], v[94:95] neg_lo:[0,1] neg_hi:[0,1]
	v_pk_add_f32 v[26:27], v[152:153], v[154:155]
	global_load_dwordx4 v[76:79], v[160:161], off offset:64
	global_load_dwordx4 v[152:155], v[2:3], off offset:64
	s_waitcnt vmcnt(0)
	v_pk_mul_f32 v[2:3], v[20:21], v[152:153]
	s_nop 0
	v_pk_fma_f32 v[156:157], v[28:29], v[76:77], v[2:3] neg_lo:[0,0,1] neg_hi:[0,0,1]
	v_pk_mul_f32 v[2:3], v[28:29], v[152:153]
	v_mul_f32_e32 v28, v22, v154
	v_pk_fma_f32 v[20:21], v[20:21], v[76:77], v[2:3]
	v_mul_f32_e32 v2, v30, v78
	v_mul_f32_e32 v76, v22, v78
	v_mul_f32_e32 v78, v30, v154
	v_mov_b32_e32 v22, v31
	v_mov_b32_e32 v154, v79
	v_pk_mul_f32 v[152:153], v[22:23], v[154:155]
	v_mov_b32_e32 v30, v23
	v_mov_b32_e32 v3, v152
	v_mov_b32_e32 v29, v153
	v_pk_add_f32 v[158:159], v[2:3], v[28:29] neg_lo:[0,1] neg_hi:[0,1]
	v_pk_mul_f32 v[2:3], v[30:31], v[154:155]
	v_mov_b64_e32 v[28:29], v[156:157]
	v_mov_b32_e32 v77, v2
	v_mov_b32_e32 v79, v3
	v_pk_add_f32 v[22:23], v[76:77], v[78:79]
	v_mov_b64_e32 v[76:77], v[92:93]
	v_mov_b64_e32 v[78:79], v[94:95]
	v_mov_b64_e32 v[92:93], v[96:97]
	v_mov_b64_e32 v[94:95], v[98:99]
	v_mov_b64_e32 v[96:97], v[100:101]
	v_mov_b64_e32 v[98:99], v[102:103]
	v_mov_b64_e32 v[100:101], v[104:105]
	v_mov_b64_e32 v[102:103], v[106:107]
	v_mov_b64_e32 v[104:105], v[108:109]
	v_mov_b64_e32 v[106:107], v[110:111]
	v_mov_b64_e32 v[108:109], v[112:113]
	v_mov_b64_e32 v[110:111], v[114:115]
	v_mov_b64_e32 v[112:113], v[120:121]
	v_mov_b64_e32 v[114:115], v[122:123]
	v_mov_b64_e32 v[120:121], v[128:129]
	v_mov_b64_e32 v[122:123], v[130:131]
	v_mov_b64_e32 v[128:129], v[148:149]
	v_mov_b64_e32 v[130:131], v[150:151]
	v_mov_b64_e32 v[148:149], v[146:147]
	v_mov_b64_e32 v[146:147], v[144:145]
	v_mov_b64_e32 v[144:145], v[142:143]
	v_mov_b64_e32 v[142:143], v[140:141]
	v_mov_b64_e32 v[140:141], v[138:139]
	v_mov_b64_e32 v[152:153], v[126:127]
	v_mov_b64_e32 v[138:139], v[136:137]
	v_mov_b64_e32 v[136:137], v[134:135]
	v_mov_b64_e32 v[150:151], v[124:125]
	v_mov_b64_e32 v[126:127], v[118:119]
	v_mov_b64_e32 v[30:31], v[158:159]
	v_mov_b64_e32 v[134:135], v[132:133]
	v_mov_b64_e32 v[124:125], v[116:117]
	s_cmp_eq_u32 s42, 1
	s_cselect_b64 s[34:35], -1, 0
	s_cmp_lg_u32 s42, 1
	s_cbranch_scc0 .LBB0_316

; __device__ __forceinline__ int otid() { int t = threadIdx.x; asm volatile("" : "+v"(t)); return t; }
; template <int MI, bool SWAP, bool F8 = false>
; __device__ __forceinline__ void gemm_core(const bf16_t* __restrict__ A, int lda, const bf16_t* __restrict__ B, int ldb,
;                                           int K, char* smem, f32x4 (&acc)[MI][4]) {
;   const int tid = otid(), lane = tid & 63, w = tid >> 6, wm = w >> 1, wn = w & 1;
;   const int lr = tid >> 3, lc = tid & 7;
;   const int li = lane & 15, g = lane >> 4;
;   u32x4 ra[MI], rb[4];
;   const bf16_t* ap = A + (size_t)lr * lda + lc * 8;
;   const bf16_t* bp = B + (size_t)lr * ldb + lc * 8;
; #pragma unroll
;   for (int i = 0; i < MI; ++i)
; #pragma unroll
;     for (int j = 0; j < 4; ++j) acc[i][j] = (f32x4){0.f, 0.f, 0.f, 0.f};
;   const int nk = K >> 6;
; #pragma unroll
;   for (int i = 0; i < MI; ++i) ra[i] = *(const u32x4*)(ap + (size_t)(32 * i) * lda);
; #pragma unroll
;   for (int i = 0; i < 4; ++i) rb[i] = *(const u32x4*)(bp + (size_t)(32 * i) * ldb);
;   const int woff = lr * 128 + ((lc ^ (lr & 7)) << 4);
;   const int xrow = (wm * 16 * MI + li) * 128;
;   const int wrow = 32768 + (wn * 32 + li) * 128;
; __device__ void even_in_tile(const P& p, int li_even, int tm, int tn, char* smem) {
;     ...
;   if (seg == 2 || seg == 5) {
;     gemm_core<MI, true>(A, 1024, B, 1024, 1024, smem, acc);
.LBB0_311:
	s_and_b64 vcc, exec, s[26:27]
	s_cbranch_vccz .LBB0_294
	s_waitcnt vmcnt(17)
	v_mov_b32_e32 v30, v208
	v_mov_b32_e32 v144, 0
	v_ashrrev_i32_e32 v2, 3, v30
	v_ashrrev_i32_e32 v3, 31, v2
	v_lshlrev_b64 v[20:21], 11, v[2:3]
	v_lshlrev_b32_e32 v0, 4, v30
	v_lshl_add_u64 v[24:25], s[20:21], 0, v[20:21]
	v_and_b32_e32 v0, 0x70, v0
	v_lshl_add_u64 v[24:25], v[24:25], 0, v[0:1]
	v_add_co_u32_e32 v26, vcc, 0x10000, v24
	v_lshl_add_u64 v[22:23], s[22:23], 0, v[20:21]
	s_nop 0
	v_addc_co_u32_e32 v27, vcc, 0, v25, vcc
	v_lshrrev_b32_e32 v254, 3, v208
	v_and_b32_e32 v254, 7, v254
	v_xor_b32_e32 v252, v254, v208
	v_and_b32_e32 v252, 7, v252
	v_lshlrev_b32_e32 v252, 4, v252
	v_lshl_or_b32 v252, v254, 11, v252
	v_add_u32_e32 v253, 0x10000, v252
	v_lshrrev_b32_e32 v254, 6, v208
	s_nop 0
	v_readfirstlane_b32 s62, v254
	s_lshl_b32 s62, s62, 10
	v_readfirstlane_b32 s56, v24
	v_readfirstlane_b32 s57, v25
	v_add_co_u32_e32 v26, vcc, 0x20000, v24
	v_lshl_add_u64 v[22:23], v[22:23], 0, v[0:1]
	s_nop 0
	v_addc_co_u32_e32 v27, vcc, 0, v25, vcc
	v_add_co_u32_e32 v28, vcc, 0x30000, v24
	s_add_i32 s20, s43, s44
	s_nop 0
	v_addc_co_u32_e32 v29, vcc, 0, v25, vcc
	v_add_co_u32_e32 v26, vcc, 0x40000, v24
	s_ashr_i32 s21, s20, 31
	s_nop 0
	v_addc_co_u32_e32 v27, vcc, 0, v25, vcc
	v_add_co_u32_e32 v28, vcc, 0x50000, v24
	s_lshl_b64 s[20:21], s[20:21], 19
	s_nop 0
	v_addc_co_u32_e32 v29, vcc, 0, v25, vcc
	v_add_co_u32_e32 v26, vcc, 0x60000, v24
	s_add_u32 s20, s8, s20
	s_nop 0
	v_addc_co_u32_e32 v27, vcc, 0, v25, vcc
	v_add_co_u32_e32 v24, vcc, 0x70000, v24
	v_and_b32_e32 v3, 15, v30
	s_nop 0
	v_addc_co_u32_e32 v25, vcc, 0, v25, vcc
	v_add_co_u32_e32 v24, vcc, s93, v22
	s_addc_u32 s21, s9, s21
	s_nop 0
	v_addc_co_u32_e32 v25, vcc, 0, v23, vcc
	s_nop 0
	v_readfirstlane_b32 s58, v22
	v_readfirstlane_b32 s59, v23
	v_add_co_u32_e32 v24, vcc, s46, v22
	v_lshrrev_b32_e32 v31, 4, v30
	s_nop 0
	v_addc_co_u32_e32 v25, vcc, 0, v23, vcc
	v_add_co_u32_e32 v22, vcc, s47, v22
	v_bfe_u32 v0, v30, 4, 2
	s_nop 0
	v_addc_co_u32_e32 v23, vcc, 0, v23, vcc
	v_lshlrev_b32_e32 v22, 7, v2
	v_xor_b32_e32 v2, v2, v30
	v_lshlrev_b32_e32 v2, 4, v2
	v_and_or_b32 v202, v2, s33, v22
	v_lshlrev_b32_e32 v2, 7, v30
	v_and_b32_e32 v203, 0xffffc780, v2
	v_lshrrev_b32_e32 v2, 1, v30
	v_and_or_b32 v2, v2, 32, v3
	v_and_b32_e32 v22, 7, v30
	s_add_u32 s8, s8, s10
	v_lshlrev_b32_e32 v204, 7, v2
	v_bitop3_b32 v2, v31, v22, 3 bitop3:0x6c
	v_bitop3_b32 v0, v0, v22, 4 bitop3:0x36
	s_addc_u32 s9, s9, s11
	v_lshlrev_b32_e32 v205, 4, v2
	v_lshlrev_b32_e32 v206, 4, v0
	v_lshl_add_u64 v[2:3], s[20:21], 0, v[20:21]
	v_lshlrev_b32_e32 v0, 4, v22
	v_lshl_add_u64 v[20:21], s[8:9], 0, v[20:21]
	v_lshl_add_u64 v[2:3], v[2:3], 0, v[0:1]
	v_lshl_add_u64 v[20:21], v[20:21], 0, v[0:1]
	v_lshl_add_u64 v[2:3], s[68:69], 0, v[2:3]
	v_lshl_add_u64 v[200:201], s[0:1], 0, v[20:21]
	s_mov_b64 s[8:9], 0
	v_mov_b32_e32 v145, v144
	v_mov_b32_e32 v146, v144
	v_mov_b32_e32 v147, v144
	v_mov_b32_e32 v20, v144
	v_mov_b32_e32 v21, v144
	v_mov_b32_e32 v22, v144
	v_mov_b32_e32 v23, v144
	s_waitcnt vmcnt(23)
	v_mov_b32_e32 v56, v144
	v_mov_b32_e32 v57, v144
	v_mov_b32_e32 v58, v144
	v_mov_b32_e32 v59, v144
	v_mov_b32_e32 v68, v144
	v_mov_b32_e32 v69, v144
	v_mov_b32_e32 v70, v144
	v_mov_b32_e32 v71, v144
	v_mov_b32_e32 v76, v144
	v_mov_b32_e32 v77, v144
	v_mov_b32_e32 v78, v144
	v_mov_b32_e32 v79, v144
	s_waitcnt vmcnt(21)
	v_mov_b32_e32 v84, v144
	v_mov_b32_e32 v85, v144
	v_mov_b32_e32 v86, v144
	v_mov_b32_e32 v87, v144
	v_mov_b32_e32 v24, v144
	v_mov_b32_e32 v25, v144
	v_mov_b32_e32 v26, v144
	v_mov_b32_e32 v27, v144
	v_mov_b32_e32 v28, v144
	v_mov_b32_e32 v29, v144
	v_mov_b32_e32 v30, v144
	v_mov_b32_e32 v31, v144
	v_mov_b32_e32 v32, v144
	v_mov_b32_e32 v33, v144
	v_mov_b32_e32 v34, v144
	v_mov_b32_e32 v35, v144
	v_mov_b32_e32 v36, v144
	v_mov_b32_e32 v37, v144
	v_mov_b32_e32 v38, v144
	v_mov_b32_e32 v39, v144
	v_mov_b32_e32 v40, v144
	v_mov_b32_e32 v41, v144
	v_mov_b32_e32 v42, v144
	v_mov_b32_e32 v43, v144
	v_mov_b32_e32 v44, v144
	v_mov_b32_e32 v45, v144
	v_mov_b32_e32 v46, v144
	v_mov_b32_e32 v47, v144
	v_mov_b32_e32 v48, v144
	v_mov_b32_e32 v49, v144
	v_mov_b32_e32 v50, v144
	v_mov_b32_e32 v51, v144
	v_mov_b32_e32 v52, v144
	v_mov_b32_e32 v53, v144
	v_mov_b32_e32 v54, v144
	v_mov_b32_e32 v55, v144
	v_mov_b32_e32 v60, v144
	v_mov_b32_e32 v61, v144
	v_mov_b32_e32 v62, v144
	v_mov_b32_e32 v63, v144
	v_mov_b32_e32 v64, v144
	v_mov_b32_e32 v65, v144
	v_mov_b32_e32 v66, v144
	v_mov_b32_e32 v67, v144
	v_mov_b32_e32 v72, v144
	v_mov_b32_e32 v73, v144
	v_mov_b32_e32 v74, v144
	v_mov_b32_e32 v75, v144
	v_mov_b32_e32 v80, v144
	v_mov_b32_e32 v81, v144
	v_mov_b32_e32 v82, v144
	v_mov_b32_e32 v83, v144
	s_waitcnt vmcnt(20)
	v_mov_b32_e32 v88, v144
	v_mov_b32_e32 v89, v144
	v_mov_b32_e32 v90, v144
	v_mov_b32_e32 v91, v144
	v_mov_b32_e32 v92, v144
	v_mov_b32_e32 v93, v144
	v_mov_b32_e32 v94, v144
	v_mov_b32_e32 v95, v144
	v_mov_b32_e32 v96, v144
	v_mov_b32_e32 v97, v144
	v_mov_b32_e32 v98, v144
	v_mov_b32_e32 v99, v144
	v_mov_b32_e32 v100, v144
	v_mov_b32_e32 v101, v144
	v_mov_b32_e32 v102, v144
	v_mov_b32_e32 v103, v144
	v_mov_b32_e32 v104, v144
	v_mov_b32_e32 v105, v144
	v_mov_b32_e32 v106, v144
	v_mov_b32_e32 v107, v144
	v_mov_b32_e32 v108, v144
	v_mov_b32_e32 v109, v144
	v_mov_b32_e32 v110, v144
	v_mov_b32_e32 v111, v144
	v_mov_b32_e32 v112, v144
	v_mov_b32_e32 v113, v144
	v_mov_b32_e32 v114, v144
	v_mov_b32_e32 v115, v144
	v_mov_b32_e32 v116, v144
	v_mov_b32_e32 v117, v144
	v_mov_b32_e32 v118, v144
	v_mov_b32_e32 v119, v144
	v_mov_b32_e32 v120, v144
	v_mov_b32_e32 v121, v144
	v_mov_b32_e32 v122, v144
	v_mov_b32_e32 v123, v144
	v_mov_b32_e32 v124, v144
	v_mov_b32_e32 v125, v144
	v_mov_b32_e32 v126, v144
	v_mov_b32_e32 v127, v144
	v_mov_b32_e32 v128, v144
	v_mov_b32_e32 v129, v144
	v_mov_b32_e32 v130, v144
	v_mov_b32_e32 v131, v144
	v_mov_b32_e32 v132, v144
	v_mov_b32_e32 v133, v144
	v_mov_b32_e32 v134, v144
	v_mov_b32_e32 v135, v144
	v_mov_b32_e32 v136, v144
	v_mov_b32_e32 v137, v144
	v_mov_b32_e32 v138, v144
	v_mov_b32_e32 v139, v144
	v_mov_b32_e32 v140, v144
	v_mov_b32_e32 v141, v144
	v_mov_b32_e32 v142, v144
	v_mov_b32_e32 v143, v144
	s_mov_b32 s7, 0x284000
	s_mov_b32 s10, 0x294000
; template <int MI, bool SWAP, bool F8 = false>
; __device__ __forceinline__ void gemm_core(const bf16_t* __restrict__ A, int lda, const bf16_t* __restrict__ B, int ldb,
;                                           int K, char* smem, f32x4 (&acc)[MI][4]) {
;     ...
;   for (int kt = 0; kt < nk; ++kt) {
;     __syncthreads();
; #pragma unroll
;     for (int i = 0; i < MI; ++i) *(u32x4*)(smem + woff + i * 4096) = ra[i];
; #pragma unroll
;     for (int i = 0; i < 4; ++i) *(u32x4*)(smem + 32768 + woff + i * 4096) = rb[i];
;     __syncthreads();
;     if (kt + 1 < nk) {
; #pragma unroll
;       for (int i = 0; i < MI; ++i) ra[i] = *(const u32x4*)(ap + (size_t)(32 * i) * lda + (kt + 1) * 64);
; #pragma unroll
;       for (int i = 0; i < 4; ++i) rb[i] = *(const u32x4*)(bp + (size_t)(32 * i) * ldb + (kt + 1) * 64);
;     }
;     if (F8) {
;       const int c0 = (g ^ (li & 7)) << 4, c1 = ((4 + g) ^ (li & 7)) << 4;
;       i32x8 wf8[4];
; #pragma unroll
;       for (int j = 0; j < 4; ++j) {
;         const char* rp = smem + wrow + ((j & 1) * 16 + (j >> 1) * 64) * 128;
;         const u32x4 lo = *(const u32x4*)(rp + c0), hi = *(const u32x4*)(rp + c1);
;         wf8[j] = (i32x8){(int)lo.x, (int)lo.y, (int)lo.z, (int)lo.w, (int)hi.x, (int)hi.y, (int)hi.z, (int)hi.w};
;       }
; #pragma unroll
;       for (int i = 0; i < MI; ++i) {
;         const char* rp = smem + xrow + i * 2048;
;         const u32x4 lo = *(const u32x4*)(rp + c0), hi = *(const u32x4*)(rp + c1);
;         const i32x8 xf8 = {(int)lo.x, (int)lo.y, (int)lo.z, (int)lo.w, (int)hi.x, (int)hi.y, (int)hi.z, (int)hi.w};
; #pragma unroll
;         for (int j = 0; j < 4; ++j)
;           acc[i][j] = __builtin_amdgcn_mfma_scale_f32_16x16x128_f8f6f4(wf8[j], xf8, acc[i][j], 0, 0, 0, 0x77777777, 0, 0x7f7f7f7f);
;       }
;     } else {
; #pragma unroll
;     for (int kk = 0; kk < 2; ++kk) {
;       const int ch = ((kk * 4 + g) ^ (li & 7)) << 4;
;       bf16x8 xf[MI], wf[4];
; #pragma unroll
;       for (int j = 0; j < 4; ++j) wf[j] = *(const bf16x8*)(smem + wrow + ((j & 1) * 16 + (j >> 1) * 64) * 128 + ch);
; #pragma unroll
;       for (int i = 0; i < MI; ++i) xf[i] = *(const bf16x8*)(smem + xrow + i * 2048 + ch);
; #pragma unroll
;       for (int i = 0; i < MI; ++i)
; #pragma unroll
;         for (int j = 0; j < 4; ++j) {
.LBB0_313:
	v_add_u32_e32 v215, v204, v205
	v_add_u32_e32 v213, v203, v205
	s_waitcnt vmcnt(63) expcnt(7) lgkmcnt(15)
	s_barrier
	s_mov_b32 m0, s62
	s_nop 0
	global_load_lds_dwordx4 v252, s[56:57]
	s_add_u32 m0, s62, 0x1000
	s_nop 0
	global_load_lds_dwordx4 v253, s[56:57]
	s_add_u32 s56, s56, 0x20000
	s_addc_u32 s57, s57, 0
	s_add_u32 m0, s62, 0x2000
	s_nop 0
	global_load_lds_dwordx4 v252, s[56:57]
	s_add_u32 m0, s62, 0x3000
	s_nop 0
	global_load_lds_dwordx4 v253, s[56:57]
	s_add_u32 s56, s56, 0x20000
	s_addc_u32 s57, s57, 0
	s_add_u32 m0, s62, 0x4000
	s_nop 0
	global_load_lds_dwordx4 v252, s[56:57]
	s_add_u32 m0, s62, 0x5000
	s_nop 0
	global_load_lds_dwordx4 v253, s[56:57]
	s_add_u32 s56, s56, 0x20000
	s_addc_u32 s57, s57, 0
	s_add_u32 m0, s62, 0x6000
	s_nop 0
	global_load_lds_dwordx4 v252, s[56:57]
	s_add_u32 m0, s62, 0x7000
	s_nop 0
	global_load_lds_dwordx4 v253, s[56:57]
	s_sub_u32 s56, s56, 0x60000
	s_subb_u32 s57, s57, 0
	s_add_u32 m0, s62, 0x8000
	s_nop 0
	global_load_lds_dwordx4 v252, s[58:59]
	s_add_u32 m0, s62, 0x9000
	s_nop 0
	global_load_lds_dwordx4 v253, s[58:59]
	s_add_u32 s58, s58, 0x20000
	s_addc_u32 s59, s59, 0
	s_add_u32 m0, s62, 0xa000
	s_nop 0
	global_load_lds_dwordx4 v252, s[58:59]
	s_add_u32 m0, s62, 0xb000
	s_nop 0
	global_load_lds_dwordx4 v253, s[58:59]
	s_sub_u32 s58, s58, 0x20000
	s_subb_u32 s59, s59, 0
	v_add_u32_e32 v252, 0x80, v252
	v_add_u32_e32 v253, 0x80, v253
	s_waitcnt vmcnt(0)
	s_barrier
	ds_read_b128 v[148:151], v213
	ds_read_b128 v[152:155], v215 offset:32768
	ds_read_b128 v[156:159], v215 offset:34816
	ds_read_b128 v[160:163], v213 offset:2048
	ds_read_b128 v[164:167], v215 offset:40960
	ds_read_b128 v[168:171], v215 offset:43008
	s_waitcnt lgkmcnt(4)
	v_mfma_f32_16x16x32_bf16 v[140:143], v[148:151], v[152:155], v[140:143]
	v_add_u32_e32 v0, v203, v206
	v_add_u32_e32 v207, v204, v206
	s_waitcnt lgkmcnt(3)
	v_mfma_f32_16x16x32_bf16 v[136:139], v[148:151], v[156:159], v[136:139]
	s_waitcnt lgkmcnt(1)
	v_mfma_f32_16x16x32_bf16 v[132:135], v[148:151], v[164:167], v[132:135]
	s_waitcnt lgkmcnt(0)
	v_mfma_f32_16x16x32_bf16 v[128:131], v[148:151], v[168:171], v[128:131]
	v_mfma_f32_16x16x32_bf16 v[124:127], v[160:163], v[152:155], v[124:127]
	v_mfma_f32_16x16x32_bf16 v[120:123], v[160:163], v[156:159], v[120:123]
	v_mfma_f32_16x16x32_bf16 v[116:119], v[160:163], v[164:167], v[116:119]
	v_mfma_f32_16x16x32_bf16 v[112:115], v[160:163], v[168:171], v[112:115]
	ds_read_b128 v[148:151], v213 offset:4096
	ds_read_b128 v[160:163], v213 offset:6144
	s_waitcnt lgkmcnt(1)
	v_mfma_f32_16x16x32_bf16 v[108:111], v[148:151], v[152:155], v[108:111]
	v_mfma_f32_16x16x32_bf16 v[104:107], v[148:151], v[156:159], v[104:107]
	v_mfma_f32_16x16x32_bf16 v[100:103], v[148:151], v[164:167], v[100:103]
	v_mfma_f32_16x16x32_bf16 v[96:99], v[148:151], v[168:171], v[96:99]
	s_waitcnt lgkmcnt(0)
	v_mfma_f32_16x16x32_bf16 v[92:95], v[160:163], v[152:155], v[92:95]
	v_mfma_f32_16x16x32_bf16 v[88:91], v[160:163], v[156:159], v[88:91]
	v_mfma_f32_16x16x32_bf16 v[80:83], v[160:163], v[164:167], v[80:83]
	v_mfma_f32_16x16x32_bf16 v[72:75], v[160:163], v[168:171], v[72:75]
	ds_read_b128 v[148:151], v213 offset:8192
	ds_read_b128 v[160:163], v213 offset:10240
	s_waitcnt lgkmcnt(1)
	v_mfma_f32_16x16x32_bf16 v[64:67], v[148:151], v[152:155], v[64:67]
	v_mfma_f32_16x16x32_bf16 v[60:63], v[148:151], v[156:159], v[60:63]
	v_mfma_f32_16x16x32_bf16 v[52:55], v[148:151], v[164:167], v[52:55]
	v_mfma_f32_16x16x32_bf16 v[48:51], v[148:151], v[168:171], v[48:51]
	s_waitcnt lgkmcnt(0)
	v_mfma_f32_16x16x32_bf16 v[44:47], v[160:163], v[152:155], v[44:47]
	v_mfma_f32_16x16x32_bf16 v[40:43], v[160:163], v[156:159], v[40:43]
	v_mfma_f32_16x16x32_bf16 v[36:39], v[160:163], v[164:167], v[36:39]
	v_mfma_f32_16x16x32_bf16 v[32:35], v[160:163], v[168:171], v[32:35]
	ds_read_b128 v[148:151], v213 offset:12288
	ds_read_b128 v[160:163], v213 offset:14336
	s_waitcnt lgkmcnt(1)
	v_mfma_f32_16x16x32_bf16 v[24:27], v[148:151], v[156:159], v[24:27]
	s_waitcnt lgkmcnt(0)
	v_mfma_f32_16x16x32_bf16 v[56:59], v[160:163], v[156:159], v[56:59]
	v_mfma_f32_16x16x32_bf16 v[68:71], v[160:163], v[152:155], v[68:71]
	v_mfma_f32_16x16x32_bf16 v[20:23], v[160:163], v[164:167], v[20:23]
	v_mfma_f32_16x16x32_bf16 v[144:147], v[160:163], v[168:171], v[144:147]
	v_mfma_f32_16x16x32_bf16 v[28:31], v[148:151], v[152:155], v[28:31]
	v_mfma_f32_16x16x32_bf16 v[84:87], v[148:151], v[164:167], v[84:87]
	v_mfma_f32_16x16x32_bf16 v[76:79], v[148:151], v[168:171], v[76:79]
	ds_read_b128 v[148:151], v0
	ds_read_b128 v[168:171], v207 offset:32768
	ds_read_b128 v[180:183], v207 offset:34816
	ds_read_b128 v[152:155], v0 offset:2048
	ds_read_b128 v[192:195], v207 offset:40960
	ds_read_b128 v[196:199], v207 offset:43008
	s_waitcnt lgkmcnt(4)
	v_mfma_f32_16x16x32_bf16 v[140:143], v[148:151], v[168:171], v[140:143]
	s_waitcnt lgkmcnt(3)
	v_mfma_f32_16x16x32_bf16 v[136:139], v[148:151], v[180:183], v[136:139]
	s_waitcnt lgkmcnt(1)
	v_mfma_f32_16x16x32_bf16 v[132:135], v[148:151], v[192:195], v[132:135]
	s_waitcnt lgkmcnt(0)
	v_mfma_f32_16x16x32_bf16 v[128:131], v[148:151], v[196:199], v[128:131]
	v_mfma_f32_16x16x32_bf16 v[124:127], v[152:155], v[168:171], v[124:127]
	v_mfma_f32_16x16x32_bf16 v[120:123], v[152:155], v[180:183], v[120:123]
	v_mfma_f32_16x16x32_bf16 v[116:119], v[152:155], v[192:195], v[116:119]
	v_mfma_f32_16x16x32_bf16 v[112:115], v[152:155], v[196:199], v[112:115]
	ds_read_b128 v[148:151], v0 offset:4096
	ds_read_b128 v[152:155], v0 offset:6144
	ds_read_b128 v[156:159], v0 offset:12288
	ds_read_b128 v[216:219], v0 offset:14336
	s_waitcnt lgkmcnt(3)
; template <int MI, bool SWAP, bool F8 = false>
; __device__ __forceinline__ void gemm_core(const bf16_t* __restrict__ A, int lda, const bf16_t* __restrict__ B, int ldb,
;                                           int K, char* smem, f32x4 (&acc)[MI][4]) {
;     ...
;   for (int kt = 0; kt < nk; ++kt) {
;     __syncthreads();
; #pragma unroll
;     for (int i = 0; i < MI; ++i) *(u32x4*)(smem + woff + i * 4096) = ra[i];
; #pragma unroll
;     for (int i = 0; i < 4; ++i) *(u32x4*)(smem + 32768 + woff + i * 4096) = rb[i];
;     __syncthreads();
;     if (kt + 1 < nk) {
; #pragma unroll
;       for (int i = 0; i < MI; ++i) ra[i] = *(const u32x4*)(ap + (size_t)(32 * i) * lda + (kt + 1) * 64);
; #pragma unroll
;       for (int i = 0; i < 4; ++i) rb[i] = *(const u32x4*)(bp + (size_t)(32 * i) * ldb + (kt + 1) * 64);
;     }
;     if (F8) {
;       const int c0 = (g ^ (li & 7)) << 4, c1 = ((4 + g) ^ (li & 7)) << 4;
;       i32x8 wf8[4];
; #pragma unroll
;       for (int j = 0; j < 4; ++j) {
;         const char* rp = smem + wrow + ((j & 1) * 16 + (j >> 1) * 64) * 128;
;         const u32x4 lo = *(const u32x4*)(rp + c0), hi = *(const u32x4*)(rp + c1);
;         wf8[j] = (i32x8){(int)lo.x, (int)lo.y, (int)lo.z, (int)lo.w, (int)hi.x, (int)hi.y, (int)hi.z, (int)hi.w};
;       }
; #pragma unroll
;       for (int i = 0; i < MI; ++i) {
;         const char* rp = smem + xrow + i * 2048;
;         const u32x4 lo = *(const u32x4*)(rp + c0), hi = *(const u32x4*)(rp + c1);
;         const i32x8 xf8 = {(int)lo.x, (int)lo.y, (int)lo.z, (int)lo.w, (int)hi.x, (int)hi.y, (int)hi.z, (int)hi.w};
; #pragma unroll
;         for (int j = 0; j < 4; ++j)
;           acc[i][j] = __builtin_amdgcn_mfma_scale_f32_16x16x128_f8f6f4(wf8[j], xf8, acc[i][j], 0, 0, 0, 0x77777777, 0, 0x7f7f7f7f);
;       }
;     } else {
; #pragma unroll
;     for (int kk = 0; kk < 2; ++kk) {
;       const int ch = ((kk * 4 + g) ^ (li & 7)) << 4;
;       bf16x8 xf[MI], wf[4];
; #pragma unroll
;       for (int j = 0; j < 4; ++j) wf[j] = *(const bf16x8*)(smem + wrow + ((j & 1) * 16 + (j >> 1) * 64) * 128 + ch);
; #pragma unroll
;       for (int i = 0; i < MI; ++i) xf[i] = *(const bf16x8*)(smem + xrow + i * 2048 + ch);
; #pragma unroll
;       for (int i = 0; i < MI; ++i)
; #pragma unroll
;         for (int j = 0; j < 4; ++j) {
	v_mfma_f32_16x16x32_bf16 v[108:111], v[148:151], v[168:171], v[108:111]
	v_mfma_f32_16x16x32_bf16 v[104:107], v[148:151], v[180:183], v[104:107]
	v_mfma_f32_16x16x32_bf16 v[100:103], v[148:151], v[192:195], v[100:103]
	v_mfma_f32_16x16x32_bf16 v[96:99], v[148:151], v[196:199], v[96:99]
	ds_read_b128 v[148:151], v0 offset:8192
	s_waitcnt lgkmcnt(3)
	v_mfma_f32_16x16x32_bf16 v[92:95], v[152:155], v[168:171], v[92:95]
	v_mfma_f32_16x16x32_bf16 v[88:91], v[152:155], v[180:183], v[88:91]
	v_mfma_f32_16x16x32_bf16 v[80:83], v[152:155], v[192:195], v[80:83]
	v_mfma_f32_16x16x32_bf16 v[72:75], v[152:155], v[196:199], v[72:75]
	ds_read_b128 v[152:155], v0 offset:10240
	s_waitcnt lgkmcnt(1)
	v_mfma_f32_16x16x32_bf16 v[64:67], v[148:151], v[168:171], v[64:67]
	v_mfma_f32_16x16x32_bf16 v[60:63], v[148:151], v[180:183], v[60:63]
	v_mfma_f32_16x16x32_bf16 v[52:55], v[148:151], v[192:195], v[52:55]
	v_mfma_f32_16x16x32_bf16 v[48:51], v[148:151], v[196:199], v[48:51]
	s_waitcnt lgkmcnt(0)
	v_mfma_f32_16x16x32_bf16 v[44:47], v[152:155], v[168:171], v[44:47]
	v_mfma_f32_16x16x32_bf16 v[40:43], v[152:155], v[180:183], v[40:43]
	v_mfma_f32_16x16x32_bf16 v[36:39], v[152:155], v[192:195], v[36:39]
	v_mfma_f32_16x16x32_bf16 v[32:35], v[152:155], v[196:199], v[32:35]
	v_mfma_f32_16x16x32_bf16 v[28:31], v[156:159], v[168:171], v[28:31]
	v_mfma_f32_16x16x32_bf16 v[24:27], v[156:159], v[180:183], v[24:27]
	v_mfma_f32_16x16x32_bf16 v[84:87], v[156:159], v[192:195], v[84:87]
	v_mfma_f32_16x16x32_bf16 v[76:79], v[156:159], v[196:199], v[76:79]
	v_mfma_f32_16x16x32_bf16 v[68:71], v[216:219], v[168:171], v[68:71]
	v_mfma_f32_16x16x32_bf16 v[56:59], v[216:219], v[180:183], v[56:59]
	v_mfma_f32_16x16x32_bf16 v[20:23], v[216:219], v[192:195], v[20:23]
	v_mfma_f32_16x16x32_bf16 v[144:147], v[216:219], v[196:199], v[144:147]
	s_add_u32 s8, s8, 0x80
	s_addc_u32 s9, s9, 0
	s_cmpk_lg_i32 s8, 0x780
	s_cbranch_scc1 .LBB0_313
	s_barrier
	s_mov_b32 m0, s62
	s_nop 0
	global_load_lds_dwordx4 v252, s[56:57]
	s_add_u32 m0, s62, 0x1000
	s_nop 0
	global_load_lds_dwordx4 v253, s[56:57]
	s_add_u32 s56, s56, 0x20000
	s_addc_u32 s57, s57, 0
	s_add_u32 m0, s62, 0x2000
	s_nop 0
	global_load_lds_dwordx4 v252, s[56:57]
	s_add_u32 m0, s62, 0x3000
	s_nop 0
	global_load_lds_dwordx4 v253, s[56:57]
	s_add_u32 s56, s56, 0x20000
	s_addc_u32 s57, s57, 0
	s_add_u32 m0, s62, 0x4000
	s_nop 0
	global_load_lds_dwordx4 v252, s[56:57]
	s_add_u32 m0, s62, 0x5000
	s_nop 0
	global_load_lds_dwordx4 v253, s[56:57]
	s_add_u32 s56, s56, 0x20000
	s_addc_u32 s57, s57, 0
	s_add_u32 m0, s62, 0x6000
	s_nop 0
	global_load_lds_dwordx4 v252, s[56:57]
	s_add_u32 m0, s62, 0x7000
	s_nop 0
	global_load_lds_dwordx4 v253, s[56:57]
	s_sub_u32 s56, s56, 0x60000
	s_subb_u32 s57, s57, 0
	s_add_u32 m0, s62, 0x8000
	s_nop 0
	global_load_lds_dwordx4 v252, s[58:59]
	s_add_u32 m0, s62, 0x9000
	s_nop 0
	global_load_lds_dwordx4 v253, s[58:59]
	s_add_u32 s58, s58, 0x20000
	s_addc_u32 s59, s59, 0
	s_add_u32 m0, s62, 0xa000
	s_nop 0
	global_load_lds_dwordx4 v252, s[58:59]
	s_add_u32 m0, s62, 0xb000
	s_nop 0
	global_load_lds_dwordx4 v253, s[58:59]
	s_sub_u32 s58, s58, 0x20000
	s_subb_u32 s59, s59, 0
	s_waitcnt vmcnt(0)
	s_barrier
	ds_read_b128 v[148:151], v215 offset:32768
	ds_read_b128 v[152:155], v215 offset:34816
	ds_read_b128 v[156:159], v215 offset:40960
	ds_read_b128 v[160:163], v215 offset:43008
	ds_read_b128 v[164:167], v213
	ds_read_b128 v[168:171], v213 offset:2048
	ds_read_b128 v[172:175], v213 offset:4096
	ds_read_b128 v[176:179], v213 offset:6144
	ds_read_b128 v[180:183], v213 offset:8192
	ds_read_b128 v[184:187], v213 offset:10240
	ds_read_b128 v[188:191], v213 offset:12288
	ds_read_b128 v[192:195], v213 offset:14336
	s_cmp_eq_u32 s42, 2
	s_mov_b32 s7, 0x6000000
	s_cselect_b32 s7, 0x2000000, s7
	s_waitcnt lgkmcnt(7)
	v_mfma_f32_16x16x32_bf16 v[140:143], v[164:167], v[148:151], v[140:143]
	s_add_u32 s8, s40, s7
	s_addc_u32 s9, s39, 0
	s_ashr_i32 s7, s6, 31
	v_mfma_f32_16x16x32_bf16 v[136:139], v[164:167], v[152:155], v[136:139]
	s_lshl_b64 s[6:7], s[6:7], 20
	s_add_u32 s6, s8, s6
	s_addc_u32 s7, s9, s7
	v_mfma_f32_16x16x32_bf16 v[132:135], v[164:167], v[156:159], v[132:135]
	s_lshl_b32 s8, s41, 1
	s_add_u32 s6, s6, s8
	s_addc_u32 s7, s7, 0
	v_mfma_f32_16x16x32_bf16 v[128:131], v[164:167], v[160:163], v[128:131]
	s_waitcnt lgkmcnt(6)
	v_mfma_f32_16x16x32_bf16 v[124:127], v[168:171], v[148:151], v[124:127]
	v_mfma_f32_16x16x32_bf16 v[120:123], v[168:171], v[152:155], v[120:123]
	v_mfma_f32_16x16x32_bf16 v[116:119], v[168:171], v[156:159], v[116:119]
	v_mfma_f32_16x16x32_bf16 v[112:115], v[168:171], v[160:163], v[112:115]
	s_waitcnt lgkmcnt(5)
	v_mfma_f32_16x16x32_bf16 v[108:111], v[172:175], v[148:151], v[108:111]
	v_mfma_f32_16x16x32_bf16 v[104:107], v[172:175], v[152:155], v[104:107]
	v_mfma_f32_16x16x32_bf16 v[100:103], v[172:175], v[156:159], v[100:103]
	v_mfma_f32_16x16x32_bf16 v[96:99], v[172:175], v[160:163], v[96:99]
	s_waitcnt lgkmcnt(4)
	v_mfma_f32_16x16x32_bf16 v[92:95], v[176:179], v[148:151], v[92:95]
	v_mfma_f32_16x16x32_bf16 v[88:91], v[176:179], v[152:155], v[88:91]
	v_mfma_f32_16x16x32_bf16 v[80:83], v[176:179], v[156:159], v[80:83]
	v_mfma_f32_16x16x32_bf16 v[72:75], v[176:179], v[160:163], v[72:75]
	s_waitcnt lgkmcnt(3)
	v_mfma_f32_16x16x32_bf16 v[64:67], v[180:183], v[148:151], v[64:67]
	v_mfma_f32_16x16x32_bf16 v[60:63], v[180:183], v[152:155], v[60:63]
	v_mfma_f32_16x16x32_bf16 v[52:55], v[180:183], v[156:159], v[52:55]
	v_mfma_f32_16x16x32_bf16 v[48:51], v[180:183], v[160:163], v[48:51]
	s_waitcnt lgkmcnt(2)
; template <int MI, bool SWAP, bool F8 = false>
; __device__ __forceinline__ void gemm_core(const bf16_t* __restrict__ A, int lda, const bf16_t* __restrict__ B, int ldb,
;                                           int K, char* smem, f32x4 (&acc)[MI][4]) {
;     ...
;     for (int kk = 0; kk < 2; ++kk) {
;       const int ch = ((kk * 4 + g) ^ (li & 7)) << 4;
;       bf16x8 xf[MI], wf[4];
; #pragma unroll
;       for (int j = 0; j < 4; ++j) wf[j] = *(const bf16x8*)(smem + wrow + ((j & 1) * 16 + (j >> 1) * 64) * 128 + ch);
; #pragma unroll
;       for (int i = 0; i < MI; ++i) xf[i] = *(const bf16x8*)(smem + xrow + i * 2048 + ch);
; #pragma unroll
;       for (int i = 0; i < MI; ++i)
; #pragma unroll
;         for (int j = 0; j < 4; ++j) {
;           if (SWAP) acc[i][j] = __builtin_amdgcn_mfma_f32_16x16x32_bf16(xf[i], wf[j], acc[i][j], 0, 0, 0);
;           else acc[i][j] = __builtin_amdgcn_mfma_f32_16x16x32_bf16(wf[j], xf[i], acc[i][j], 0, 0, 0);
;         }
; __device__ void even_in_tile(const P& p, int li_even, int tm, int tn, char* smem) {
;     ...
;     EPI_COORDS
;     bf16_t* dst = R + (seg == 2 ? R_MVT : R_RVT) + (size_t)bh * 128 * 4096;
; #pragma unroll
;     for (int i = 0; i < MI; ++i)
; #pragma unroll
;       for (int j = 0; j < 4; ++j) {
;         u32x2 v;
;         v.x = pk_bf16(acc[i][j][0], acc[i][j][1]);
;         v.y = pk_bf16(acc[i][j][2], acc[i][j][3]);
;         *(u32x2*)(dst + (size_t)NCOLS(j) * 4096 + s0 + MROWS(i)) = v;
;       }
	v_mfma_f32_16x16x32_bf16 v[44:47], v[184:187], v[148:151], v[44:47]
	v_mfma_f32_16x16x32_bf16 v[40:43], v[184:187], v[152:155], v[40:43]
	v_mfma_f32_16x16x32_bf16 v[36:39], v[184:187], v[156:159], v[36:39]
	v_mfma_f32_16x16x32_bf16 v[32:35], v[184:187], v[160:163], v[32:35]
	s_waitcnt lgkmcnt(1)
	v_mfma_f32_16x16x32_bf16 v[28:31], v[188:191], v[148:151], v[28:31]
	v_mfma_f32_16x16x32_bf16 v[24:27], v[188:191], v[152:155], v[24:27]
	v_mfma_f32_16x16x32_bf16 v[164:167], v[188:191], v[156:159], v[84:87]
	v_mfma_f32_16x16x32_bf16 v[168:171], v[188:191], v[160:163], v[76:79]
	s_waitcnt lgkmcnt(0)
	v_mfma_f32_16x16x32_bf16 v[148:151], v[192:195], v[148:151], v[68:71]
	v_mfma_f32_16x16x32_bf16 v[152:155], v[192:195], v[152:155], v[56:59]
	v_mfma_f32_16x16x32_bf16 v[20:23], v[192:195], v[156:159], v[20:23]
	v_mfma_f32_16x16x32_bf16 v[144:147], v[192:195], v[160:163], v[144:147]
	ds_read_b128 v[156:159], v207 offset:32768
	ds_read_b128 v[160:163], v207 offset:34816
	ds_read_b128 v[172:175], v207 offset:40960
	ds_read_b128 v[176:179], v207 offset:43008
	ds_read_b128 v[56:59], v0
	ds_read_b128 v[68:71], v0 offset:2048
	ds_read_b128 v[76:79], v0 offset:4096
	ds_read_b128 v[84:87], v0 offset:6144
	ds_read_b128 v[180:183], v0 offset:8192
	ds_read_b128 v[184:187], v0 offset:10240
	ds_read_b128 v[188:191], v0 offset:12288
	ds_read_b128 v[192:195], v0 offset:14336
	v_mov_b32_e32 v0, v208
	s_waitcnt lgkmcnt(7)
	v_mfma_f32_16x16x32_bf16 v[140:143], v[56:59], v[156:159], v[140:143]
	v_and_b32_e32 v2, 15, v0
	v_lshrrev_b32_e32 v3, 1, v0
	v_mfma_f32_16x16x32_bf16 v[196:199], v[56:59], v[160:163], v[136:139]
	s_nop 2
	v_and_or_b32 v136, v3, 32, v2
	v_and_b32_e32 v2, 0xffffff80, v0
	v_lshrrev_b32_e32 v0, 2, v0
	v_and_or_b32 v2, v0, 12, v2
	v_ashrrev_i32_e32 v3, 31, v2
	v_lshl_add_u64 v[2:3], v[2:3], 1, s[6:7]
	v_lshlrev_b32_e32 v0, 13, v136
	v_mfma_f32_16x16x32_bf16 v[200:203], v[56:59], v[172:175], v[132:135]
	v_cvt_pk_bf16_f32 v138, v140, v141
	v_cvt_pk_bf16_f32 v139, v142, v143
	v_lshl_add_u64 v[136:137], v[2:3], 0, v[0:1]
	v_mfma_f32_16x16x32_bf16 v[132:135], v[56:59], v[176:179], v[128:131]
	global_store_dwordx2 v[136:137], v[138:139], off
	v_or_b32_e32 v138, 0x20000, v0
	v_mov_b32_e32 v139, v1
	s_waitcnt lgkmcnt(6)
	v_mfma_f32_16x16x32_bf16 v[128:131], v[68:71], v[156:159], v[124:127]
	v_cvt_pk_bf16_f32 v140, v196, v197
	v_cvt_pk_bf16_f32 v141, v198, v199
	v_lshl_add_u64 v[142:143], v[2:3], 0, v[138:139]
	v_mfma_f32_16x16x32_bf16 v[124:127], v[68:71], v[160:163], v[120:123]
	global_store_dwordx2 v[142:143], v[140:141], off
	v_or_b32_e32 v140, 0x80000, v0
	v_or_b32_e32 v0, 0xa0000, v0
	v_mfma_f32_16x16x32_bf16 v[120:123], v[68:71], v[172:175], v[116:119]
	v_cvt_pk_bf16_f32 v132, v132, v133
	v_cvt_pk_bf16_f32 v133, v134, v135
	v_lshl_add_u64 v[134:135], v[2:3], 0, v[0:1]
	v_mfma_f32_16x16x32_bf16 v[116:119], v[68:71], v[176:179], v[112:115]
	global_store_dwordx2 v[134:135], v[132:133], off
	v_lshl_add_u64 v[132:133], v[2:3], 0, 32
	s_mov_b64 s[6:7], 0x60
	s_waitcnt lgkmcnt(5)
	v_mfma_f32_16x16x32_bf16 v[112:115], v[76:79], v[156:159], v[108:111]
	v_mov_b32_e32 v141, v1
	s_nop 1
	v_cvt_pk_bf16_f32 v116, v116, v117
	v_cvt_pk_bf16_f32 v117, v118, v119
	v_mfma_f32_16x16x32_bf16 v[108:111], v[76:79], v[160:163], v[104:107]
	v_lshl_add_u64 v[118:119], v[132:133], 0, v[0:1]
	global_store_dwordx2 v[118:119], v[116:117], off
	v_lshl_add_u64 v[116:117], v[2:3], 0, 64
	v_mfma_f32_16x16x32_bf16 v[104:107], v[76:79], v[172:175], v[100:103]
	v_cvt_pk_bf16_f32 v142, v200, v201
	v_cvt_pk_bf16_f32 v143, v202, v203
	v_cvt_pk_bf16_f32 v128, v128, v129
	v_mfma_f32_16x16x32_bf16 v[100:103], v[76:79], v[176:179], v[96:99]
	v_cvt_pk_bf16_f32 v129, v130, v131
	v_cvt_pk_bf16_f32 v124, v124, v125
	v_cvt_pk_bf16_f32 v125, v126, v127
	s_waitcnt lgkmcnt(4)
	v_mfma_f32_16x16x32_bf16 v[96:99], v[84:87], v[156:159], v[92:95]
	v_lshl_add_u64 v[126:127], v[132:133], 0, v[138:139]
	s_nop 1
	v_cvt_pk_bf16_f32 v100, v100, v101
	v_cvt_pk_bf16_f32 v101, v102, v103
	v_mfma_f32_16x16x32_bf16 v[92:95], v[84:87], v[160:163], v[88:91]
	v_lshl_add_u64 v[102:103], v[116:117], 0, v[0:1]
	global_store_dwordx2 v[102:103], v[100:101], off
	v_lshl_add_u64 v[100:101], v[2:3], 0, s[6:7]
	v_mfma_f32_16x16x32_bf16 v[88:91], v[84:87], v[172:175], v[80:83]
	s_mov_b64 s[6:7], 0x80
	v_cvt_pk_bf16_f32 v120, v120, v121
	v_cvt_pk_bf16_f32 v121, v122, v123
	v_mfma_f32_16x16x32_bf16 v[84:87], v[84:87], v[176:179], v[72:75]
	v_lshl_add_u64 v[122:123], v[132:133], 0, v[140:141]
	v_cvt_pk_bf16_f32 v112, v112, v113
	v_cvt_pk_bf16_f32 v113, v114, v115
	s_waitcnt lgkmcnt(3)
	v_mfma_f32_16x16x32_bf16 v[68:71], v[180:183], v[176:179], v[48:51]
	v_cvt_pk_bf16_f32 v108, v108, v109
	s_nop 1
	v_cvt_pk_bf16_f32 v84, v84, v85
	v_cvt_pk_bf16_f32 v85, v86, v87
	v_mfma_f32_16x16x32_bf16 v[72:75], v[180:183], v[172:175], v[52:55]
	v_lshl_add_u64 v[86:87], v[100:101], 0, v[0:1]
	global_store_dwordx2 v[86:87], v[84:85], off
	v_lshl_add_u64 v[84:85], v[2:3], 0, s[6:7]
	s_waitcnt lgkmcnt(2)
; __device__ void even_in_tile(const P& p, int li_even, int tm, int tn, char* smem) {
;     ...
; #pragma unroll
;     for (int i = 0; i < MI; ++i)
; #pragma unroll
;       for (int j = 0; j < 4; ++j) {
;         u32x2 v;
;         v.x = pk_bf16(acc[i][j][0], acc[i][j][1]);
;         v.y = pk_bf16(acc[i][j][2], acc[i][j][3]);
;         *(u32x2*)(dst + (size_t)NCOLS(j) * 4096 + s0 + MROWS(i)) = v;
;       }
	v_mfma_f32_16x16x32_bf16 v[52:55], v[184:187], v[176:179], v[32:35]
	v_cvt_pk_bf16_f32 v68, v68, v69
	v_cvt_pk_bf16_f32 v69, v70, v71
	v_lshl_add_u64 v[70:71], v[84:85], 0, v[0:1]
	s_mov_b64 s[6:7], 0xa0
	v_mfma_f32_16x16x32_bf16 v[80:83], v[180:183], v[156:159], v[64:67]
	global_store_dwordx2 v[70:71], v[68:69], off
	v_lshl_add_u64 v[68:69], v[2:3], 0, s[6:7]
	s_nop 0
	v_cvt_pk_bf16_f32 v52, v52, v53
	v_mfma_f32_16x16x32_bf16 v[76:79], v[180:183], v[160:163], v[60:63]
	v_cvt_pk_bf16_f32 v53, v54, v55
	v_lshl_add_u64 v[54:55], v[68:69], 0, v[0:1]
	s_mov_b64 s[6:7], 0xc0
	v_mfma_f32_16x16x32_bf16 v[64:67], v[184:187], v[156:159], v[44:47]
	global_store_dwordx2 v[54:55], v[52:53], off
	v_lshl_add_u64 v[52:53], v[2:3], 0, s[6:7]
	s_mov_b64 s[6:7], 0xe0
	v_mfma_f32_16x16x32_bf16 v[60:63], v[184:187], v[160:163], v[40:43]
	v_cvt_pk_bf16_f32 v109, v110, v111
	v_lshl_add_u64 v[110:111], v[116:117], 0, v[138:139]
	v_cvt_pk_bf16_f32 v104, v104, v105
	v_mfma_f32_16x16x32_bf16 v[56:59], v[184:187], v[172:175], v[36:39]
	v_cvt_pk_bf16_f32 v105, v106, v107
	v_lshl_add_u64 v[106:107], v[116:117], 0, v[140:141]
	v_cvt_pk_bf16_f32 v96, v96, v97
	s_waitcnt lgkmcnt(1)
	v_mfma_f32_16x16x32_bf16 v[48:51], v[188:191], v[156:159], v[28:31]
	v_cvt_pk_bf16_f32 v97, v98, v99
	v_cvt_pk_bf16_f32 v92, v92, v93
	v_cvt_pk_bf16_f32 v93, v94, v95
	v_mfma_f32_16x16x32_bf16 v[44:47], v[188:191], v[160:163], v[24:27]
	v_lshl_add_u64 v[94:95], v[100:101], 0, v[138:139]
	v_cvt_pk_bf16_f32 v88, v88, v89
	v_cvt_pk_bf16_f32 v89, v90, v91
	v_mfma_f32_16x16x32_bf16 v[40:43], v[188:191], v[172:175], v[164:167]
	v_lshl_add_u64 v[90:91], v[100:101], 0, v[140:141]
	v_cvt_pk_bf16_f32 v80, v80, v81
	v_cvt_pk_bf16_f32 v81, v82, v83
	v_mfma_f32_16x16x32_bf16 v[36:39], v[188:191], v[176:179], v[168:171]
	v_cvt_pk_bf16_f32 v76, v76, v77
	v_cvt_pk_bf16_f32 v77, v78, v79
	v_lshl_add_u64 v[78:79], v[84:85], 0, v[138:139]
	s_waitcnt lgkmcnt(0)
	v_mfma_f32_16x16x32_bf16 v[32:35], v[192:195], v[156:159], v[148:151]
	v_cvt_pk_bf16_f32 v72, v72, v73
	v_cvt_pk_bf16_f32 v73, v74, v75
	v_lshl_add_u64 v[74:75], v[84:85], 0, v[140:141]
	v_mfma_f32_16x16x32_bf16 v[28:31], v[192:195], v[160:163], v[152:155]
	v_cvt_pk_bf16_f32 v64, v64, v65
	v_cvt_pk_bf16_f32 v65, v66, v67
	v_cvt_pk_bf16_f32 v60, v60, v61
	v_mfma_f32_16x16x32_bf16 v[24:27], v[192:195], v[172:175], v[20:23]
	v_cvt_pk_bf16_f32 v61, v62, v63
	v_lshl_add_u64 v[62:63], v[68:69], 0, v[138:139]
	v_cvt_pk_bf16_f32 v56, v56, v57
	v_mfma_f32_16x16x32_bf16 v[20:23], v[192:195], v[176:179], v[144:147]
	v_cvt_pk_bf16_f32 v57, v58, v59
	v_lshl_add_u64 v[58:59], v[68:69], 0, v[140:141]
	v_cvt_pk_bf16_f32 v48, v48, v49
	v_lshl_add_u64 v[144:145], v[2:3], 0, v[140:141]
	v_lshl_add_u64 v[2:3], v[2:3], 0, s[6:7]
	v_cvt_pk_bf16_f32 v49, v50, v51
	v_cvt_pk_bf16_f32 v44, v44, v45
	v_cvt_pk_bf16_f32 v45, v46, v47
	v_lshl_add_u64 v[46:47], v[52:53], 0, v[138:139]
	v_cvt_pk_bf16_f32 v40, v40, v41
	v_cvt_pk_bf16_f32 v41, v42, v43
	v_lshl_add_u64 v[42:43], v[52:53], 0, v[140:141]
	v_cvt_pk_bf16_f32 v36, v36, v37
	v_cvt_pk_bf16_f32 v37, v38, v39
	v_lshl_add_u64 v[38:39], v[52:53], 0, v[0:1]
	v_cvt_pk_bf16_f32 v32, v32, v33
	v_cvt_pk_bf16_f32 v33, v34, v35
	v_cvt_pk_bf16_f32 v28, v28, v29
	v_cvt_pk_bf16_f32 v29, v30, v31
	v_lshl_add_u64 v[30:31], v[2:3], 0, v[138:139]
	v_cvt_pk_bf16_f32 v24, v24, v25
	v_cvt_pk_bf16_f32 v25, v26, v27
	v_lshl_add_u64 v[26:27], v[2:3], 0, v[140:141]
	v_cvt_pk_bf16_f32 v20, v20, v21
	v_cvt_pk_bf16_f32 v21, v22, v23
	v_lshl_add_u64 v[2:3], v[2:3], 0, v[0:1]
	global_store_dwordx2 v[144:145], v[142:143], off
	global_store_dwordx2 v[136:137], v[128:129], off offset:32
	global_store_dwordx2 v[126:127], v[124:125], off
	global_store_dwordx2 v[122:123], v[120:121], off
	global_store_dwordx2 v[136:137], v[112:113], off offset:64
	global_store_dwordx2 v[110:111], v[108:109], off
	global_store_dwordx2 v[106:107], v[104:105], off
	global_store_dwordx2 v[136:137], v[96:97], off offset:96
	global_store_dwordx2 v[94:95], v[92:93], off
	global_store_dwordx2 v[90:91], v[88:89], off
	global_store_dwordx2 v[136:137], v[80:81], off offset:128
	global_store_dwordx2 v[78:79], v[76:77], off
	global_store_dwordx2 v[74:75], v[72:73], off
	global_store_dwordx2 v[136:137], v[64:65], off offset:160
	global_store_dwordx2 v[62:63], v[60:61], off
	global_store_dwordx2 v[58:59], v[56:57], off
	global_store_dwordx2 v[136:137], v[48:49], off offset:192
	global_store_dwordx2 v[46:47], v[44:45], off
	global_store_dwordx2 v[42:43], v[40:41], off
	global_store_dwordx2 v[38:39], v[36:37], off
	global_store_dwordx2 v[136:137], v[32:33], off offset:224
	global_store_dwordx2 v[30:31], v[28:29], off
	global_store_dwordx2 v[26:27], v[24:25], off
	global_store_dwordx2 v[2:3], v[20:21], off
	s_branch .LBB0_294

; __device__ __forceinline__ int otid() { int t = threadIdx.x; asm volatile("" : "+v"(t)); return t; }
; template <int MI, bool SWAP, bool F8 = false>
; __device__ __forceinline__ void gemm_core(const bf16_t* __restrict__ A, int lda, const bf16_t* __restrict__ B, int ldb,
;                                           int K, char* smem, f32x4 (&acc)[MI][4]) {
;   const int tid = otid(), lane = tid & 63, w = tid >> 6, wm = w >> 1, wn = w & 1;
;   const int lr = tid >> 3, lc = tid & 7;
;   const int li = lane & 15, g = lane >> 4;
;   u32x4 ra[MI], rb[4];
;   const bf16_t* ap = A + (size_t)lr * lda + lc * 8;
;   const bf16_t* bp = B + (size_t)lr * ldb + lc * 8;
; #pragma unroll
;   for (int i = 0; i < MI; ++i)
; #pragma unroll
;     for (int j = 0; j < 4; ++j) acc[i][j] = (f32x4){0.f, 0.f, 0.f, 0.f};
;   const int nk = K >> 6;
; #pragma unroll
;   for (int i = 0; i < MI; ++i) ra[i] = *(const u32x4*)(ap + (size_t)(32 * i) * lda);
; #pragma unroll
;   for (int i = 0; i < 4; ++i) rb[i] = *(const u32x4*)(bp + (size_t)(32 * i) * ldb);
;   const int woff = lr * 128 + ((lc ^ (lr & 7)) << 4);
;   const int xrow = (wm * 16 * MI + li) * 128;
;   const int wrow = 32768 + (wn * 32 + li) * 128;
; __global__ void __launch_bounds__(256, 2) fwd_kernel(P p) {
;     ...
;       for (int it = blockIdx.x; it < 64 * 8; it += G) {
;         const int tm = (it & 7) * 8 + ((it >> 3) >> 3), tn = (it >> 3) & 7;
;         gemm_tile_f32<true, 8>((const bf16_t*)(ws + OFF_AO) + (size_t)tm * 256 * 1024, 1024,
;                             (const bf16_t*)(ws + OFF_WEOUT) + ((size_t)li2 * 1024 + tn * 128) * 1024, 1024, 1024,
;                             H + (size_t)tm * 256 * 1024 + tn * 128, 1024, smem);
.LBB0_818:
	s_lshl_b32 s0, s19, 10
	s_and_b32 s0, s0, 0xe0000
	s_add_i32 s66, s8, s0
	s_lshl_b32 s0, s21, 3
	s_and_b32 s0, s0, 56
	s_ashr_i32 s29, s21, 6
	s_add_i32 s22, s0, s29
	s_ashr_i32 s23, s22, 31
	s_waitcnt vmcnt(17)
	v_mov_b32_e32 v30, v208
	s_and_b32 s28, s20, 56
	s_lshl_b64 s[6:7], s[66:67], 1
	s_lshl_b64 s[0:1], s[22:23], 18
	s_lshl_b64 s[22:23], s[22:23], 19
	s_add_u32 s24, s9, s22
	v_ashrrev_i32_e32 v2, 3, v30
	v_ashrrev_i32_e32 v3, 31, v2
	s_addc_u32 s25, s10, s23
	v_lshlrev_b64 v[20:21], 11, v[2:3]
	v_lshlrev_b32_e32 v0, 4, v30
	v_lshl_add_u64 v[24:25], s[24:25], 0, v[20:21]
	v_and_b32_e32 v0, 0x70, v0
	v_lshl_add_u64 v[24:25], v[24:25], 0, v[0:1]
	v_add_co_u32_e32 v26, vcc, s93, v24
	s_lshl_b32 s22, s21, 4
	s_nop 0
	v_addc_co_u32_e32 v27, vcc, 0, v25, vcc
	v_lshrrev_b32_e32 v254, 3, v208
	v_and_b32_e32 v254, 7, v254
	v_xor_b32_e32 v252, v254, v208
	v_and_b32_e32 v252, 7, v252
	v_lshlrev_b32_e32 v252, 4, v252
	v_lshl_or_b32 v252, v254, 11, v252
	v_add_u32_e32 v253, 0x10000, v252
	v_lshrrev_b32_e32 v254, 6, v208
	s_nop 0
	v_readfirstlane_b32 s62, v254
	s_lshl_b32 s62, s62, 10
	v_readfirstlane_b32 s56, v24
	v_readfirstlane_b32 s57, v25
	v_add_co_u32_e32 v26, vcc, s46, v24
	s_and_b32 s22, s22, 0x380
	s_nop 0
	v_addc_co_u32_e32 v27, vcc, 0, v25, vcc
	v_add_co_u32_e32 v28, vcc, s47, v24
	s_lshl_b32 s23, s8, 1
	s_nop 0
	v_addc_co_u32_e32 v29, vcc, 0, v25, vcc
	v_add_co_u32_e32 v26, vcc, s50, v24
	s_lshl_b32 s26, s22, 11
	s_nop 0
	v_addc_co_u32_e32 v27, vcc, 0, v25, vcc
	s_or_b32 s23, s26, s23
	v_add_co_u32_e32 v28, vcc, s51, v24
	s_add_u32 s26, s11, s23
	s_nop 0
	v_addc_co_u32_e32 v29, vcc, 0, v25, vcc
	s_mov_b32 s23, 0x60000
	v_add_co_u32_e32 v26, vcc, s23, v24
	s_addc_u32 s27, s18, 0
	s_nop 0
	v_addc_co_u32_e32 v27, vcc, 0, v25, vcc
	s_mov_b32 s23, 0x70000
	v_lshl_add_u64 v[22:23], s[26:27], 0, v[20:21]
	v_add_co_u32_e32 v24, vcc, s23, v24
	v_lshl_add_u64 v[22:23], v[22:23], 0, v[0:1]
	s_nop 0
	v_addc_co_u32_e32 v25, vcc, 0, v25, vcc
	v_add_co_u32_e32 v24, vcc, s93, v22
	v_lshlrev_b32_e32 v0, 7, v2
	s_nop 0
	v_addc_co_u32_e32 v25, vcc, 0, v23, vcc
	s_nop 0
	v_readfirstlane_b32 s58, v22
	v_readfirstlane_b32 s59, v23
	v_add_co_u32_e32 v24, vcc, s46, v22
	v_xor_b32_e32 v2, v2, v30
	s_nop 0
	v_addc_co_u32_e32 v25, vcc, 0, v23, vcc
	v_add_co_u32_e32 v22, vcc, s47, v22
	v_lshlrev_b32_e32 v2, 4, v2
	s_nop 0
	v_addc_co_u32_e32 v23, vcc, 0, v23, vcc
	v_and_or_b32 v0, v2, s33, v0
	v_lshlrev_b32_e32 v2, 7, v30
	v_and_b32_e32 v3, 15, v30
	v_and_b32_e32 v202, 0xffffc780, v2
	v_lshrrev_b32_e32 v2, 1, v30
	v_lshrrev_b32_e32 v31, 4, v30
	v_and_or_b32 v2, v2, 32, v3
	v_and_b32_e32 v23, 7, v30
	s_add_i32 s24, s29, s28
	v_bfe_u32 v22, v30, 4, 2
	v_lshlrev_b32_e32 v203, 7, v2
	v_bitop3_b32 v2, v31, v23, 3 bitop3:0x6c
	s_ashr_i32 s25, s24, 31
	v_lshlrev_b32_e32 v204, 4, v2
	v_bitop3_b32 v2, v22, v23, 4 bitop3:0x36
	s_lshl_b64 s[24:25], s[24:25], 19
	v_lshlrev_b32_e32 v205, 4, v2
	v_lshl_add_u64 v[2:3], s[24:25], 0, v[20:21]
	v_lshlrev_b32_e32 v22, 4, v23
	s_add_u32 s6, s12, s6
	v_or_b32_e32 v2, v2, v22
	v_or_b32_e32 v20, v20, v22
	s_addc_u32 s7, s13, s7
	v_mov_b32_e32 v144, 0
	v_lshl_add_u64 v[2:3], s[12:13], 0, v[2:3]
	v_lshl_add_u64 v[200:201], s[6:7], 0, v[20:21]
	s_mov_b64 s[6:7], 0
	v_mov_b32_e32 v145, v144
	v_mov_b32_e32 v146, v144
	v_mov_b32_e32 v147, v144
	s_waitcnt vmcnt(24)
	v_mov_b32_e32 v100, v144
	v_mov_b32_e32 v101, v144
	v_mov_b32_e32 v102, v144
	v_mov_b32_e32 v103, v144
	v_mov_b32_e32 v112, v144
	v_mov_b32_e32 v113, v144
	v_mov_b32_e32 v114, v144
	v_mov_b32_e32 v115, v144
	s_waitcnt vmcnt(23)
	v_mov_b32_e32 v116, v144
	v_mov_b32_e32 v117, v144
	v_mov_b32_e32 v118, v144
	v_mov_b32_e32 v119, v144
	s_waitcnt vmcnt(22)
	v_mov_b32_e32 v120, v144
	v_mov_b32_e32 v121, v144
	v_mov_b32_e32 v122, v144
	v_mov_b32_e32 v123, v144
	s_waitcnt vmcnt(20)
	v_mov_b32_e32 v128, v144
	v_mov_b32_e32 v129, v144
	v_mov_b32_e32 v130, v144
	v_mov_b32_e32 v131, v144
	v_mov_b32_e32 v76, v144
	v_mov_b32_e32 v77, v144
	v_mov_b32_e32 v78, v144
	v_mov_b32_e32 v79, v144
	v_mov_b32_e32 v72, v144
	v_mov_b32_e32 v73, v144
	v_mov_b32_e32 v74, v144
	v_mov_b32_e32 v75, v144
	v_mov_b32_e32 v64, v144
	v_mov_b32_e32 v65, v144
	v_mov_b32_e32 v66, v144
	v_mov_b32_e32 v67, v144
	v_mov_b32_e32 v68, v144
	v_mov_b32_e32 v69, v144
	v_mov_b32_e32 v70, v144
	v_mov_b32_e32 v71, v144
	v_mov_b32_e32 v20, v144
	v_mov_b32_e32 v21, v144
	v_mov_b32_e32 v22, v144
	v_mov_b32_e32 v23, v144
	v_mov_b32_e32 v24, v144
	v_mov_b32_e32 v25, v144
	v_mov_b32_e32 v26, v144
	v_mov_b32_e32 v27, v144
	v_mov_b32_e32 v28, v144
	v_mov_b32_e32 v29, v144
	v_mov_b32_e32 v30, v144
	v_mov_b32_e32 v31, v144
	v_mov_b32_e32 v32, v144
	v_mov_b32_e32 v33, v144
	v_mov_b32_e32 v34, v144
	v_mov_b32_e32 v35, v144
	v_mov_b32_e32 v36, v144
	v_mov_b32_e32 v37, v144
	v_mov_b32_e32 v38, v144
	v_mov_b32_e32 v39, v144
	v_mov_b32_e32 v40, v144
	v_mov_b32_e32 v41, v144
	v_mov_b32_e32 v42, v144
	v_mov_b32_e32 v43, v144
	v_mov_b32_e32 v44, v144
	v_mov_b32_e32 v45, v144
	v_mov_b32_e32 v46, v144
	v_mov_b32_e32 v47, v144
	v_mov_b32_e32 v48, v144
	v_mov_b32_e32 v49, v144
	v_mov_b32_e32 v50, v144
	v_mov_b32_e32 v51, v144
	v_mov_b32_e32 v52, v144
	v_mov_b32_e32 v53, v144
	v_mov_b32_e32 v54, v144
	v_mov_b32_e32 v55, v144
	v_mov_b32_e32 v56, v144
	v_mov_b32_e32 v57, v144
	v_mov_b32_e32 v58, v144
	v_mov_b32_e32 v59, v144
	v_mov_b32_e32 v60, v144
	v_mov_b32_e32 v61, v144
	v_mov_b32_e32 v62, v144
	v_mov_b32_e32 v63, v144
	v_mov_b32_e32 v80, v144
	v_mov_b32_e32 v81, v144
	v_mov_b32_e32 v82, v144
	v_mov_b32_e32 v83, v144
	v_mov_b32_e32 v84, v144
	v_mov_b32_e32 v85, v144
	v_mov_b32_e32 v86, v144
	v_mov_b32_e32 v87, v144
	v_mov_b32_e32 v88, v144
	v_mov_b32_e32 v89, v144
	v_mov_b32_e32 v90, v144
	v_mov_b32_e32 v91, v144
	v_mov_b32_e32 v92, v144
	v_mov_b32_e32 v93, v144
	v_mov_b32_e32 v94, v144
	v_mov_b32_e32 v95, v144
	v_mov_b32_e32 v96, v144
	v_mov_b32_e32 v97, v144
	v_mov_b32_e32 v98, v144
	v_mov_b32_e32 v99, v144
	v_mov_b32_e32 v104, v144
	v_mov_b32_e32 v105, v144
	v_mov_b32_e32 v106, v144
	v_mov_b32_e32 v107, v144
	v_mov_b32_e32 v108, v144
	v_mov_b32_e32 v109, v144
	v_mov_b32_e32 v110, v144
	v_mov_b32_e32 v111, v144
	v_mov_b32_e32 v124, v144
	v_mov_b32_e32 v125, v144
	v_mov_b32_e32 v126, v144
	v_mov_b32_e32 v127, v144
	v_mov_b32_e32 v132, v144
	v_mov_b32_e32 v133, v144
	v_mov_b32_e32 v134, v144
	v_mov_b32_e32 v135, v144
	v_mov_b32_e32 v136, v144
	v_mov_b32_e32 v137, v144
	v_mov_b32_e32 v138, v144
	v_mov_b32_e32 v139, v144
	v_mov_b32_e32 v140, v144
	v_mov_b32_e32 v141, v144
	v_mov_b32_e32 v142, v144
	v_mov_b32_e32 v143, v144
; template <int MI, bool SWAP, bool F8 = false>
; __device__ __forceinline__ void gemm_core(const bf16_t* __restrict__ A, int lda, const bf16_t* __restrict__ B, int ldb,
;                                           int K, char* smem, f32x4 (&acc)[MI][4]) {
;     ...
;   for (int kt = 0; kt < nk; ++kt) {
;     __syncthreads();
; #pragma unroll
;     for (int i = 0; i < MI; ++i) *(u32x4*)(smem + woff + i * 4096) = ra[i];
; #pragma unroll
;     for (int i = 0; i < 4; ++i) *(u32x4*)(smem + 32768 + woff + i * 4096) = rb[i];
;     __syncthreads();
;     if (kt + 1 < nk) {
; #pragma unroll
;       for (int i = 0; i < MI; ++i) ra[i] = *(const u32x4*)(ap + (size_t)(32 * i) * lda + (kt + 1) * 64);
; #pragma unroll
;       for (int i = 0; i < 4; ++i) rb[i] = *(const u32x4*)(bp + (size_t)(32 * i) * ldb + (kt + 1) * 64);
;     }
;     if (F8) {
;       const int c0 = (g ^ (li & 7)) << 4, c1 = ((4 + g) ^ (li & 7)) << 4;
;       i32x8 wf8[4];
; #pragma unroll
;       for (int j = 0; j < 4; ++j) {
;         const char* rp = smem + wrow + ((j & 1) * 16 + (j >> 1) * 64) * 128;
;         const u32x4 lo = *(const u32x4*)(rp + c0), hi = *(const u32x4*)(rp + c1);
;         wf8[j] = (i32x8){(int)lo.x, (int)lo.y, (int)lo.z, (int)lo.w, (int)hi.x, (int)hi.y, (int)hi.z, (int)hi.w};
;       }
; #pragma unroll
;       for (int i = 0; i < MI; ++i) {
;         const char* rp = smem + xrow + i * 2048;
;         const u32x4 lo = *(const u32x4*)(rp + c0), hi = *(const u32x4*)(rp + c1);
;         const i32x8 xf8 = {(int)lo.x, (int)lo.y, (int)lo.z, (int)lo.w, (int)hi.x, (int)hi.y, (int)hi.z, (int)hi.w};
; #pragma unroll
;         for (int j = 0; j < 4; ++j)
;           acc[i][j] = __builtin_amdgcn_mfma_scale_f32_16x16x128_f8f6f4(wf8[j], xf8, acc[i][j], 0, 0, 0, 0x77777777, 0, 0x7f7f7f7f);
;       }
;     } else {
; #pragma unroll
;     for (int kk = 0; kk < 2; ++kk) {
;       const int ch = ((kk * 4 + g) ^ (li & 7)) << 4;
;       bf16x8 xf[MI], wf[4];
; #pragma unroll
;       for (int j = 0; j < 4; ++j) wf[j] = *(const bf16x8*)(smem + wrow + ((j & 1) * 16 + (j >> 1) * 64) * 128 + ch);
; #pragma unroll
;       for (int i = 0; i < MI; ++i) xf[i] = *(const bf16x8*)(smem + xrow + i * 2048 + ch);
; #pragma unroll
;       for (int i = 0; i < MI; ++i)
; #pragma unroll
;         for (int j = 0; j < 4; ++j) {
.LBB0_819:
	v_add_u32_e32 v215, v203, v204
	s_barrier
	s_mov_b32 m0, s62
	s_nop 0
	global_load_lds_dwordx4 v252, s[56:57]
	s_add_u32 m0, s62, 0x1000
	s_nop 0
	global_load_lds_dwordx4 v253, s[56:57]
	s_add_u32 s56, s56, 0x20000
	s_addc_u32 s57, s57, 0
	s_add_u32 m0, s62, 0x2000
	s_nop 0
	global_load_lds_dwordx4 v252, s[56:57]
	s_add_u32 m0, s62, 0x3000
	s_nop 0
	global_load_lds_dwordx4 v253, s[56:57]
	s_add_u32 s56, s56, 0x20000
	s_addc_u32 s57, s57, 0
	s_add_u32 m0, s62, 0x4000
	s_nop 0
	global_load_lds_dwordx4 v252, s[56:57]
	s_add_u32 m0, s62, 0x5000
	s_nop 0
	global_load_lds_dwordx4 v253, s[56:57]
	s_add_u32 s56, s56, 0x20000
	s_addc_u32 s57, s57, 0
	s_add_u32 m0, s62, 0x6000
	s_nop 0
	global_load_lds_dwordx4 v252, s[56:57]
	s_add_u32 m0, s62, 0x7000
	s_nop 0
	global_load_lds_dwordx4 v253, s[56:57]
	s_sub_u32 s56, s56, 0x60000
	s_subb_u32 s57, s57, 0
	s_add_u32 m0, s62, 0x8000
	s_nop 0
	global_load_lds_dwordx4 v252, s[58:59]
	s_add_u32 m0, s62, 0x9000
	s_nop 0
	global_load_lds_dwordx4 v253, s[58:59]
	s_add_u32 s58, s58, 0x20000
	s_addc_u32 s59, s59, 0
	s_add_u32 m0, s62, 0xa000
	s_nop 0
	global_load_lds_dwordx4 v252, s[58:59]
	s_add_u32 m0, s62, 0xb000
	s_nop 0
	global_load_lds_dwordx4 v253, s[58:59]
	s_sub_u32 s58, s58, 0x20000
	s_subb_u32 s59, s59, 0
	v_add_u32_e32 v252, 0x80, v252
	v_add_u32_e32 v253, 0x80, v253
	s_waitcnt vmcnt(0)
	s_barrier
	v_add_u32_e32 v213, v202, v204
	ds_read_b128 v[148:151], v215 offset:32768
	ds_read_b128 v[152:155], v215 offset:34816
	ds_read_b128 v[156:159], v213
	ds_read_b128 v[160:163], v213 offset:2048
	ds_read_b128 v[164:167], v215 offset:40960
	ds_read_b128 v[168:171], v215 offset:43008
	s_waitcnt lgkmcnt(3)
	v_mfma_f32_16x16x32_bf16 v[140:143], v[148:151], v[156:159], v[140:143]
	v_add_u32_e32 v207, v203, v205
	v_add_u32_e32 v206, v202, v205
	v_mfma_f32_16x16x32_bf16 v[136:139], v[152:155], v[156:159], v[136:139]
	s_waitcnt lgkmcnt(1)
	v_mfma_f32_16x16x32_bf16 v[132:135], v[164:167], v[156:159], v[132:135]
	s_waitcnt lgkmcnt(0)
	v_mfma_f32_16x16x32_bf16 v[124:127], v[168:171], v[156:159], v[124:127]
	v_mfma_f32_16x16x32_bf16 v[108:111], v[148:151], v[160:163], v[108:111]
	v_mfma_f32_16x16x32_bf16 v[104:107], v[152:155], v[160:163], v[104:107]
	v_mfma_f32_16x16x32_bf16 v[96:99], v[164:167], v[160:163], v[96:99]
	v_mfma_f32_16x16x32_bf16 v[92:95], v[168:171], v[160:163], v[92:95]
	ds_read_b128 v[156:159], v213 offset:4096
	ds_read_b128 v[160:163], v213 offset:6144
	s_waitcnt lgkmcnt(1)
	v_mfma_f32_16x16x32_bf16 v[88:91], v[148:151], v[156:159], v[88:91]
	v_mfma_f32_16x16x32_bf16 v[84:87], v[152:155], v[156:159], v[84:87]
	v_mfma_f32_16x16x32_bf16 v[80:83], v[164:167], v[156:159], v[80:83]
	v_mfma_f32_16x16x32_bf16 v[60:63], v[168:171], v[156:159], v[60:63]
	s_waitcnt lgkmcnt(0)
	v_mfma_f32_16x16x32_bf16 v[56:59], v[148:151], v[160:163], v[56:59]
	v_mfma_f32_16x16x32_bf16 v[52:55], v[152:155], v[160:163], v[52:55]
	v_mfma_f32_16x16x32_bf16 v[48:51], v[164:167], v[160:163], v[48:51]
	v_mfma_f32_16x16x32_bf16 v[44:47], v[168:171], v[160:163], v[44:47]
	ds_read_b128 v[156:159], v213 offset:8192
	ds_read_b128 v[160:163], v213 offset:10240
	s_waitcnt lgkmcnt(1)
	v_mfma_f32_16x16x32_bf16 v[40:43], v[148:151], v[156:159], v[40:43]
	v_mfma_f32_16x16x32_bf16 v[36:39], v[152:155], v[156:159], v[36:39]
	v_mfma_f32_16x16x32_bf16 v[32:35], v[164:167], v[156:159], v[32:35]
	v_mfma_f32_16x16x32_bf16 v[28:31], v[168:171], v[156:159], v[28:31]
	s_waitcnt lgkmcnt(0)
	v_mfma_f32_16x16x32_bf16 v[24:27], v[148:151], v[160:163], v[24:27]
	v_mfma_f32_16x16x32_bf16 v[20:23], v[152:155], v[160:163], v[20:23]
	v_mfma_f32_16x16x32_bf16 v[68:71], v[164:167], v[160:163], v[68:71]
	v_mfma_f32_16x16x32_bf16 v[64:67], v[168:171], v[160:163], v[64:67]
	ds_read_b128 v[156:159], v213 offset:12288
	ds_read_b128 v[160:163], v213 offset:14336
	ds_read_b128 v[172:175], v207 offset:32768
	ds_read_b128 v[180:183], v207 offset:34816
	s_waitcnt lgkmcnt(3)
	v_mfma_f32_16x16x32_bf16 v[72:75], v[148:151], v[156:159], v[72:75]
	v_mfma_f32_16x16x32_bf16 v[76:79], v[152:155], v[156:159], v[76:79]
	v_mfma_f32_16x16x32_bf16 v[128:131], v[164:167], v[156:159], v[128:131]
	v_mfma_f32_16x16x32_bf16 v[120:123], v[168:171], v[156:159], v[120:123]
	s_waitcnt lgkmcnt(2)
	v_mfma_f32_16x16x32_bf16 v[116:119], v[148:151], v[160:163], v[116:119]
	v_mfma_f32_16x16x32_bf16 v[112:115], v[152:155], v[160:163], v[112:115]
	ds_read_b128 v[148:151], v206
	ds_read_b128 v[152:155], v206 offset:2048
	ds_read_b128 v[192:195], v207 offset:40960
	ds_read_b128 v[196:199], v207 offset:43008
	v_mfma_f32_16x16x32_bf16 v[100:103], v[164:167], v[160:163], v[100:103]
	v_mfma_f32_16x16x32_bf16 v[144:147], v[168:171], v[160:163], v[144:147]
	s_waitcnt lgkmcnt(3)
	v_mfma_f32_16x16x32_bf16 v[140:143], v[172:175], v[148:151], v[140:143]
	v_mfma_f32_16x16x32_bf16 v[136:139], v[180:183], v[148:151], v[136:139]
	s_waitcnt lgkmcnt(1)
	v_mfma_f32_16x16x32_bf16 v[132:135], v[192:195], v[148:151], v[132:135]
	s_waitcnt lgkmcnt(0)
	v_mfma_f32_16x16x32_bf16 v[124:127], v[196:199], v[148:151], v[124:127]
	v_mfma_f32_16x16x32_bf16 v[108:111], v[172:175], v[152:155], v[108:111]
	v_mfma_f32_16x16x32_bf16 v[104:107], v[180:183], v[152:155], v[104:107]
	v_mfma_f32_16x16x32_bf16 v[96:99], v[192:195], v[152:155], v[96:99]
	v_mfma_f32_16x16x32_bf16 v[92:95], v[196:199], v[152:155], v[92:95]
	ds_read_b128 v[148:151], v206 offset:4096
	ds_read_b128 v[152:155], v206 offset:6144
	s_waitcnt lgkmcnt(1)
; template <int MI, bool SWAP, bool F8 = false>
; __device__ __forceinline__ void gemm_core(const bf16_t* __restrict__ A, int lda, const bf16_t* __restrict__ B, int ldb,
;                                           int K, char* smem, f32x4 (&acc)[MI][4]) {
;     ...
;   for (int kt = 0; kt < nk; ++kt) {
;     __syncthreads();
; #pragma unroll
;     for (int i = 0; i < MI; ++i) *(u32x4*)(smem + woff + i * 4096) = ra[i];
; #pragma unroll
;     for (int i = 0; i < 4; ++i) *(u32x4*)(smem + 32768 + woff + i * 4096) = rb[i];
;     __syncthreads();
;     if (kt + 1 < nk) {
; #pragma unroll
;       for (int i = 0; i < MI; ++i) ra[i] = *(const u32x4*)(ap + (size_t)(32 * i) * lda + (kt + 1) * 64);
; #pragma unroll
;       for (int i = 0; i < 4; ++i) rb[i] = *(const u32x4*)(bp + (size_t)(32 * i) * ldb + (kt + 1) * 64);
;     }
;     if (F8) {
;       const int c0 = (g ^ (li & 7)) << 4, c1 = ((4 + g) ^ (li & 7)) << 4;
;       i32x8 wf8[4];
; #pragma unroll
;       for (int j = 0; j < 4; ++j) {
;         const char* rp = smem + wrow + ((j & 1) * 16 + (j >> 1) * 64) * 128;
;         const u32x4 lo = *(const u32x4*)(rp + c0), hi = *(const u32x4*)(rp + c1);
;         wf8[j] = (i32x8){(int)lo.x, (int)lo.y, (int)lo.z, (int)lo.w, (int)hi.x, (int)hi.y, (int)hi.z, (int)hi.w};
;       }
; #pragma unroll
;       for (int i = 0; i < MI; ++i) {
;         const char* rp = smem + xrow + i * 2048;
;         const u32x4 lo = *(const u32x4*)(rp + c0), hi = *(const u32x4*)(rp + c1);
;         const i32x8 xf8 = {(int)lo.x, (int)lo.y, (int)lo.z, (int)lo.w, (int)hi.x, (int)hi.y, (int)hi.z, (int)hi.w};
; #pragma unroll
;         for (int j = 0; j < 4; ++j)
;           acc[i][j] = __builtin_amdgcn_mfma_scale_f32_16x16x128_f8f6f4(wf8[j], xf8, acc[i][j], 0, 0, 0, 0x77777777, 0, 0x7f7f7f7f);
;       }
;     } else {
; #pragma unroll
;     for (int kk = 0; kk < 2; ++kk) {
;       const int ch = ((kk * 4 + g) ^ (li & 7)) << 4;
;       bf16x8 xf[MI], wf[4];
; #pragma unroll
;       for (int j = 0; j < 4; ++j) wf[j] = *(const bf16x8*)(smem + wrow + ((j & 1) * 16 + (j >> 1) * 64) * 128 + ch);
; #pragma unroll
;       for (int i = 0; i < MI; ++i) xf[i] = *(const bf16x8*)(smem + xrow + i * 2048 + ch);
; #pragma unroll
;       for (int i = 0; i < MI; ++i)
; #pragma unroll
;         for (int j = 0; j < 4; ++j) {
	v_mfma_f32_16x16x32_bf16 v[88:91], v[172:175], v[148:151], v[88:91]
	ds_read_b128 v[156:159], v206 offset:12288
	ds_read_b128 v[216:219], v206 offset:14336
	v_mfma_f32_16x16x32_bf16 v[84:87], v[180:183], v[148:151], v[84:87]
	v_mfma_f32_16x16x32_bf16 v[80:83], v[192:195], v[148:151], v[80:83]
	v_mfma_f32_16x16x32_bf16 v[60:63], v[196:199], v[148:151], v[60:63]
	ds_read_b128 v[148:151], v206 offset:8192
	s_waitcnt lgkmcnt(3)
	v_mfma_f32_16x16x32_bf16 v[56:59], v[172:175], v[152:155], v[56:59]
	v_mfma_f32_16x16x32_bf16 v[52:55], v[180:183], v[152:155], v[52:55]
	v_mfma_f32_16x16x32_bf16 v[48:51], v[192:195], v[152:155], v[48:51]
	v_mfma_f32_16x16x32_bf16 v[44:47], v[196:199], v[152:155], v[44:47]
	ds_read_b128 v[152:155], v206 offset:10240
	s_waitcnt lgkmcnt(1)
	v_mfma_f32_16x16x32_bf16 v[40:43], v[172:175], v[148:151], v[40:43]
	v_mfma_f32_16x16x32_bf16 v[36:39], v[180:183], v[148:151], v[36:39]
	v_mfma_f32_16x16x32_bf16 v[32:35], v[192:195], v[148:151], v[32:35]
	v_mfma_f32_16x16x32_bf16 v[28:31], v[196:199], v[148:151], v[28:31]
	s_waitcnt lgkmcnt(0)
	v_mfma_f32_16x16x32_bf16 v[24:27], v[172:175], v[152:155], v[24:27]
	v_mfma_f32_16x16x32_bf16 v[20:23], v[180:183], v[152:155], v[20:23]
	v_mfma_f32_16x16x32_bf16 v[68:71], v[192:195], v[152:155], v[68:71]
	v_mfma_f32_16x16x32_bf16 v[64:67], v[196:199], v[152:155], v[64:67]
	v_mfma_f32_16x16x32_bf16 v[72:75], v[172:175], v[156:159], v[72:75]
	v_mfma_f32_16x16x32_bf16 v[76:79], v[180:183], v[156:159], v[76:79]
	v_mfma_f32_16x16x32_bf16 v[128:131], v[192:195], v[156:159], v[128:131]
	v_mfma_f32_16x16x32_bf16 v[120:123], v[196:199], v[156:159], v[120:123]
	v_mfma_f32_16x16x32_bf16 v[116:119], v[172:175], v[216:219], v[116:119]
	v_mfma_f32_16x16x32_bf16 v[112:115], v[180:183], v[216:219], v[112:115]
	v_mfma_f32_16x16x32_bf16 v[100:103], v[192:195], v[216:219], v[100:103]
	v_mfma_f32_16x16x32_bf16 v[144:147], v[196:199], v[216:219], v[144:147]
	s_add_u32 s6, s6, 0x80
	s_addc_u32 s7, s7, 0
	s_cmpk_lg_i32 s6, 0x780
	s_cbranch_scc1 .LBB0_819
	s_barrier
	s_mov_b32 m0, s62
	s_nop 0
	global_load_lds_dwordx4 v252, s[56:57]
	s_add_u32 m0, s62, 0x1000
	s_nop 0
	global_load_lds_dwordx4 v253, s[56:57]
	s_add_u32 s56, s56, 0x20000
	s_addc_u32 s57, s57, 0
	s_add_u32 m0, s62, 0x2000
	s_nop 0
	global_load_lds_dwordx4 v252, s[56:57]
	s_add_u32 m0, s62, 0x3000
	s_nop 0
	global_load_lds_dwordx4 v253, s[56:57]
	s_add_u32 s56, s56, 0x20000
	s_addc_u32 s57, s57, 0
	s_add_u32 m0, s62, 0x4000
	s_nop 0
	global_load_lds_dwordx4 v252, s[56:57]
	s_add_u32 m0, s62, 0x5000
	s_nop 0
	global_load_lds_dwordx4 v253, s[56:57]
	s_add_u32 s56, s56, 0x20000
	s_addc_u32 s57, s57, 0
	s_add_u32 m0, s62, 0x6000
	s_nop 0
	global_load_lds_dwordx4 v252, s[56:57]
	s_add_u32 m0, s62, 0x7000
	s_nop 0
	global_load_lds_dwordx4 v253, s[56:57]
	s_sub_u32 s56, s56, 0x60000
	s_subb_u32 s57, s57, 0
	s_add_u32 m0, s62, 0x8000
	s_nop 0
	global_load_lds_dwordx4 v252, s[58:59]
	s_add_u32 m0, s62, 0x9000
	s_nop 0
	global_load_lds_dwordx4 v253, s[58:59]
	s_add_u32 s58, s58, 0x20000
	s_addc_u32 s59, s59, 0
	s_add_u32 m0, s62, 0xa000
	s_nop 0
	global_load_lds_dwordx4 v252, s[58:59]
	s_add_u32 m0, s62, 0xb000
	s_nop 0
	global_load_lds_dwordx4 v253, s[58:59]
	s_sub_u32 s58, s58, 0x20000
	s_subb_u32 s59, s59, 0
	s_waitcnt vmcnt(0)
	s_barrier
	ds_read_b128 v[148:151], v215 offset:32768
	ds_read_b128 v[152:155], v215 offset:34816
	ds_read_b128 v[156:159], v215 offset:40960
	ds_read_b128 v[160:163], v215 offset:43008
	ds_read_b128 v[164:167], v213
	ds_read_b128 v[168:171], v213 offset:2048
	ds_read_b128 v[172:175], v213 offset:4096
	ds_read_b128 v[176:179], v213 offset:6144
	ds_read_b128 v[180:183], v213 offset:8192
	ds_read_b128 v[184:187], v213 offset:10240
	ds_read_b128 v[188:191], v213 offset:12288
	ds_read_b128 v[192:195], v213 offset:14336
	s_waitcnt lgkmcnt(7)
	v_mfma_f32_16x16x32_bf16 v[132:135], v[156:159], v[164:167], v[132:135]
	s_lshl_b64 s[0:1], s[0:1], 2
	s_add_u32 s0, s16, s0
	s_addc_u32 s1, s17, s1
	v_mfma_f32_16x16x32_bf16 v[140:143], v[148:151], v[164:167], v[140:143]
	s_lshl_b32 s6, s22, 2
	s_add_u32 s0, s0, s6
	s_addc_u32 s1, s1, 0
	v_mfma_f32_16x16x32_bf16 v[136:139], v[152:155], v[164:167], v[136:139]
	s_add_i32 s21, s21, s78
	s_add_i32 s20, s20, s71
	s_add_i32 s19, s19, s76
	v_mfma_f32_16x16x32_bf16 v[124:127], v[160:163], v[164:167], v[124:127]
	s_cmpk_gt_i32 s21, 0x1ff
	s_waitcnt lgkmcnt(6)
	v_mfma_f32_16x16x32_bf16 v[108:111], v[148:151], v[168:171], v[108:111]
	v_mfma_f32_16x16x32_bf16 v[104:107], v[152:155], v[168:171], v[104:107]
	v_mfma_f32_16x16x32_bf16 v[96:99], v[156:159], v[168:171], v[96:99]
	v_mfma_f32_16x16x32_bf16 v[92:95], v[160:163], v[168:171], v[92:95]
	s_waitcnt lgkmcnt(5)
	v_mfma_f32_16x16x32_bf16 v[88:91], v[148:151], v[172:175], v[88:91]
	v_mfma_f32_16x16x32_bf16 v[84:87], v[152:155], v[172:175], v[84:87]
	v_mfma_f32_16x16x32_bf16 v[80:83], v[156:159], v[172:175], v[80:83]
	v_mfma_f32_16x16x32_bf16 v[60:63], v[160:163], v[172:175], v[60:63]
	s_waitcnt lgkmcnt(4)
	v_mfma_f32_16x16x32_bf16 v[56:59], v[148:151], v[176:179], v[56:59]
	v_mfma_f32_16x16x32_bf16 v[52:55], v[152:155], v[176:179], v[52:55]
	v_mfma_f32_16x16x32_bf16 v[48:51], v[156:159], v[176:179], v[48:51]
	v_mfma_f32_16x16x32_bf16 v[44:47], v[160:163], v[176:179], v[44:47]
	s_waitcnt lgkmcnt(3)
	v_mfma_f32_16x16x32_bf16 v[40:43], v[148:151], v[180:183], v[40:43]
	v_mfma_f32_16x16x32_bf16 v[36:39], v[152:155], v[180:183], v[36:39]
	v_mfma_f32_16x16x32_bf16 v[32:35], v[156:159], v[180:183], v[32:35]
	v_mfma_f32_16x16x32_bf16 v[28:31], v[160:163], v[180:183], v[28:31]
	s_waitcnt lgkmcnt(2)
; template <int MI, bool SWAP, bool F8 = false>
; __device__ __forceinline__ void gemm_core(const bf16_t* __restrict__ A, int lda, const bf16_t* __restrict__ B, int ldb,
;                                           int K, char* smem, f32x4 (&acc)[MI][4]) {
;     ...
; #pragma unroll
;     for (int kk = 0; kk < 2; ++kk) {
;       const int ch = ((kk * 4 + g) ^ (li & 7)) << 4;
;       bf16x8 xf[MI], wf[4];
; #pragma unroll
;       for (int j = 0; j < 4; ++j) wf[j] = *(const bf16x8*)(smem + wrow + ((j & 1) * 16 + (j >> 1) * 64) * 128 + ch);
; #pragma unroll
;       for (int i = 0; i < MI; ++i) xf[i] = *(const bf16x8*)(smem + xrow + i * 2048 + ch);
; #pragma unroll
;       for (int i = 0; i < MI; ++i)
; #pragma unroll
;         for (int j = 0; j < 4; ++j) {
;           if (SWAP) acc[i][j] = __builtin_amdgcn_mfma_f32_16x16x32_bf16(xf[i], wf[j], acc[i][j], 0, 0, 0);
;           else acc[i][j] = __builtin_amdgcn_mfma_f32_16x16x32_bf16(wf[j], xf[i], acc[i][j], 0, 0, 0);
;         }
; template <bool ACCUM, int MI>
; __device__ void gemm_tile_f32(const bf16_t* A, int lda, const bf16_t* B, int ldb, int K, float* C, int ldc, char* smem) {
;     ...
; #pragma unroll
;   for (int i = 0; i < MI; ++i)
; #pragma unroll
;     for (int j = 0; j < 4; ++j) {
;       f32x4* cp = (f32x4*)(C + (size_t)MROW(i) * ldc + NCOL(j));
;       f32x4 v = acc[i][j];
;       if (ACCUM) v += *cp;
;       *cp = v;
;     }
	v_mfma_f32_16x16x32_bf16 v[24:27], v[148:151], v[184:187], v[24:27]
	v_mfma_f32_16x16x32_bf16 v[20:23], v[152:155], v[184:187], v[20:23]
	v_mfma_f32_16x16x32_bf16 v[164:167], v[156:159], v[184:187], v[68:71]
	v_mfma_f32_16x16x32_bf16 v[168:171], v[160:163], v[184:187], v[64:67]
	s_waitcnt lgkmcnt(1)
	v_mfma_f32_16x16x32_bf16 v[172:175], v[148:151], v[188:191], v[72:75]
	v_mfma_f32_16x16x32_bf16 v[176:179], v[152:155], v[188:191], v[76:79]
	v_mfma_f32_16x16x32_bf16 v[180:183], v[156:159], v[188:191], v[128:131]
	v_mfma_f32_16x16x32_bf16 v[184:187], v[160:163], v[188:191], v[120:123]
	s_waitcnt lgkmcnt(0)
	v_mfma_f32_16x16x32_bf16 v[148:151], v[148:151], v[192:195], v[116:119]
	v_mfma_f32_16x16x32_bf16 v[152:155], v[152:155], v[192:195], v[112:115]
	v_mfma_f32_16x16x32_bf16 v[156:159], v[156:159], v[192:195], v[100:103]
	v_mfma_f32_16x16x32_bf16 v[144:147], v[160:163], v[192:195], v[144:147]
	ds_read_b128 v[160:163], v207 offset:32768
	ds_read_b128 v[188:191], v207 offset:34816
	ds_read_b128 v[192:195], v207 offset:40960
	ds_read_b128 v[196:199], v207 offset:43008
	ds_read_b128 v[64:67], v206
	ds_read_b128 v[68:71], v206 offset:2048
	ds_read_b128 v[72:75], v206 offset:4096
	ds_read_b128 v[76:79], v206 offset:6144
	ds_read_b128 v[200:203], v206 offset:8192
	ds_read_b128 v[216:219], v206 offset:10240
	ds_read_b128 v[220:223], v206 offset:12288
	ds_read_b128 v[204:207], v206 offset:14336
	s_waitcnt lgkmcnt(7)
	v_mfma_f32_16x16x32_bf16 v[224:227], v[192:195], v[64:67], v[132:135]
	s_nop 2
	v_mov_b32_e32 v132, v208
	v_mfma_f32_16x16x32_bf16 v[228:231], v[196:199], v[64:67], v[124:127]
	v_lshrrev_b32_e32 v0, 1, v132
	v_and_b32_e32 v2, 0xffffff8f, v132
	v_and_b32_e32 v0, 32, v0
	v_lshrrev_b32_e32 v3, 2, v132
	v_and_or_b32 v0, v3, 12, v0
	v_ashrrev_i32_e32 v3, 31, v2
	v_lshlrev_b64 v[134:135], 12, v[2:3]
	v_lshl_add_u64 v[134:135], s[0:1], 0, v[134:135]
	v_lshlrev_b32_e32 v0, 2, v0
	s_waitcnt lgkmcnt(6)
	v_mfma_f32_16x16x32_bf16 v[128:131], v[160:163], v[68:71], v[108:111]
	v_mfma_f32_16x16x32_bf16 v[124:127], v[188:191], v[68:71], v[104:107]
	s_waitcnt lgkmcnt(5)
	v_mfma_f32_16x16x32_bf16 v[112:115], v[160:163], v[72:75], v[88:91]
	v_mfma_f32_16x16x32_bf16 v[108:111], v[188:191], v[72:75], v[84:87]
	v_mfma_f32_16x16x32_bf16 v[104:107], v[192:195], v[72:75], v[80:83]
	v_mfma_f32_16x16x32_bf16 v[100:103], v[196:199], v[72:75], v[60:63]
	s_waitcnt lgkmcnt(3)
	v_mfma_f32_16x16x32_bf16 v[72:75], v[192:195], v[200:203], v[32:35]
	s_waitcnt lgkmcnt(0)
	v_mfma_f32_16x16x32_bf16 v[32:35], v[160:163], v[204:207], v[148:151]
	s_nop 2
	v_lshl_add_u64 v[148:149], v[134:135], 0, v[0:1]
	v_mfma_f32_16x16x32_bf16 v[60:63], v[188:191], v[216:219], v[20:23]
	v_mfma_f32_16x16x32_bf16 v[20:23], v[196:199], v[204:207], v[144:147]
	s_nop 2
	global_load_dwordx4 v[144:147], v[148:149], off
	v_mfma_f32_16x16x32_bf16 v[140:143], v[160:163], v[64:67], v[140:143]
	v_mfma_f32_16x16x32_bf16 v[136:139], v[188:191], v[64:67], v[136:139]
	v_mfma_f32_16x16x32_bf16 v[120:123], v[192:195], v[68:71], v[96:99]
	s_waitcnt vmcnt(0)
	s_nop 4
	v_pk_add_f32 v[142:143], v[142:143], v[146:147]
	v_pk_add_f32 v[140:141], v[140:141], v[144:145]
	global_store_dwordx4 v[148:149], v[140:143], off
	global_load_dwordx4 v[140:143], v[148:149], off offset:64
	v_mfma_f32_16x16x32_bf16 v[116:119], v[196:199], v[68:71], v[92:95]
	s_waitcnt vmcnt(0)
	v_pk_add_f32 v[138:139], v[138:139], v[142:143]
	v_pk_add_f32 v[136:137], v[136:137], v[140:141]
	global_store_dwordx4 v[148:149], v[136:139], off offset:64
	global_load_dwordx4 v[134:137], v[148:149], off offset:256
	v_mfma_f32_16x16x32_bf16 v[96:99], v[160:163], v[76:79], v[56:59]
	s_waitcnt vmcnt(0)
	v_pk_add_f32 v[136:137], v[226:227], v[136:137]
	v_pk_add_f32 v[134:135], v[224:225], v[134:135]
	global_store_dwordx4 v[148:149], v[134:137], off offset:256
	global_load_dwordx4 v[134:137], v[148:149], off offset:320
	v_mfma_f32_16x16x32_bf16 v[92:95], v[188:191], v[76:79], v[52:55]
	s_waitcnt vmcnt(0)
	v_pk_add_f32 v[136:137], v[230:231], v[136:137]
	v_pk_add_f32 v[134:135], v[228:229], v[134:135]
	global_store_dwordx4 v[148:149], v[134:137], off offset:320
	v_mfma_f32_16x16x32_bf16 v[88:91], v[192:195], v[76:79], v[48:51]
	s_nop 0
	v_or_b32_e32 v134, 16, v2
	v_ashrrev_i32_e32 v135, 31, v134
	v_lshlrev_b64 v[134:135], 12, v[134:135]
	v_lshl_add_u64 v[134:135], s[0:1], 0, v[134:135]
	v_lshl_add_u64 v[138:139], v[134:135], 0, v[0:1]
	global_load_dwordx4 v[134:137], v[138:139], off
	v_mfma_f32_16x16x32_bf16 v[84:87], v[196:199], v[76:79], v[44:47]
	s_waitcnt vmcnt(0)
	v_pk_add_f32 v[130:131], v[130:131], v[136:137]
	v_pk_add_f32 v[128:129], v[128:129], v[134:135]
	global_store_dwordx4 v[138:139], v[128:131], off
	global_load_dwordx4 v[128:131], v[138:139], off offset:64
	v_mfma_f32_16x16x32_bf16 v[80:83], v[160:163], v[200:203], v[40:43]
	s_waitcnt vmcnt(0)
	v_pk_add_f32 v[126:127], v[126:127], v[130:131]
	v_pk_add_f32 v[124:125], v[124:125], v[128:129]
	global_store_dwordx4 v[138:139], v[124:127], off offset:64
	global_load_dwordx4 v[124:127], v[138:139], off offset:256
	v_mfma_f32_16x16x32_bf16 v[76:79], v[188:191], v[200:203], v[36:39]
	s_waitcnt vmcnt(0)
	v_pk_add_f32 v[122:123], v[122:123], v[126:127]
	v_pk_add_f32 v[120:121], v[120:121], v[124:125]
	global_store_dwordx4 v[138:139], v[120:123], off offset:256
	global_load_dwordx4 v[120:123], v[138:139], off offset:320
	v_mfma_f32_16x16x32_bf16 v[68:71], v[196:199], v[200:203], v[28:31]
	s_waitcnt vmcnt(0)
; template <bool ACCUM, int MI>
; __device__ void gemm_tile_f32(const bf16_t* A, int lda, const bf16_t* B, int ldb, int K, float* C, int ldc, char* smem) {
;     ...
; #pragma unroll
;   for (int i = 0; i < MI; ++i)
; #pragma unroll
;     for (int j = 0; j < 4; ++j) {
;       f32x4* cp = (f32x4*)(C + (size_t)MROW(i) * ldc + NCOL(j));
;       f32x4 v = acc[i][j];
;       if (ACCUM) v += *cp;
;       *cp = v;
;     }
	v_pk_add_f32 v[118:119], v[118:119], v[122:123]
	v_pk_add_f32 v[116:117], v[116:117], v[120:121]
	global_store_dwordx4 v[138:139], v[116:119], off offset:320
	v_mfma_f32_16x16x32_bf16 v[64:67], v[160:163], v[216:219], v[24:27]
	s_nop 0
	v_or_b32_e32 v116, 32, v2
	v_ashrrev_i32_e32 v117, 31, v116
	v_lshlrev_b64 v[116:117], 12, v[116:117]
	v_lshl_add_u64 v[116:117], s[0:1], 0, v[116:117]
	v_lshl_add_u64 v[120:121], v[116:117], 0, v[0:1]
	global_load_dwordx4 v[116:119], v[120:121], off
	v_mfma_f32_16x16x32_bf16 v[56:59], v[192:195], v[216:219], v[164:167]
	s_waitcnt vmcnt(0)
	v_pk_add_f32 v[114:115], v[114:115], v[118:119]
	v_pk_add_f32 v[112:113], v[112:113], v[116:117]
	global_store_dwordx4 v[120:121], v[112:115], off
	global_load_dwordx4 v[112:115], v[120:121], off offset:64
	v_mfma_f32_16x16x32_bf16 v[52:55], v[196:199], v[216:219], v[168:171]
	s_waitcnt vmcnt(0)
	v_pk_add_f32 v[110:111], v[110:111], v[114:115]
	v_pk_add_f32 v[108:109], v[108:109], v[112:113]
	global_store_dwordx4 v[120:121], v[108:111], off offset:64
	global_load_dwordx4 v[108:111], v[120:121], off offset:256
	v_mfma_f32_16x16x32_bf16 v[48:51], v[160:163], v[220:223], v[172:175]
	s_waitcnt vmcnt(0)
	v_pk_add_f32 v[106:107], v[106:107], v[110:111]
	v_pk_add_f32 v[104:105], v[104:105], v[108:109]
	global_store_dwordx4 v[120:121], v[104:107], off offset:256
	global_load_dwordx4 v[104:107], v[120:121], off offset:320
	v_mfma_f32_16x16x32_bf16 v[44:47], v[188:191], v[220:223], v[176:179]
	s_waitcnt vmcnt(0)
	v_pk_add_f32 v[102:103], v[102:103], v[106:107]
	v_pk_add_f32 v[100:101], v[100:101], v[104:105]
	global_store_dwordx4 v[120:121], v[100:103], off offset:320
	v_mfma_f32_16x16x32_bf16 v[40:43], v[192:195], v[220:223], v[180:183]
	s_nop 0
	v_or_b32_e32 v100, 48, v2
	v_ashrrev_i32_e32 v101, 31, v100
	v_lshlrev_b64 v[100:101], 12, v[100:101]
	v_lshl_add_u64 v[100:101], s[0:1], 0, v[100:101]
	v_lshl_add_u64 v[104:105], v[100:101], 0, v[0:1]
	global_load_dwordx4 v[100:103], v[104:105], off
	v_mfma_f32_16x16x32_bf16 v[36:39], v[196:199], v[220:223], v[184:187]
	s_waitcnt vmcnt(0)
	v_pk_add_f32 v[98:99], v[98:99], v[102:103]
	v_pk_add_f32 v[96:97], v[96:97], v[100:101]
	global_store_dwordx4 v[104:105], v[96:99], off
	global_load_dwordx4 v[96:99], v[104:105], off offset:64
	v_mfma_f32_16x16x32_bf16 v[28:31], v[188:191], v[204:207], v[152:155]
	s_waitcnt vmcnt(0)
	v_pk_add_f32 v[94:95], v[94:95], v[98:99]
	v_pk_add_f32 v[92:93], v[92:93], v[96:97]
	global_store_dwordx4 v[104:105], v[92:95], off offset:64
	global_load_dwordx4 v[92:95], v[104:105], off offset:256
	v_mfma_f32_16x16x32_bf16 v[24:27], v[192:195], v[204:207], v[156:159]
	s_waitcnt vmcnt(0)
	v_pk_add_f32 v[90:91], v[90:91], v[94:95]
	v_pk_add_f32 v[88:89], v[88:89], v[92:93]
	global_store_dwordx4 v[104:105], v[88:91], off offset:256
	global_load_dwordx4 v[88:91], v[104:105], off offset:320
	s_waitcnt vmcnt(0)
	v_pk_add_f32 v[86:87], v[86:87], v[90:91]
	v_pk_add_f32 v[84:85], v[84:85], v[88:89]
	global_store_dwordx4 v[104:105], v[84:87], off offset:320
	s_nop 1
	v_or_b32_e32 v84, 64, v2
	v_ashrrev_i32_e32 v85, 31, v84
	v_lshlrev_b64 v[84:85], 12, v[84:85]
	v_lshl_add_u64 v[84:85], s[0:1], 0, v[84:85]
	v_lshl_add_u64 v[88:89], v[84:85], 0, v[0:1]
	global_load_dwordx4 v[84:87], v[88:89], off
	s_waitcnt vmcnt(0)
	v_pk_add_f32 v[82:83], v[82:83], v[86:87]
	v_pk_add_f32 v[80:81], v[80:81], v[84:85]
	global_store_dwordx4 v[88:89], v[80:83], off
	global_load_dwordx4 v[80:83], v[88:89], off offset:64
	s_waitcnt vmcnt(0)
; template <bool ACCUM, int MI>
; __device__ void gemm_tile_f32(const bf16_t* A, int lda, const bf16_t* B, int ldb, int K, float* C, int ldc, char* smem) {
;     ...
; #pragma unroll
;   for (int i = 0; i < MI; ++i)
; #pragma unroll
;     for (int j = 0; j < 4; ++j) {
;       f32x4* cp = (f32x4*)(C + (size_t)MROW(i) * ldc + NCOL(j));
;       f32x4 v = acc[i][j];
;       if (ACCUM) v += *cp;
;       *cp = v;
;     }
	v_pk_add_f32 v[78:79], v[78:79], v[82:83]
	v_pk_add_f32 v[76:77], v[76:77], v[80:81]
	global_store_dwordx4 v[88:89], v[76:79], off offset:64
	global_load_dwordx4 v[76:79], v[88:89], off offset:256
	s_waitcnt vmcnt(0)
	v_pk_add_f32 v[74:75], v[74:75], v[78:79]
	v_pk_add_f32 v[72:73], v[72:73], v[76:77]
	global_store_dwordx4 v[88:89], v[72:75], off offset:256
	global_load_dwordx4 v[72:75], v[88:89], off offset:320
	s_waitcnt vmcnt(0)
	v_pk_add_f32 v[70:71], v[70:71], v[74:75]
	v_pk_add_f32 v[68:69], v[68:69], v[72:73]
	global_store_dwordx4 v[88:89], v[68:71], off offset:320
	s_nop 1
	v_or_b32_e32 v68, 0x50, v2
	v_ashrrev_i32_e32 v69, 31, v68
	v_lshlrev_b64 v[68:69], 12, v[68:69]
	v_lshl_add_u64 v[68:69], s[0:1], 0, v[68:69]
	v_lshl_add_u64 v[72:73], v[68:69], 0, v[0:1]
	global_load_dwordx4 v[68:71], v[72:73], off
	v_or_b32_e32 v2, 0x60, v2
	v_ashrrev_i32_e32 v3, 31, v2
	v_lshlrev_b64 v[2:3], 12, v[2:3]
	v_lshl_add_u64 v[2:3], s[0:1], 0, v[2:3]
	v_lshl_add_u64 v[2:3], v[2:3], 0, v[0:1]
	s_waitcnt vmcnt(0)
	v_pk_add_f32 v[66:67], v[66:67], v[70:71]
	v_pk_add_f32 v[64:65], v[64:65], v[68:69]
	global_store_dwordx4 v[72:73], v[64:67], off
	global_load_dwordx4 v[64:67], v[72:73], off offset:64
	s_waitcnt vmcnt(0)
	v_pk_add_f32 v[62:63], v[62:63], v[66:67]
	v_pk_add_f32 v[60:61], v[60:61], v[64:65]
	global_store_dwordx4 v[72:73], v[60:63], off offset:64
	global_load_dwordx4 v[60:63], v[72:73], off offset:256
	s_waitcnt vmcnt(0)
	v_pk_add_f32 v[58:59], v[58:59], v[62:63]
	v_pk_add_f32 v[56:57], v[56:57], v[60:61]
	global_store_dwordx4 v[72:73], v[56:59], off offset:256
	global_load_dwordx4 v[56:59], v[72:73], off offset:320
	s_waitcnt vmcnt(0)
	v_pk_add_f32 v[54:55], v[54:55], v[58:59]
	v_pk_add_f32 v[52:53], v[52:53], v[56:57]
	global_store_dwordx4 v[72:73], v[52:55], off offset:320
	global_load_dwordx4 v[52:55], v[2:3], off
	s_waitcnt vmcnt(0)
	v_pk_add_f32 v[50:51], v[50:51], v[54:55]
	v_pk_add_f32 v[48:49], v[48:49], v[52:53]
	global_store_dwordx4 v[2:3], v[48:51], off
	global_load_dwordx4 v[48:51], v[2:3], off offset:64
	s_waitcnt vmcnt(0)
	v_pk_add_f32 v[46:47], v[46:47], v[50:51]
	v_pk_add_f32 v[44:45], v[44:45], v[48:49]
	global_store_dwordx4 v[2:3], v[44:47], off offset:64
	global_load_dwordx4 v[44:47], v[2:3], off offset:256
	s_waitcnt vmcnt(0)
	v_pk_add_f32 v[42:43], v[42:43], v[46:47]
	v_pk_add_f32 v[40:41], v[40:41], v[44:45]
	global_store_dwordx4 v[2:3], v[40:43], off offset:256
	global_load_dwordx4 v[40:43], v[2:3], off offset:320
	s_waitcnt vmcnt(0)
	v_pk_add_f32 v[38:39], v[38:39], v[42:43]
	v_pk_add_f32 v[36:37], v[36:37], v[40:41]
	global_store_dwordx4 v[2:3], v[36:39], off offset:320
	v_or_b32_e32 v2, 0x70, v132
	v_ashrrev_i32_e32 v3, 31, v2
	v_lshlrev_b64 v[2:3], 12, v[2:3]
	v_lshl_add_u64 v[2:3], s[0:1], 0, v[2:3]
	v_lshl_add_u64 v[2:3], v[2:3], 0, v[0:1]
	global_load_dwordx4 v[36:39], v[2:3], off
	s_waitcnt vmcnt(0)
	v_pk_add_f32 v[34:35], v[34:35], v[38:39]
	v_pk_add_f32 v[32:33], v[32:33], v[36:37]
	global_store_dwordx4 v[2:3], v[32:35], off
	global_load_dwordx4 v[32:35], v[2:3], off offset:64
	s_waitcnt vmcnt(0)
	v_pk_add_f32 v[30:31], v[30:31], v[34:35]
	v_pk_add_f32 v[28:29], v[28:29], v[32:33]
	global_store_dwordx4 v[2:3], v[28:31], off offset:64
	global_load_dwordx4 v[28:31], v[2:3], off offset:256
	s_waitcnt vmcnt(0)
	v_pk_add_f32 v[26:27], v[26:27], v[30:31]
	v_pk_add_f32 v[24:25], v[24:25], v[28:29]
	global_store_dwordx4 v[2:3], v[24:27], off offset:256
	global_load_dwordx4 v[24:27], v[2:3], off offset:320
	s_waitcnt vmcnt(0)
	v_pk_add_f32 v[22:23], v[22:23], v[26:27]
	v_pk_add_f32 v[20:21], v[20:21], v[24:25]
	global_store_dwordx4 v[2:3], v[20:23], off offset:320
	s_cbranch_scc0 .LBB0_818

; __device__ __forceinline__ int otid() { int t = threadIdx.x; asm volatile("" : "+v"(t)); return t; }
; template <int MI, bool SWAP, bool F8 = false>
; __device__ __forceinline__ void gemm_core(const bf16_t* __restrict__ A, int lda, const bf16_t* __restrict__ B, int ldb,
;                                           int K, char* smem, f32x4 (&acc)[MI][4]) {
;   const int tid = otid(), lane = tid & 63, w = tid >> 6, wm = w >> 1, wn = w & 1;
;   const int lr = tid >> 3, lc = tid & 7;
;   const int li = lane & 15, g = lane >> 4;
;   u32x4 ra[MI], rb[4];
;   const bf16_t* ap = A + (size_t)lr * lda + lc * 8;
;   const bf16_t* bp = B + (size_t)lr * ldb + lc * 8;
; #pragma unroll
;   for (int i = 0; i < MI; ++i)
; #pragma unroll
;     for (int j = 0; j < 4; ++j) acc[i][j] = (f32x4){0.f, 0.f, 0.f, 0.f};
;   const int nk = K >> 6;
; #pragma unroll
;   for (int i = 0; i < MI; ++i) ra[i] = *(const u32x4*)(ap + (size_t)(32 * i) * lda);
; #pragma unroll
;   for (int i = 0; i < 4; ++i) rb[i] = *(const u32x4*)(bp + (size_t)(32 * i) * ldb);
;   const int woff = lr * 128 + ((lc ^ (lr & 7)) << 4);
;   const int xrow = (wm * 16 * MI + li) * 128;
;   const int wrow = 32768 + (wn * 32 + li) * 128;
; __global__ void __launch_bounds__(256, 2) fwd_kernel(P p) {
;     ...
;       for (int it = blockIdx.x; it < 64 * 16; it += G) {
;         const int tm = (it & 7) * 8 + ((it >> 3) >> 4), tn = (it >> 3) & 15;
;         gemm_tile_bf16<8, true>((const bf16_t*)(ws + OFF_AO + (32ull << 20)) + (size_t)tm * 256 * 512, 512,
;                        (const bf16_t*)(ws + OFF_WPQ) + ((size_t)layer * 2048 + tn * 128) * 512, 512, 512,
;                        SCB + (size_t)tm * 256 * 2048 + tn * 128, 2048, smem);
.LBB0_943:
	s_lshl_b32 s6, s14, 10
	s_and_b32 s66, s6, 0x1e0000
	s_lshl_b32 s6, s18, 3
	s_and_b32 s6, s6, 56
	s_ashr_i32 s23, s18, 7
	s_add_i32 s6, s6, s23
	s_ashr_i32 s7, s6, 31
	s_waitcnt vmcnt(15)
	v_mov_b32_e32 v36, v208
	s_and_b32 s22, s15, 56
	s_lshl_b64 s[8:9], s[6:7], 18
	s_add_u32 s8, s10, s8
	v_ashrrev_i32_e32 v2, 3, v36
	v_ashrrev_i32_e32 v3, 31, v2
	s_addc_u32 s9, s11, s9
	v_lshlrev_b64 v[32:33], 10, v[2:3]
	v_lshlrev_b32_e32 v0, 4, v36
	v_lshl_add_u64 v[20:21], s[8:9], 0, v[32:33]
	v_and_b32_e32 v0, 0x70, v0
	v_lshl_add_u64 v[30:31], v[20:21], 0, v[0:1]
	s_mov_b32 s8, 0x8000
	v_add_co_u32_e32 v20, vcc, s8, v30
	s_lshl_b32 s19, s18, 4
	s_nop 0
	v_addc_co_u32_e32 v21, vcc, 0, v31, vcc
	v_lshrrev_b32_e32 v254, 3, v208
	v_and_b32_e32 v254, 7, v254
	v_xor_b32_e32 v252, v254, v208
	v_and_b32_e32 v252, 7, v252
	v_lshlrev_b32_e32 v252, 4, v252
	v_lshl_or_b32 v252, v254, 10, v252
	v_add_u32_e32 v253, 0x8000, v252
	v_lshrrev_b32_e32 v254, 6, v208
	s_nop 0
	v_readfirstlane_b32 s62, v254
	s_lshl_b32 s62, s62, 10
	v_readfirstlane_b32 s56, v30
	v_readfirstlane_b32 s57, v31
	v_add_co_u32_e32 v20, vcc, s93, v30
	s_and_b32 s19, s19, 0x780
	s_nop 0
	v_addc_co_u32_e32 v21, vcc, 0, v31, vcc
	s_mov_b32 s9, 0x18000
	s_lshl_b32 s20, s19, 10
	v_add_co_u32_e32 v22, vcc, s9, v30
	s_add_u32 s20, s16, s20
	s_nop 0
	v_addc_co_u32_e32 v23, vcc, 0, v31, vcc
	s_addc_u32 s21, s17, 0
	v_add_co_u32_e32 v20, vcc, s46, v30
	v_lshl_add_u64 v[28:29], s[20:21], 0, v[32:33]
	s_nop 0
	v_addc_co_u32_e32 v21, vcc, 0, v31, vcc
	s_mov_b32 s20, 0x28000
	v_add_co_u32_e32 v24, vcc, s20, v30
	s_mov_b32 s20, 0x38000
	s_nop 0
	v_addc_co_u32_e32 v25, vcc, 0, v31, vcc
	v_add_co_u32_e32 v34, vcc, s47, v30
	v_lshl_add_u64 v[28:29], v[28:29], 0, v[0:1]
	s_nop 0
	v_addc_co_u32_e32 v35, vcc, 0, v31, vcc
	v_add_co_u32_e32 v30, vcc, s20, v30
	s_nop 0
	v_addc_co_u32_e32 v31, vcc, 0, v31, vcc
	v_add_co_u32_e32 v30, vcc, s8, v28
	v_lshlrev_b32_e32 v0, 7, v2
	s_nop 0
	v_addc_co_u32_e32 v31, vcc, 0, v29, vcc
	s_nop 0
	v_readfirstlane_b32 s58, v28
	v_readfirstlane_b32 s59, v29
	v_add_co_u32_e32 v30, vcc, s93, v28
	v_xor_b32_e32 v2, v2, v36
	s_nop 0
	v_addc_co_u32_e32 v31, vcc, 0, v29, vcc
	v_add_co_u32_e32 v28, vcc, s9, v28
	v_lshlrev_b32_e32 v2, 4, v2
	s_nop 0
	v_addc_co_u32_e32 v29, vcc, 0, v29, vcc
	s_nop 0
	v_and_or_b32 v0, v2, s33, v0
	v_lshlrev_b32_e32 v2, 7, v36
	v_and_b32_e32 v3, 15, v36
	v_and_b32_e32 v213, 0xffffc780, v2
	v_lshrrev_b32_e32 v2, 1, v36
	v_lshrrev_b32_e32 v37, 4, v36
	v_and_or_b32 v2, v2, 32, v3
	v_and_b32_e32 v35, 7, v36
	s_add_i32 s8, s23, s22
	v_bfe_u32 v34, v36, 4, 2
	v_lshlrev_b32_e32 v215, 7, v2
	v_bitop3_b32 v2, v37, v35, 3 bitop3:0x6c
	s_ashr_i32 s9, s8, 31
	v_lshlrev_b32_e32 v218, 4, v2
	v_bitop3_b32 v2, v34, v35, 4 bitop3:0x36
	s_lshl_b64 s[8:9], s[8:9], 18
	v_lshlrev_b32_e32 v219, 4, v2
	v_lshl_add_u64 v[2:3], s[8:9], 0, v[32:33]
	v_lshlrev_b32_e32 v34, 4, v35
	v_lshl_add_u64 v[32:33], s[66:67], 0, v[32:33]
	v_or_b32_e32 v2, v2, v34
	v_or_b32_e32 v32, v32, v34
	v_mov_b32_e32 v52, 0
	v_lshl_add_u64 v[2:3], s[12:13], 0, v[2:3]
	v_lshl_add_u64 v[216:217], s[0:1], 0, v[32:33]
	s_mov_b64 s[8:9], 0
	v_mov_b32_e32 v53, v52
	v_mov_b32_e32 v54, v52
	v_mov_b32_e32 v55, v52
	s_waitcnt vmcnt(23)
	v_mov_b32_e32 v56, v52
	v_mov_b32_e32 v57, v52
	v_mov_b32_e32 v58, v52
	v_mov_b32_e32 v59, v52
	v_mov_b32_e32 v60, v52
	v_mov_b32_e32 v61, v52
	v_mov_b32_e32 v62, v52
	v_mov_b32_e32 v63, v52
	s_waitcnt vmcnt(22)
	v_mov_b32_e32 v64, v52
	v_mov_b32_e32 v65, v52
	v_mov_b32_e32 v66, v52
	v_mov_b32_e32 v67, v52
	v_mov_b32_e32 v68, v52
	v_mov_b32_e32 v69, v52
	v_mov_b32_e32 v70, v52
	v_mov_b32_e32 v71, v52
	v_mov_b32_e32 v72, v52
	v_mov_b32_e32 v73, v52
	v_mov_b32_e32 v74, v52
	v_mov_b32_e32 v75, v52
	v_mov_b32_e32 v76, v52
	v_mov_b32_e32 v77, v52
	v_mov_b32_e32 v78, v52
	v_mov_b32_e32 v79, v52
	v_mov_b32_e32 v80, v52
	v_mov_b32_e32 v81, v52
	v_mov_b32_e32 v82, v52
	v_mov_b32_e32 v83, v52
	s_waitcnt vmcnt(21)
	v_mov_b32_e32 v84, v52
	v_mov_b32_e32 v85, v52
	v_mov_b32_e32 v86, v52
	v_mov_b32_e32 v87, v52
	s_waitcnt vmcnt(20)
	v_mov_b32_e32 v88, v52
	v_mov_b32_e32 v89, v52
	v_mov_b32_e32 v90, v52
	v_mov_b32_e32 v91, v52
	v_mov_b32_e32 v92, v52
	v_mov_b32_e32 v93, v52
	v_mov_b32_e32 v94, v52
	v_mov_b32_e32 v95, v52
	v_mov_b32_e32 v96, v52
	v_mov_b32_e32 v97, v52
	v_mov_b32_e32 v98, v52
	v_mov_b32_e32 v99, v52
	v_mov_b32_e32 v100, v52
	v_mov_b32_e32 v101, v52
	v_mov_b32_e32 v102, v52
	v_mov_b32_e32 v103, v52
	v_mov_b32_e32 v104, v52
	v_mov_b32_e32 v105, v52
	v_mov_b32_e32 v106, v52
	v_mov_b32_e32 v107, v52
	v_mov_b32_e32 v108, v52
	v_mov_b32_e32 v109, v52
	v_mov_b32_e32 v110, v52
	v_mov_b32_e32 v111, v52
	v_mov_b32_e32 v112, v52
	v_mov_b32_e32 v113, v52
	v_mov_b32_e32 v114, v52
	v_mov_b32_e32 v115, v52
	v_mov_b32_e32 v116, v52
	v_mov_b32_e32 v117, v52
	v_mov_b32_e32 v118, v52
	v_mov_b32_e32 v119, v52
	v_mov_b32_e32 v120, v52
	v_mov_b32_e32 v121, v52
	v_mov_b32_e32 v122, v52
	v_mov_b32_e32 v123, v52
	v_mov_b32_e32 v124, v52
	v_mov_b32_e32 v125, v52
	v_mov_b32_e32 v126, v52
	v_mov_b32_e32 v127, v52
	v_mov_b32_e32 v128, v52
	v_mov_b32_e32 v129, v52
	v_mov_b32_e32 v130, v52
	v_mov_b32_e32 v131, v52
	v_mov_b32_e32 v132, v52
	v_mov_b32_e32 v133, v52
	v_mov_b32_e32 v134, v52
	v_mov_b32_e32 v135, v52
	v_mov_b32_e32 v136, v52
	v_mov_b32_e32 v137, v52
	v_mov_b32_e32 v138, v52
	v_mov_b32_e32 v139, v52
	v_mov_b32_e32 v140, v52
	v_mov_b32_e32 v141, v52
	v_mov_b32_e32 v142, v52
	v_mov_b32_e32 v143, v52
	v_mov_b32_e32 v144, v52
	v_mov_b32_e32 v145, v52
	v_mov_b32_e32 v146, v52
	v_mov_b32_e32 v147, v52
	v_mov_b32_e32 v148, v52
	v_mov_b32_e32 v149, v52
	v_mov_b32_e32 v150, v52
	v_mov_b32_e32 v151, v52
	v_mov_b32_e32 v152, v52
	v_mov_b32_e32 v153, v52
	v_mov_b32_e32 v154, v52
	v_mov_b32_e32 v155, v52
	v_mov_b32_e32 v156, v52
	v_mov_b32_e32 v157, v52
	v_mov_b32_e32 v158, v52
	v_mov_b32_e32 v159, v52
	v_mov_b32_e32 v160, v52
	v_mov_b32_e32 v161, v52
	v_mov_b32_e32 v162, v52
	v_mov_b32_e32 v163, v52
	v_mov_b32_e32 v164, v52
	v_mov_b32_e32 v165, v52
	v_mov_b32_e32 v166, v52
	v_mov_b32_e32 v167, v52
	v_mov_b32_e32 v168, v52
	v_mov_b32_e32 v169, v52
	v_mov_b32_e32 v170, v52
	v_mov_b32_e32 v171, v52
	v_mov_b32_e32 v172, v52
	v_mov_b32_e32 v173, v52
	v_mov_b32_e32 v174, v52
	v_mov_b32_e32 v175, v52
	v_mov_b32_e32 v176, v52
	v_mov_b32_e32 v177, v52
	v_mov_b32_e32 v178, v52
	v_mov_b32_e32 v179, v52
; template <int MI, bool SWAP, bool F8 = false>
; __device__ __forceinline__ void gemm_core(const bf16_t* __restrict__ A, int lda, const bf16_t* __restrict__ B, int ldb,
;                                           int K, char* smem, f32x4 (&acc)[MI][4]) {
;     ...
;   for (int kt = 0; kt < nk; ++kt) {
;     __syncthreads();
; #pragma unroll
;     for (int i = 0; i < MI; ++i) *(u32x4*)(smem + woff + i * 4096) = ra[i];
; #pragma unroll
;     for (int i = 0; i < 4; ++i) *(u32x4*)(smem + 32768 + woff + i * 4096) = rb[i];
;     __syncthreads();
;     if (kt + 1 < nk) {
; #pragma unroll
;       for (int i = 0; i < MI; ++i) ra[i] = *(const u32x4*)(ap + (size_t)(32 * i) * lda + (kt + 1) * 64);
; #pragma unroll
;       for (int i = 0; i < 4; ++i) rb[i] = *(const u32x4*)(bp + (size_t)(32 * i) * ldb + (kt + 1) * 64);
;     }
;     if (F8) {
;       const int c0 = (g ^ (li & 7)) << 4, c1 = ((4 + g) ^ (li & 7)) << 4;
;       i32x8 wf8[4];
; #pragma unroll
;       for (int j = 0; j < 4; ++j) {
;         const char* rp = smem + wrow + ((j & 1) * 16 + (j >> 1) * 64) * 128;
;         const u32x4 lo = *(const u32x4*)(rp + c0), hi = *(const u32x4*)(rp + c1);
;         wf8[j] = (i32x8){(int)lo.x, (int)lo.y, (int)lo.z, (int)lo.w, (int)hi.x, (int)hi.y, (int)hi.z, (int)hi.w};
;       }
; #pragma unroll
;       for (int i = 0; i < MI; ++i) {
;         const char* rp = smem + xrow + i * 2048;
;         const u32x4 lo = *(const u32x4*)(rp + c0), hi = *(const u32x4*)(rp + c1);
;         const i32x8 xf8 = {(int)lo.x, (int)lo.y, (int)lo.z, (int)lo.w, (int)hi.x, (int)hi.y, (int)hi.z, (int)hi.w};
; #pragma unroll
;         for (int j = 0; j < 4; ++j)
;           acc[i][j] = __builtin_amdgcn_mfma_scale_f32_16x16x128_f8f6f4(wf8[j], xf8, acc[i][j], 0, 0, 0, 0x77777777, 0, 0x7f7f7f7f);
;       }
.LBB0_944:
	v_add_u32_e32 v222, v215, v218
	v_add_u32_e32 v223, v215, v219
	s_barrier
	s_mov_b32 m0, s62
	s_nop 0
	global_load_lds_dwordx4 v252, s[56:57]
	s_add_u32 m0, s62, 0x1000
	s_nop 0
	global_load_lds_dwordx4 v253, s[56:57]
	s_add_u32 s56, s56, 0x10000
	s_addc_u32 s57, s57, 0
	s_add_u32 m0, s62, 0x2000
	s_nop 0
	global_load_lds_dwordx4 v252, s[56:57]
	s_add_u32 m0, s62, 0x3000
	s_nop 0
	global_load_lds_dwordx4 v253, s[56:57]
	s_add_u32 s56, s56, 0x10000
	s_addc_u32 s57, s57, 0
	s_add_u32 m0, s62, 0x4000
	s_nop 0
	global_load_lds_dwordx4 v252, s[56:57]
	s_add_u32 m0, s62, 0x5000
	s_nop 0
	global_load_lds_dwordx4 v253, s[56:57]
	s_add_u32 s56, s56, 0x10000
	s_addc_u32 s57, s57, 0
	s_add_u32 m0, s62, 0x6000
	s_nop 0
	global_load_lds_dwordx4 v252, s[56:57]
	s_add_u32 m0, s62, 0x7000
	s_nop 0
	global_load_lds_dwordx4 v253, s[56:57]
	s_sub_u32 s56, s56, 0x30000
	s_subb_u32 s57, s57, 0
	s_add_u32 m0, s62, 0x8000
	s_nop 0
	global_load_lds_dwordx4 v252, s[58:59]
	s_add_u32 m0, s62, 0x9000
	s_nop 0
	global_load_lds_dwordx4 v253, s[58:59]
	s_add_u32 s58, s58, 0x10000
	s_addc_u32 s59, s59, 0
	s_add_u32 m0, s62, 0xa000
	s_nop 0
	global_load_lds_dwordx4 v252, s[58:59]
	s_add_u32 m0, s62, 0xb000
	s_nop 0
	global_load_lds_dwordx4 v253, s[58:59]
	s_sub_u32 s58, s58, 0x10000
	s_subb_u32 s59, s59, 0
	v_add_u32_e32 v252, 0x80, v252
	v_add_u32_e32 v253, 0x80, v253
	s_waitcnt vmcnt(0)
	s_barrier
	v_add_u32_e32 v221, v213, v218
	v_add_u32_e32 v220, v213, v219
	ds_read_b128 v[44:47], v222 offset:32768
	ds_read_b128 v[48:51], v223 offset:32768
	ds_read_b128 v[180:183], v221
	ds_read_b128 v[184:187], v220
	ds_read_b128 v[20:23], v222 offset:34816
	ds_read_b128 v[24:27], v223 offset:34816
	ds_read_b128 v[188:191], v221 offset:2048
	ds_read_b128 v[192:195], v220 offset:2048
	ds_read_b128 v[32:35], v223 offset:40960
	ds_read_b128 v[28:31], v222 offset:40960
	ds_read_b128 v[36:39], v222 offset:43008
	ds_read_b128 v[40:43], v223 offset:43008
	s_waitcnt lgkmcnt(8)
	v_mfma_scale_f32_16x16x128_f8f6f4 v[176:179], v[44:51], v[180:187], v[176:179], v239, v238 op_sel_hi:[0,0,0]
	s_waitcnt lgkmcnt(6)
	v_mfma_scale_f32_16x16x128_f8f6f4 v[172:175], v[20:27], v[180:187], v[172:175], v239, v238 op_sel_hi:[0,0,0]
	s_waitcnt lgkmcnt(2)
	v_mfma_scale_f32_16x16x128_f8f6f4 v[168:171], v[28:35], v[180:187], v[168:171], v239, v238 op_sel_hi:[0,0,0]
	s_waitcnt lgkmcnt(0)
	v_mfma_scale_f32_16x16x128_f8f6f4 v[164:167], v[36:43], v[180:187], v[164:167], v239, v238 op_sel_hi:[0,0,0]
	v_mfma_scale_f32_16x16x128_f8f6f4 v[160:163], v[44:51], v[188:195], v[160:163], v239, v238 op_sel_hi:[0,0,0]
	v_mfma_scale_f32_16x16x128_f8f6f4 v[156:159], v[20:27], v[188:195], v[156:159], v239, v238 op_sel_hi:[0,0,0]
	v_mfma_scale_f32_16x16x128_f8f6f4 v[152:155], v[28:35], v[188:195], v[152:155], v239, v238 op_sel_hi:[0,0,0]
	v_mfma_scale_f32_16x16x128_f8f6f4 v[148:151], v[36:43], v[188:195], v[148:151], v239, v238 op_sel_hi:[0,0,0]
	ds_read_b128 v[184:187], v220 offset:4096
	ds_read_b128 v[180:183], v221 offset:4096
	ds_read_b128 v[188:191], v221 offset:6144
	ds_read_b128 v[192:195], v220 offset:6144
	s_waitcnt lgkmcnt(2)
	v_mfma_scale_f32_16x16x128_f8f6f4 v[144:147], v[44:51], v[180:187], v[144:147], v239, v238 op_sel_hi:[0,0,0]
	v_mfma_scale_f32_16x16x128_f8f6f4 v[140:143], v[20:27], v[180:187], v[140:143], v239, v238 op_sel_hi:[0,0,0]
	v_mfma_scale_f32_16x16x128_f8f6f4 v[136:139], v[28:35], v[180:187], v[136:139], v239, v238 op_sel_hi:[0,0,0]
	v_mfma_scale_f32_16x16x128_f8f6f4 v[132:135], v[36:43], v[180:187], v[132:135], v239, v238 op_sel_hi:[0,0,0]
	s_waitcnt lgkmcnt(0)
	v_mfma_scale_f32_16x16x128_f8f6f4 v[128:131], v[44:51], v[188:195], v[128:131], v239, v238 op_sel_hi:[0,0,0]
	v_mfma_scale_f32_16x16x128_f8f6f4 v[124:127], v[20:27], v[188:195], v[124:127], v239, v238 op_sel_hi:[0,0,0]
	v_mfma_scale_f32_16x16x128_f8f6f4 v[120:123], v[28:35], v[188:195], v[120:123], v239, v238 op_sel_hi:[0,0,0]
	v_mfma_scale_f32_16x16x128_f8f6f4 v[116:119], v[36:43], v[188:195], v[116:119], v239, v238 op_sel_hi:[0,0,0]
	ds_read_b128 v[184:187], v220 offset:8192
	ds_read_b128 v[180:183], v221 offset:8192
	ds_read_b128 v[188:191], v221 offset:10240
	ds_read_b128 v[192:195], v220 offset:10240
	s_waitcnt lgkmcnt(0)
	v_mfma_scale_f32_16x16x128_f8f6f4 v[96:99], v[44:51], v[188:195], v[96:99], v239, v238 op_sel_hi:[0,0,0]
	v_mfma_scale_f32_16x16x128_f8f6f4 v[92:95], v[20:27], v[188:195], v[92:95], v239, v238 op_sel_hi:[0,0,0]
	v_mfma_scale_f32_16x16x128_f8f6f4 v[88:91], v[28:35], v[188:195], v[88:91], v239, v238 op_sel_hi:[0,0,0]
	v_mfma_scale_f32_16x16x128_f8f6f4 v[84:87], v[36:43], v[188:195], v[84:87], v239, v238 op_sel_hi:[0,0,0]
	v_mfma_scale_f32_16x16x128_f8f6f4 v[112:115], v[44:51], v[180:187], v[112:115], v239, v238 op_sel_hi:[0,0,0]
	v_mfma_scale_f32_16x16x128_f8f6f4 v[108:111], v[20:27], v[180:187], v[108:111], v239, v238 op_sel_hi:[0,0,0]
	v_mfma_scale_f32_16x16x128_f8f6f4 v[104:107], v[28:35], v[180:187], v[104:107], v239, v238 op_sel_hi:[0,0,0]
	v_mfma_scale_f32_16x16x128_f8f6f4 v[100:103], v[36:43], v[180:187], v[100:103], v239, v238 op_sel_hi:[0,0,0]
	ds_read_b128 v[180:183], v221 offset:12288
	ds_read_b128 v[184:187], v220 offset:12288
	ds_read_b128 v[224:227], v221 offset:14336
	ds_read_b128 v[228:231], v220 offset:14336
	s_waitcnt lgkmcnt(2)
	v_mfma_scale_f32_16x16x128_f8f6f4 v[80:83], v[44:51], v[180:187], v[80:83], v239, v238 op_sel_hi:[0,0,0]
	v_mfma_scale_f32_16x16x128_f8f6f4 v[76:79], v[20:27], v[180:187], v[76:79], v239, v238 op_sel_hi:[0,0,0]
	v_mfma_scale_f32_16x16x128_f8f6f4 v[72:75], v[28:35], v[180:187], v[72:75], v239, v238 op_sel_hi:[0,0,0]
	v_mfma_scale_f32_16x16x128_f8f6f4 v[68:71], v[36:43], v[180:187], v[68:71], v239, v238 op_sel_hi:[0,0,0]
	s_waitcnt lgkmcnt(0)
	v_mfma_scale_f32_16x16x128_f8f6f4 v[64:67], v[44:51], v[224:231], v[64:67], v239, v238 op_sel_hi:[0,0,0]
	v_mfma_scale_f32_16x16x128_f8f6f4 v[60:63], v[20:27], v[224:231], v[60:63], v239, v238 op_sel_hi:[0,0,0]
	v_mfma_scale_f32_16x16x128_f8f6f4 v[56:59], v[28:35], v[224:231], v[56:59], v239, v238 op_sel_hi:[0,0,0]
	v_mfma_scale_f32_16x16x128_f8f6f4 v[52:55], v[36:43], v[224:231], v[52:55], v239, v238 op_sel_hi:[0,0,0]
	s_add_u32 s8, s8, 0x80
	s_addc_u32 s9, s9, 0
	s_cmpk_lg_i32 s8, 0x380
	s_cbranch_scc1 .LBB0_944
; template <int MI, bool SWAP, bool F8 = false>
; __device__ __forceinline__ void gemm_core(const bf16_t* __restrict__ A, int lda, const bf16_t* __restrict__ B, int ldb,
;                                           int K, char* smem, f32x4 (&acc)[MI][4]) {
;     ...
;   for (int kt = 0; kt < nk; ++kt) {
;     __syncthreads();
; #pragma unroll
;     for (int i = 0; i < MI; ++i) *(u32x4*)(smem + woff + i * 4096) = ra[i];
; #pragma unroll
;     for (int i = 0; i < 4; ++i) *(u32x4*)(smem + 32768 + woff + i * 4096) = rb[i];
;     __syncthreads();
;     if (kt + 1 < nk) {
; #pragma unroll
;       for (int i = 0; i < MI; ++i) ra[i] = *(const u32x4*)(ap + (size_t)(32 * i) * lda + (kt + 1) * 64);
; #pragma unroll
;       for (int i = 0; i < 4; ++i) rb[i] = *(const u32x4*)(bp + (size_t)(32 * i) * ldb + (kt + 1) * 64);
;     }
;     if (F8) {
;       const int c0 = (g ^ (li & 7)) << 4, c1 = ((4 + g) ^ (li & 7)) << 4;
;       i32x8 wf8[4];
; #pragma unroll
;       for (int j = 0; j < 4; ++j) {
;         const char* rp = smem + wrow + ((j & 1) * 16 + (j >> 1) * 64) * 128;
;         const u32x4 lo = *(const u32x4*)(rp + c0), hi = *(const u32x4*)(rp + c1);
;         wf8[j] = (i32x8){(int)lo.x, (int)lo.y, (int)lo.z, (int)lo.w, (int)hi.x, (int)hi.y, (int)hi.z, (int)hi.w};
;       }
; #pragma unroll
;       for (int i = 0; i < MI; ++i) {
;         const char* rp = smem + xrow + i * 2048;
;         const u32x4 lo = *(const u32x4*)(rp + c0), hi = *(const u32x4*)(rp + c1);
;         const i32x8 xf8 = {(int)lo.x, (int)lo.y, (int)lo.z, (int)lo.w, (int)hi.x, (int)hi.y, (int)hi.z, (int)hi.w};
; #pragma unroll
;         for (int j = 0; j < 4; ++j)
;           acc[i][j] = __builtin_amdgcn_mfma_scale_f32_16x16x128_f8f6f4(wf8[j], xf8, acc[i][j], 0, 0, 0, 0x77777777, 0, 0x7f7f7f7f);
;       }
	s_barrier
	s_mov_b32 m0, s62
	s_nop 0
	global_load_lds_dwordx4 v252, s[56:57]
	s_add_u32 m0, s62, 0x1000
	s_nop 0
	global_load_lds_dwordx4 v253, s[56:57]
	s_add_u32 s56, s56, 0x10000
	s_addc_u32 s57, s57, 0
	s_add_u32 m0, s62, 0x2000
	s_nop 0
	global_load_lds_dwordx4 v252, s[56:57]
	s_add_u32 m0, s62, 0x3000
	s_nop 0
	global_load_lds_dwordx4 v253, s[56:57]
	s_add_u32 s56, s56, 0x10000
	s_addc_u32 s57, s57, 0
	s_add_u32 m0, s62, 0x4000
	s_nop 0
	global_load_lds_dwordx4 v252, s[56:57]
	s_add_u32 m0, s62, 0x5000
	s_nop 0
	global_load_lds_dwordx4 v253, s[56:57]
	s_add_u32 s56, s56, 0x10000
	s_addc_u32 s57, s57, 0
	s_add_u32 m0, s62, 0x6000
	s_nop 0
	global_load_lds_dwordx4 v252, s[56:57]
	s_add_u32 m0, s62, 0x7000
	s_nop 0
	global_load_lds_dwordx4 v253, s[56:57]
	s_sub_u32 s56, s56, 0x30000
	s_subb_u32 s57, s57, 0
	s_add_u32 m0, s62, 0x8000
	s_nop 0
	global_load_lds_dwordx4 v252, s[58:59]
	s_add_u32 m0, s62, 0x9000
	s_nop 0
	global_load_lds_dwordx4 v253, s[58:59]
	s_add_u32 s58, s58, 0x10000
	s_addc_u32 s59, s59, 0
	s_add_u32 m0, s62, 0xa000
	s_nop 0
	global_load_lds_dwordx4 v252, s[58:59]
	s_add_u32 m0, s62, 0xb000
	s_nop 0
	global_load_lds_dwordx4 v253, s[58:59]
	s_sub_u32 s58, s58, 0x10000
	s_subb_u32 s59, s59, 0
	s_waitcnt vmcnt(0)
	s_barrier
	ds_read_b128 v[20:23], v222 offset:32768
	ds_read_b128 v[24:27], v223 offset:32768
	ds_read_b128 v[28:31], v222 offset:34816
	ds_read_b128 v[32:35], v223 offset:34816
	ds_read_b128 v[36:39], v222 offset:40960
	ds_read_b128 v[40:43], v223 offset:40960
	ds_read_b128 v[44:47], v222 offset:43008
	ds_read_b128 v[48:51], v223 offset:43008
	ds_read_b128 v[180:183], v221
	ds_read_b128 v[184:187], v220
	s_waitcnt lgkmcnt(0)
	v_mfma_scale_f32_16x16x128_f8f6f4 v[176:179], v[20:27], v[180:187], v[176:179], v239, v238 op_sel_hi:[0,0,0]
	s_lshl_b64 s[6:7], s[6:7], 20
	s_add_u32 s6, s42, s6
	s_addc_u32 s7, s43, s7
	s_lshl_b32 s8, s19, 1
	s_add_u32 s6, s6, s8
	s_addc_u32 s7, s7, 0
	s_add_i32 s18, s18, s78
	v_mfma_scale_f32_16x16x128_f8f6f4 v[172:175], v[28:35], v[180:187], v[172:175], v239, v238 op_sel_hi:[0,0,0]
	s_add_i32 s15, s15, s71
	s_add_i32 s14, s14, s76
	s_cmpk_gt_i32 s18, 0x3ff
	v_mfma_scale_f32_16x16x128_f8f6f4 v[168:171], v[36:43], v[180:187], v[168:171], v239, v238 op_sel_hi:[0,0,0]
	v_mfma_scale_f32_16x16x128_f8f6f4 v[164:167], v[44:51], v[180:187], v[164:167], v239, v238 op_sel_hi:[0,0,0]
	ds_read_b128 v[180:183], v221 offset:2048
	ds_read_b128 v[184:187], v220 offset:2048
	s_waitcnt lgkmcnt(0)
	v_mfma_scale_f32_16x16x128_f8f6f4 v[160:163], v[20:27], v[180:187], v[160:163], v239, v238 op_sel_hi:[0,0,0]
	v_mfma_scale_f32_16x16x128_f8f6f4 v[156:159], v[28:35], v[180:187], v[156:159], v239, v238 op_sel_hi:[0,0,0]
	v_mfma_scale_f32_16x16x128_f8f6f4 v[152:155], v[36:43], v[180:187], v[152:155], v239, v238 op_sel_hi:[0,0,0]
	v_mfma_scale_f32_16x16x128_f8f6f4 v[148:151], v[44:51], v[180:187], v[148:151], v239, v238 op_sel_hi:[0,0,0]
	ds_read_b128 v[180:183], v221 offset:4096
	ds_read_b128 v[184:187], v220 offset:4096
	s_waitcnt lgkmcnt(0)
	v_mfma_scale_f32_16x16x128_f8f6f4 v[144:147], v[20:27], v[180:187], v[144:147], v239, v238 op_sel_hi:[0,0,0]
	v_mfma_scale_f32_16x16x128_f8f6f4 v[140:143], v[28:35], v[180:187], v[140:143], v239, v238 op_sel_hi:[0,0,0]
	v_mfma_scale_f32_16x16x128_f8f6f4 v[136:139], v[36:43], v[180:187], v[136:139], v239, v238 op_sel_hi:[0,0,0]
	v_mfma_scale_f32_16x16x128_f8f6f4 v[132:135], v[44:51], v[180:187], v[132:135], v239, v238 op_sel_hi:[0,0,0]
	ds_read_b128 v[180:183], v221 offset:6144
	ds_read_b128 v[184:187], v220 offset:6144
	s_waitcnt lgkmcnt(0)
	v_mfma_scale_f32_16x16x128_f8f6f4 v[128:131], v[20:27], v[180:187], v[128:131], v239, v238 op_sel_hi:[0,0,0]
	v_mfma_scale_f32_16x16x128_f8f6f4 v[124:127], v[28:35], v[180:187], v[124:127], v239, v238 op_sel_hi:[0,0,0]
	v_mfma_scale_f32_16x16x128_f8f6f4 v[120:123], v[36:43], v[180:187], v[120:123], v239, v238 op_sel_hi:[0,0,0]
	v_mfma_scale_f32_16x16x128_f8f6f4 v[116:119], v[44:51], v[180:187], v[116:119], v239, v238 op_sel_hi:[0,0,0]
	ds_read_b128 v[180:183], v221 offset:8192
	ds_read_b128 v[184:187], v220 offset:8192
	s_waitcnt lgkmcnt(0)
	v_mfma_scale_f32_16x16x128_f8f6f4 v[112:115], v[20:27], v[180:187], v[112:115], v239, v238 op_sel_hi:[0,0,0]
	v_mfma_scale_f32_16x16x128_f8f6f4 v[108:111], v[28:35], v[180:187], v[108:111], v239, v238 op_sel_hi:[0,0,0]
	v_mfma_scale_f32_16x16x128_f8f6f4 v[104:107], v[36:43], v[180:187], v[104:107], v239, v238 op_sel_hi:[0,0,0]
	v_mfma_scale_f32_16x16x128_f8f6f4 v[100:103], v[44:51], v[180:187], v[100:103], v239, v238 op_sel_hi:[0,0,0]
	ds_read_b128 v[180:183], v221 offset:10240
	ds_read_b128 v[184:187], v220 offset:10240
	s_waitcnt lgkmcnt(0)
	v_mfma_scale_f32_16x16x128_f8f6f4 v[96:99], v[20:27], v[180:187], v[96:99], v239, v238 op_sel_hi:[0,0,0]
	v_mfma_scale_f32_16x16x128_f8f6f4 v[92:95], v[28:35], v[180:187], v[92:95], v239, v238 op_sel_hi:[0,0,0]
	v_mfma_scale_f32_16x16x128_f8f6f4 v[88:91], v[36:43], v[180:187], v[88:91], v239, v238 op_sel_hi:[0,0,0]
	v_mfma_scale_f32_16x16x128_f8f6f4 v[84:87], v[44:51], v[180:187], v[84:87], v239, v238 op_sel_hi:[0,0,0]
	ds_read_b128 v[180:183], v221 offset:12288
	ds_read_b128 v[184:187], v220 offset:12288
	s_waitcnt lgkmcnt(0)
	v_mfma_scale_f32_16x16x128_f8f6f4 v[80:83], v[20:27], v[180:187], v[80:83], v239, v238 op_sel_hi:[0,0,0]
	v_mfma_scale_f32_16x16x128_f8f6f4 v[76:79], v[28:35], v[180:187], v[76:79], v239, v238 op_sel_hi:[0,0,0]
	v_mfma_scale_f32_16x16x128_f8f6f4 v[72:75], v[36:43], v[180:187], v[72:75], v239, v238 op_sel_hi:[0,0,0]
	v_mfma_scale_f32_16x16x128_f8f6f4 v[68:71], v[44:51], v[180:187], v[68:71], v239, v238 op_sel_hi:[0,0,0]
	ds_read_b128 v[180:183], v221 offset:14336
	ds_read_b128 v[184:187], v220 offset:14336
	s_waitcnt lgkmcnt(0)
; template <int MI, bool F8 = false>
; __device__ void gemm_tile_bf16(const bf16_t* A, int lda, const bf16_t* B, int ldb, int K, bf16_t* C, int ldc, char* smem) {
;     ...
; #pragma unroll
;   for (int i = 0; i < MI; ++i)
; #pragma unroll
;     for (int j = 0; j < 4; ++j) {
;       u32x2 v;
;       v.x = pk_bf16(acc[i][j][0], acc[i][j][1]);
;       v.y = pk_bf16(acc[i][j][2], acc[i][j][3]);
;       *(u32x2*)(C + (size_t)MROW(i) * ldc + NCOL(j)) = v;
;     }
	v_mfma_scale_f32_16x16x128_f8f6f4 v[64:67], v[20:27], v[180:187], v[64:67], v239, v238 op_sel_hi:[0,0,0]
	v_mfma_scale_f32_16x16x128_f8f6f4 v[24:27], v[36:43], v[180:187], v[56:59], v239, v238 op_sel_hi:[0,0,0]
	v_mov_b32_e32 v36, v208
	s_nop 0
	v_lshrrev_b32_e32 v0, 1, v36
	v_and_b32_e32 v2, 0xffffff8f, v36
	v_and_b32_e32 v0, 32, v0
	v_lshrrev_b32_e32 v3, 2, v36
	v_and_or_b32 v0, v3, 12, v0
	v_ashrrev_i32_e32 v3, 31, v2
	v_mfma_scale_f32_16x16x128_f8f6f4 v[28:31], v[28:35], v[180:187], v[60:63], v239, v238 op_sel_hi:[0,0,0]
	v_lshlrev_b64 v[32:33], 12, v[2:3]
	v_lshl_add_u64 v[32:33], s[6:7], 0, v[32:33]
	v_lshlrev_b32_e32 v0, 1, v0
	v_cvt_pk_bf16_f32 v34, v176, v177
	v_cvt_pk_bf16_f32 v35, v178, v179
	v_lshl_add_u64 v[32:33], v[32:33], 0, v[0:1]
	global_store_dwordx2 v[32:33], v[34:35], off
	v_cvt_pk_bf16_f32 v34, v172, v173
	v_cvt_pk_bf16_f32 v35, v174, v175
	global_store_dwordx2 v[32:33], v[34:35], off offset:32
	v_cvt_pk_bf16_f32 v34, v168, v169
	v_cvt_pk_bf16_f32 v35, v170, v171
	global_store_dwordx2 v[32:33], v[34:35], off offset:128
	v_cvt_pk_bf16_f32 v34, v164, v165
	v_cvt_pk_bf16_f32 v35, v166, v167
	global_store_dwordx2 v[32:33], v[34:35], off offset:160
	v_or_b32_e32 v32, 16, v2
	v_ashrrev_i32_e32 v33, 31, v32
	v_lshlrev_b64 v[32:33], 12, v[32:33]
	v_lshl_add_u64 v[32:33], s[6:7], 0, v[32:33]
	v_cvt_pk_bf16_f32 v34, v160, v161
	v_cvt_pk_bf16_f32 v35, v162, v163
	v_lshl_add_u64 v[32:33], v[32:33], 0, v[0:1]
	global_store_dwordx2 v[32:33], v[34:35], off
	v_cvt_pk_bf16_f32 v34, v156, v157
	v_cvt_pk_bf16_f32 v35, v158, v159
	global_store_dwordx2 v[32:33], v[34:35], off offset:32
	v_cvt_pk_bf16_f32 v34, v152, v153
	v_cvt_pk_bf16_f32 v35, v154, v155
	global_store_dwordx2 v[32:33], v[34:35], off offset:128
	v_cvt_pk_bf16_f32 v34, v148, v149
	v_cvt_pk_bf16_f32 v35, v150, v151
	global_store_dwordx2 v[32:33], v[34:35], off offset:160
	v_or_b32_e32 v32, 32, v2
	v_ashrrev_i32_e32 v33, 31, v32
	v_lshlrev_b64 v[32:33], 12, v[32:33]
	v_lshl_add_u64 v[32:33], s[6:7], 0, v[32:33]
	v_cvt_pk_bf16_f32 v34, v144, v145
	v_cvt_pk_bf16_f32 v35, v146, v147
	v_lshl_add_u64 v[32:33], v[32:33], 0, v[0:1]
	global_store_dwordx2 v[32:33], v[34:35], off
	v_cvt_pk_bf16_f32 v34, v140, v141
	v_cvt_pk_bf16_f32 v35, v142, v143
	global_store_dwordx2 v[32:33], v[34:35], off offset:32
	v_cvt_pk_bf16_f32 v34, v136, v137
	v_cvt_pk_bf16_f32 v35, v138, v139
	global_store_dwordx2 v[32:33], v[34:35], off offset:128
	v_cvt_pk_bf16_f32 v34, v132, v133
	v_cvt_pk_bf16_f32 v35, v134, v135
	global_store_dwordx2 v[32:33], v[34:35], off offset:160
	v_or_b32_e32 v32, 48, v2
	v_ashrrev_i32_e32 v33, 31, v32
	v_lshlrev_b64 v[32:33], 12, v[32:33]
	v_lshl_add_u64 v[32:33], s[6:7], 0, v[32:33]
	v_cvt_pk_bf16_f32 v34, v128, v129
	v_cvt_pk_bf16_f32 v35, v130, v131
	v_lshl_add_u64 v[32:33], v[32:33], 0, v[0:1]
	global_store_dwordx2 v[32:33], v[34:35], off
	v_cvt_pk_bf16_f32 v34, v124, v125
	v_cvt_pk_bf16_f32 v35, v126, v127
	global_store_dwordx2 v[32:33], v[34:35], off offset:32
	v_cvt_pk_bf16_f32 v34, v120, v121
	v_cvt_pk_bf16_f32 v35, v122, v123
	global_store_dwordx2 v[32:33], v[34:35], off offset:128
	v_cvt_pk_bf16_f32 v34, v116, v117
	v_cvt_pk_bf16_f32 v35, v118, v119
	global_store_dwordx2 v[32:33], v[34:35], off offset:160
	v_or_b32_e32 v32, 64, v2
	v_ashrrev_i32_e32 v33, 31, v32
	v_lshlrev_b64 v[32:33], 12, v[32:33]
	v_lshl_add_u64 v[32:33], s[6:7], 0, v[32:33]
	v_cvt_pk_bf16_f32 v34, v112, v113
	v_cvt_pk_bf16_f32 v35, v114, v115
	v_lshl_add_u64 v[32:33], v[32:33], 0, v[0:1]
	global_store_dwordx2 v[32:33], v[34:35], off
	v_cvt_pk_bf16_f32 v34, v108, v109
	v_cvt_pk_bf16_f32 v35, v110, v111
	global_store_dwordx2 v[32:33], v[34:35], off offset:32
	v_cvt_pk_bf16_f32 v34, v104, v105
	v_cvt_pk_bf16_f32 v35, v106, v107
	global_store_dwordx2 v[32:33], v[34:35], off offset:128
	v_cvt_pk_bf16_f32 v34, v100, v101
	v_cvt_pk_bf16_f32 v35, v102, v103
	global_store_dwordx2 v[32:33], v[34:35], off offset:160
	v_or_b32_e32 v32, 0x50, v2
	v_ashrrev_i32_e32 v33, 31, v32
	v_lshlrev_b64 v[32:33], 12, v[32:33]
	v_lshl_add_u64 v[32:33], s[6:7], 0, v[32:33]
	v_cvt_pk_bf16_f32 v34, v96, v97
	v_cvt_pk_bf16_f32 v35, v98, v99
	v_lshl_add_u64 v[32:33], v[32:33], 0, v[0:1]
	v_or_b32_e32 v2, 0x60, v2
	global_store_dwordx2 v[32:33], v[34:35], off
	v_cvt_pk_bf16_f32 v34, v92, v93
	v_cvt_pk_bf16_f32 v35, v94, v95
	v_ashrrev_i32_e32 v3, 31, v2
	global_store_dwordx2 v[32:33], v[34:35], off offset:32
	v_cvt_pk_bf16_f32 v34, v88, v89
	v_cvt_pk_bf16_f32 v35, v90, v91
	v_lshlrev_b64 v[2:3], 12, v[2:3]
	global_store_dwordx2 v[32:33], v[34:35], off offset:128
	v_cvt_pk_bf16_f32 v34, v84, v85
	v_cvt_pk_bf16_f32 v35, v86, v87
	v_lshl_add_u64 v[2:3], s[6:7], 0, v[2:3]
	v_mfma_scale_f32_16x16x128_f8f6f4 v[20:23], v[44:51], v[180:187], v[52:55], v239, v238 op_sel_hi:[0,0,0]
	global_store_dwordx2 v[32:33], v[34:35], off offset:160
	v_cvt_pk_bf16_f32 v32, v80, v81
	v_cvt_pk_bf16_f32 v33, v82, v83
	v_lshl_add_u64 v[2:3], v[2:3], 0, v[0:1]
	global_store_dwordx2 v[2:3], v[32:33], off
	v_cvt_pk_bf16_f32 v32, v76, v77
	v_cvt_pk_bf16_f32 v33, v78, v79
	global_store_dwordx2 v[2:3], v[32:33], off offset:32
	v_cvt_pk_bf16_f32 v32, v72, v73
	v_cvt_pk_bf16_f32 v33, v74, v75
	global_store_dwordx2 v[2:3], v[32:33], off offset:128
	v_cvt_pk_bf16_f32 v32, v68, v69
	v_cvt_pk_bf16_f32 v33, v70, v71
	global_store_dwordx2 v[2:3], v[32:33], off offset:160
	v_or_b32_e32 v2, 0x70, v36
	v_ashrrev_i32_e32 v3, 31, v2
	v_lshlrev_b64 v[2:3], 12, v[2:3]
	v_lshl_add_u64 v[2:3], s[6:7], 0, v[2:3]
	v_cvt_pk_bf16_f32 v32, v64, v65
	v_cvt_pk_bf16_f32 v33, v66, v67
	v_lshl_add_u64 v[2:3], v[2:3], 0, v[0:1]
	v_cvt_pk_bf16_f32 v28, v28, v29
	v_cvt_pk_bf16_f32 v29, v30, v31
	v_cvt_pk_bf16_f32 v24, v24, v25
	v_cvt_pk_bf16_f32 v25, v26, v27
	v_cvt_pk_bf16_f32 v20, v20, v21
	v_cvt_pk_bf16_f32 v21, v22, v23
	global_store_dwordx2 v[2:3], v[32:33], off
	global_store_dwordx2 v[2:3], v[28:29], off offset:32
	global_store_dwordx2 v[2:3], v[24:25], off offset:128
	global_store_dwordx2 v[2:3], v[20:21], off offset:160
	s_cbranch_scc0 .LBB0_943
